# GEMM K-loops: LDS-DMA tile loads use scalar base + 32-bit lane offset addressing (no per-load 64-bit VALU address adds)
# speedup vs baseline: 1.0255x; 1.0048x over previous
; #define PG8_STAGE(bufoff, gbase, voff) do { _Pragma("unroll") for (int _i = 0; _i < 2; ++_i) \
;         __builtin_amdgcn_global_load_lds((const unsigned*)((const char*)(gbase) + (voff)[_i]), (LAS unsigned*)(lds + (bufoff) + ldsw + _i * 8192), 16, 0, 0); } while (0)
; #define PG8_LDA(dst, b, h) do { _Pragma("unroll") for (int m = 0; m < 4; ++m) _Pragma("unroll") for (int k = 0; k < 2; ++k) dst[m][k] = *(const LAS bf16x8*)(lds + PG8_SA(b, h) + aoff + m * 2048 + k * 1024); } while (0)
; #define PG8_LDB(dst, b, h) do { _Pragma("unroll") for (int n = 0; n < 2; ++n) _Pragma("unroll") for (int k = 0; k < 2; ++k) dst[n][k] = *(const LAS bf16x8*)(lds + PG8_SB(b, h) + boff + n * 2048 + k * 1024); } while (0)
; #define PG8_MMA(ai, bj, At, Bt) do { __builtin_amdgcn_s_setprio(1); _Pragma("unroll") for (int m = 0; m < 4; ++m) _Pragma("unroll") for (int n = 0; n < 2; ++n) _Pragma("unroll") for (int k = 0; k < 2; ++k) \
;         acc[ai][bj][m][n] = __builtin_amdgcn_mfma_f32_16x16x32_bf16(Bt[n][k], At[m][k], acc[ai][bj][m][n], 0, 0, 0); __builtin_amdgcn_s_setprio(0); } while (0)
; #define PG8_WAIT_V(n) asm volatile("s_waitcnt vmcnt(" #n ")" ::: "memory")
; #define PG8_WAIT_L(n) asm volatile("s_waitcnt lgkmcnt(" #n ")" ::: "memory")
; #define PG8_BAR __builtin_amdgcn_s_barrier()
; #define PG8_SCHED __builtin_amdgcn_sched_barrier(0)
; template <class Epi, class Sched, bool ALIGN_EPI = true, bool SP2 = true>
; __device__ __forceinline__ void gemm_phase(LAS unsigned char* lds, const Gemm g, const Sched& S, const Epi& E) {
;     ...
;             PG8_LDB(B0, 0, 0); PG8_LDB(B1, 0, 1); PG8_SCHED; PG8_LDA(At, 0, 0); PG8_STAGE(PG8_SA(1, 1), a1 + hstep, voffA);
;             PG8_WAIT_V(8); PG8_WAIT_L(0); PG8_BAR; PG8_MMA(0, 0, At, B0); PG8_MMA(0, 1, At, B1); PG8_BAR; PG8_SCHED;
;             PG8_LDA(At, 0, 1); PG8_STAGE(PG8_SB(0, 0), b2, voffB); PG8_STAGE(PG8_SB(0, 1), b2 + hstep, voffB); PG8_STAGE(PG8_SA(0, 0), a2, voffA);
;             PG8_WAIT_V(8); PG8_WAIT_L(0); PG8_BAR; PG8_MMA(1, 0, At, B0); PG8_MMA(1, 1, At, B1); PG8_BAR; PG8_SCHED;
.LBB0_40:
	s_add_u32 s24, s90, 0xfffe0080
	s_addc_u32 s25, s91, -1
	s_add_i32 s46, 0, 0x10000
	s_cmp_eq_u32 vcc_hi, 4
	s_cselect_b32 s83, s2, s25
	s_cselect_b32 s82, s3, s24
	v_add_u32_e32 v142, s46, v145
	s_cselect_b32 s25, s45, vcc_lo
	s_cselect_b32 s24, s53, s55
	s_add_i32 s48, 0, 0x14000
	ds_read_b128 v[138:141], v142
	ds_read_b128 v[148:151], v142 offset:1024
	ds_read_b128 v[152:155], v142 offset:2048
	ds_read_b128 v[156:159], v142 offset:3072
	v_add_u32_e32 v142, s48, v145
	ds_read_b128 v[170:173], v142
	ds_read_b128 v[174:177], v142 offset:1024
	ds_read_b128 v[178:181], v142 offset:2048
	ds_read_b128 v[182:185], v142 offset:3072
	s_add_i32 m0, s67, 0xc000
	ds_read_b128 v[186:189], v147
	ds_read_b128 v[190:193], v147 offset:1024
	ds_read_b128 v[194:197], v147 offset:2048
	ds_read_b128 v[198:201], v147 offset:3072
	ds_read_b128 v[202:205], v147 offset:4096
	ds_read_b128 v[206:209], v147 offset:5120
	ds_read_b128 v[210:213], v147 offset:6144
	ds_read_b128 v[214:217], v147 offset:7168
	global_load_lds_dwordx4 v134, s[90:91]
	s_add_i32 m0, s67, 0xe000
	s_nop 0
	global_load_lds_dwordx4 v136, s[90:91]
	s_waitcnt vmcnt(8)
	s_waitcnt lgkmcnt(0)
	s_barrier
	s_setprio 1
	s_waitcnt lgkmcnt(0)
	v_mfma_f32_16x16x32_bf16 v[124:127], v[138:141], v[186:189], v[124:127]
	v_mfma_f32_16x16x32_bf16 v[120:123], v[152:155], v[186:189], v[120:123]
	v_mfma_f32_16x16x32_bf16 v[108:111], v[138:141], v[194:197], v[108:111]
	v_mfma_f32_16x16x32_bf16 v[104:107], v[152:155], v[194:197], v[104:107]
	v_mfma_f32_16x16x32_bf16 v[92:95], v[138:141], v[202:205], v[92:95]
	v_mfma_f32_16x16x32_bf16 v[88:91], v[152:155], v[202:205], v[88:91]
	v_mfma_f32_16x16x32_bf16 v[76:79], v[138:141], v[210:213], v[76:79]
	v_mfma_f32_16x16x32_bf16 v[72:75], v[152:155], v[210:213], v[72:75]
	v_mfma_f32_16x16x32_bf16 v[124:127], v[148:151], v[190:193], v[124:127]
	v_mfma_f32_16x16x32_bf16 v[120:123], v[156:159], v[190:193], v[120:123]
	v_mfma_f32_16x16x32_bf16 v[108:111], v[148:151], v[198:201], v[108:111]
	v_mfma_f32_16x16x32_bf16 v[104:107], v[156:159], v[198:201], v[104:107]
	v_mfma_f32_16x16x32_bf16 v[92:95], v[148:151], v[206:209], v[92:95]
	v_mfma_f32_16x16x32_bf16 v[88:91], v[156:159], v[206:209], v[88:91]
	v_mfma_f32_16x16x32_bf16 v[76:79], v[148:151], v[214:217], v[76:79]
	v_mfma_f32_16x16x32_bf16 v[72:75], v[156:159], v[214:217], v[72:75]
	s_setprio 0
	s_setprio 1
	v_mfma_f32_16x16x32_bf16 v[116:119], v[170:173], v[186:189], v[116:119]
	v_mfma_f32_16x16x32_bf16 v[112:115], v[178:181], v[186:189], v[112:115]
	v_mfma_f32_16x16x32_bf16 v[100:103], v[170:173], v[194:197], v[100:103]
	v_mfma_f32_16x16x32_bf16 v[96:99], v[178:181], v[194:197], v[96:99]
	v_mfma_f32_16x16x32_bf16 v[84:87], v[170:173], v[202:205], v[84:87]
	v_mfma_f32_16x16x32_bf16 v[80:83], v[178:181], v[202:205], v[80:83]
	v_mfma_f32_16x16x32_bf16 v[68:71], v[170:173], v[210:213], v[68:71]
	v_mfma_f32_16x16x32_bf16 v[64:67], v[178:181], v[210:213], v[64:67]
	v_mfma_f32_16x16x32_bf16 v[116:119], v[174:177], v[190:193], v[116:119]
	v_mfma_f32_16x16x32_bf16 v[112:115], v[182:185], v[190:193], v[112:115]
	v_mfma_f32_16x16x32_bf16 v[100:103], v[174:177], v[198:201], v[100:103]
	v_mfma_f32_16x16x32_bf16 v[96:99], v[182:185], v[198:201], v[96:99]
	v_mfma_f32_16x16x32_bf16 v[84:87], v[174:177], v[206:209], v[84:87]
	v_mfma_f32_16x16x32_bf16 v[80:83], v[182:185], v[206:209], v[80:83]
	v_mfma_f32_16x16x32_bf16 v[68:71], v[174:177], v[214:217], v[68:71]
	v_mfma_f32_16x16x32_bf16 v[64:67], v[182:185], v[214:217], v[64:67]
	s_setprio 0
	s_barrier
	s_add_i32 s46, s46, s93
	s_mov_b32 m0, s46
	ds_read_b128 v[186:189], v147 offset:16384
	ds_read_b128 v[190:193], v147 offset:17408
	ds_read_b128 v[194:197], v147 offset:18432
	ds_read_b128 v[198:201], v147 offset:19456
	ds_read_b128 v[202:205], v147 offset:20480
	ds_read_b128 v[206:209], v147 offset:21504
	ds_read_b128 v[210:213], v147 offset:22528
	ds_read_b128 v[214:217], v147 offset:23552
	global_load_lds_dwordx4 v160, s[24:25]
	s_add_i32 m0, s46, 0x2000
	s_add_u32 s46, s24, 0x20000
	s_addc_u32 s47, s25, 0
	s_add_i32 s48, s48, s93
	global_load_lds_dwordx4 v132, s[24:25]
	s_mov_b32 m0, s48
	s_nop 0
	global_load_lds_dwordx4 v160, s[46:47]
	s_add_i32 m0, s48, 0x2000
	s_nop 0
	global_load_lds_dwordx4 v132, s[46:47]
	s_mov_b32 m0, s67
	s_nop 0
	global_load_lds_dwordx4 v128, s[82:83]
	s_mov_b32 m0, s73
	s_nop 0
	global_load_lds_dwordx4 v130, s[82:83]
	s_waitcnt vmcnt(8)
	s_waitcnt lgkmcnt(0)
	s_barrier
	s_setprio 1
	s_waitcnt lgkmcnt(0)
	v_mfma_f32_16x16x32_bf16 v[60:63], v[138:141], v[186:189], v[60:63]
	v_mfma_f32_16x16x32_bf16 v[56:59], v[152:155], v[186:189], v[56:59]
	v_mfma_f32_16x16x32_bf16 v[44:47], v[138:141], v[194:197], v[44:47]
	v_mfma_f32_16x16x32_bf16 v[40:43], v[152:155], v[194:197], v[40:43]
	v_mfma_f32_16x16x32_bf16 v[28:31], v[138:141], v[202:205], v[28:31]
	v_mfma_f32_16x16x32_bf16 v[24:27], v[152:155], v[202:205], v[24:27]
	v_mfma_f32_16x16x32_bf16 v[12:15], v[138:141], v[210:213], v[12:15]
	v_mfma_f32_16x16x32_bf16 v[8:11], v[152:155], v[210:213], v[8:11]
	v_mfma_f32_16x16x32_bf16 v[60:63], v[148:151], v[190:193], v[60:63]
	v_mfma_f32_16x16x32_bf16 v[56:59], v[156:159], v[190:193], v[56:59]
	v_mfma_f32_16x16x32_bf16 v[44:47], v[148:151], v[198:201], v[44:47]
	v_mfma_f32_16x16x32_bf16 v[40:43], v[156:159], v[198:201], v[40:43]
	v_mfma_f32_16x16x32_bf16 v[28:31], v[148:151], v[206:209], v[28:31]
	v_mfma_f32_16x16x32_bf16 v[24:27], v[156:159], v[206:209], v[24:27]
	v_mfma_f32_16x16x32_bf16 v[12:15], v[148:151], v[214:217], v[12:15]
	v_mfma_f32_16x16x32_bf16 v[8:11], v[156:159], v[214:217], v[8:11]
	s_setprio 0
	s_setprio 1
	v_mfma_f32_16x16x32_bf16 v[52:55], v[170:173], v[186:189], v[52:55]
	v_mfma_f32_16x16x32_bf16 v[48:51], v[178:181], v[186:189], v[48:51]
	v_mfma_f32_16x16x32_bf16 v[36:39], v[170:173], v[194:197], v[36:39]
	v_mfma_f32_16x16x32_bf16 v[32:35], v[178:181], v[194:197], v[32:35]
	v_mfma_f32_16x16x32_bf16 v[20:23], v[170:173], v[202:205], v[20:23]
	v_mfma_f32_16x16x32_bf16 v[16:19], v[178:181], v[202:205], v[16:19]
	v_mfma_f32_16x16x32_bf16 v[4:7], v[170:173], v[210:213], v[4:7]
	v_mfma_f32_16x16x32_bf16 v[0:3], v[178:181], v[210:213], v[0:3]
	v_mfma_f32_16x16x32_bf16 v[52:55], v[174:177], v[190:193], v[52:55]
	v_mfma_f32_16x16x32_bf16 v[48:51], v[182:185], v[190:193], v[48:51]
	v_mfma_f32_16x16x32_bf16 v[36:39], v[174:177], v[198:201], v[36:39]
	v_mfma_f32_16x16x32_bf16 v[32:35], v[182:185], v[198:201], v[32:35]
	v_mfma_f32_16x16x32_bf16 v[20:23], v[174:177], v[206:209], v[20:23]
	v_mfma_f32_16x16x32_bf16 v[16:19], v[182:185], v[206:209], v[16:19]
	v_mfma_f32_16x16x32_bf16 v[4:7], v[174:177], v[214:217], v[4:7]
	v_mfma_f32_16x16x32_bf16 v[0:3], v[182:185], v[214:217], v[0:3]
	s_setprio 0
	s_barrier
; #define PG8_STAGE(bufoff, gbase, voff) do { _Pragma("unroll") for (int _i = 0; _i < 2; ++_i) \
;         __builtin_amdgcn_global_load_lds((const unsigned*)((const char*)(gbase) + (voff)[_i]), (LAS unsigned*)(lds + (bufoff) + ldsw + _i * 8192), 16, 0, 0); } while (0)
; #define PG8_LDA(dst, b, h) do { _Pragma("unroll") for (int m = 0; m < 4; ++m) _Pragma("unroll") for (int k = 0; k < 2; ++k) dst[m][k] = *(const LAS bf16x8*)(lds + PG8_SA(b, h) + aoff + m * 2048 + k * 1024); } while (0)
; #define PG8_LDB(dst, b, h) do { _Pragma("unroll") for (int n = 0; n < 2; ++n) _Pragma("unroll") for (int k = 0; k < 2; ++k) dst[n][k] = *(const LAS bf16x8*)(lds + PG8_SB(b, h) + boff + n * 2048 + k * 1024); } while (0)
; #define PG8_MMA(ai, bj, At, Bt) do { __builtin_amdgcn_s_setprio(1); _Pragma("unroll") for (int m = 0; m < 4; ++m) _Pragma("unroll") for (int n = 0; n < 2; ++n) _Pragma("unroll") for (int k = 0; k < 2; ++k) \
;         acc[ai][bj][m][n] = __builtin_amdgcn_mfma_f32_16x16x32_bf16(Bt[n][k], At[m][k], acc[ai][bj][m][n], 0, 0, 0); __builtin_amdgcn_s_setprio(0); } while (0)
; #define PG8_WAIT_V(n) asm volatile("s_waitcnt vmcnt(" #n ")" ::: "memory")
; #define PG8_WAIT_L(n) asm volatile("s_waitcnt lgkmcnt(" #n ")" ::: "memory")
; #define PG8_BAR __builtin_amdgcn_s_barrier()
; #define PG8_SCHED __builtin_amdgcn_sched_barrier(0)
; template <class Epi, class Sched, bool ALIGN_EPI = true, bool SP2 = true>
; __device__ __forceinline__ void gemm_phase(LAS unsigned char* lds, const Gemm g, const Sched& S, const Epi& E) {
;     ...
;             PG8_LDB(B0, 1, 0); PG8_LDB(B1, 1, 1); PG8_SCHED; PG8_LDA(At, 1, 0); PG8_STAGE(PG8_SA(0, 1), a2 + hstep, voffA);
;             PG8_WAIT_V(8); PG8_WAIT_L(0); PG8_BAR; PG8_MMA(0, 0, At, B0); PG8_MMA(0, 1, At, B1); PG8_BAR; PG8_SCHED;
;             PG8_LDA(At, 1, 1); PG8_STAGE(PG8_SB(1, 0), b3, voffB); PG8_STAGE(PG8_SB(1, 1), b3 + hstep, voffB); PG8_STAGE(PG8_SA(1, 0), a3, voffA);
;             PG8_WAIT_V(8); PG8_WAIT_L(0); PG8_BAR; PG8_MMA(1, 0, At, B0); PG8_MMA(1, 1, At, B1); PG8_BAR; PG8_SCHED;
	s_add_i32 s48, 0, 0x18000
	s_add_i32 s49, 0, 0x1c000
	v_add_u32_e32 v156, s48, v145
	v_add_u32_e32 v182, s49, v145
	ds_read_b128 v[138:141], v156
	ds_read_b128 v[148:151], v156 offset:1024
	ds_read_b128 v[152:155], v156 offset:2048
	ds_read_b128 v[156:159], v156 offset:3072
	ds_read_b128 v[170:173], v182
	ds_read_b128 v[174:177], v182 offset:1024
	ds_read_b128 v[178:181], v182 offset:2048
	ds_read_b128 v[182:185], v182 offset:3072
	s_add_u32 s46, s82, 0x20000
	s_addc_u32 s47, s83, 0
	s_mov_b32 m0, s94
	ds_read_b128 v[186:189], v147 offset:32768
	ds_read_b128 v[190:193], v147 offset:33792
	ds_read_b128 v[194:197], v147 offset:34816
	ds_read_b128 v[198:201], v147 offset:35840
	ds_read_b128 v[202:205], v147 offset:36864
	ds_read_b128 v[206:209], v147 offset:37888
	ds_read_b128 v[210:213], v147 offset:38912
	ds_read_b128 v[214:217], v147 offset:39936
	global_load_lds_dwordx4 v128, s[46:47]
	s_mov_b32 m0, s95
	s_nop 0
	global_load_lds_dwordx4 v130, s[46:47]
	s_waitcnt vmcnt(8)
	s_waitcnt lgkmcnt(0)
	s_barrier
	s_setprio 1
	s_waitcnt lgkmcnt(0)
	v_mfma_f32_16x16x32_bf16 v[124:127], v[138:141], v[186:189], v[124:127]
	v_mfma_f32_16x16x32_bf16 v[120:123], v[152:155], v[186:189], v[120:123]
	v_mfma_f32_16x16x32_bf16 v[108:111], v[138:141], v[194:197], v[108:111]
	v_mfma_f32_16x16x32_bf16 v[104:107], v[152:155], v[194:197], v[104:107]
	v_mfma_f32_16x16x32_bf16 v[92:95], v[138:141], v[202:205], v[92:95]
	v_mfma_f32_16x16x32_bf16 v[88:91], v[152:155], v[202:205], v[88:91]
	v_mfma_f32_16x16x32_bf16 v[76:79], v[138:141], v[210:213], v[76:79]
	v_mfma_f32_16x16x32_bf16 v[72:75], v[152:155], v[210:213], v[72:75]
	v_mfma_f32_16x16x32_bf16 v[124:127], v[148:151], v[190:193], v[124:127]
	v_mfma_f32_16x16x32_bf16 v[120:123], v[156:159], v[190:193], v[120:123]
	v_mfma_f32_16x16x32_bf16 v[108:111], v[148:151], v[198:201], v[108:111]
	v_mfma_f32_16x16x32_bf16 v[104:107], v[156:159], v[198:201], v[104:107]
	v_mfma_f32_16x16x32_bf16 v[92:95], v[148:151], v[206:209], v[92:95]
	v_mfma_f32_16x16x32_bf16 v[88:91], v[156:159], v[206:209], v[88:91]
	v_mfma_f32_16x16x32_bf16 v[76:79], v[148:151], v[214:217], v[76:79]
	v_mfma_f32_16x16x32_bf16 v[72:75], v[156:159], v[214:217], v[72:75]
	s_setprio 0
	s_setprio 1
	v_mfma_f32_16x16x32_bf16 v[116:119], v[170:173], v[186:189], v[116:119]
	v_mfma_f32_16x16x32_bf16 v[112:115], v[178:181], v[186:189], v[112:115]
	v_mfma_f32_16x16x32_bf16 v[100:103], v[170:173], v[194:197], v[100:103]
	v_mfma_f32_16x16x32_bf16 v[96:99], v[178:181], v[194:197], v[96:99]
	v_mfma_f32_16x16x32_bf16 v[84:87], v[170:173], v[202:205], v[84:87]
	v_mfma_f32_16x16x32_bf16 v[80:83], v[178:181], v[202:205], v[80:83]
	v_mfma_f32_16x16x32_bf16 v[68:71], v[170:173], v[210:213], v[68:71]
	v_mfma_f32_16x16x32_bf16 v[64:67], v[178:181], v[210:213], v[64:67]
	v_mfma_f32_16x16x32_bf16 v[116:119], v[174:177], v[190:193], v[116:119]
	v_mfma_f32_16x16x32_bf16 v[112:115], v[182:185], v[190:193], v[112:115]
	v_mfma_f32_16x16x32_bf16 v[100:103], v[174:177], v[198:201], v[100:103]
	v_mfma_f32_16x16x32_bf16 v[96:99], v[182:185], v[198:201], v[96:99]
	v_mfma_f32_16x16x32_bf16 v[84:87], v[174:177], v[206:209], v[84:87]
	v_mfma_f32_16x16x32_bf16 v[80:83], v[182:185], v[206:209], v[80:83]
	v_mfma_f32_16x16x32_bf16 v[68:71], v[174:177], v[214:217], v[68:71]
	v_mfma_f32_16x16x32_bf16 v[64:67], v[182:185], v[214:217], v[64:67]
	s_setprio 0
	s_barrier
	s_add_i32 s46, s48, s93
	s_mov_b32 m0, s46
	ds_read_b128 v[186:189], v147 offset:49152
	ds_read_b128 v[190:193], v147 offset:50176
	ds_read_b128 v[194:197], v147 offset:51200
	ds_read_b128 v[198:201], v147 offset:52224
	ds_read_b128 v[202:205], v147 offset:53248
	ds_read_b128 v[206:209], v147 offset:54272
	ds_read_b128 v[210:213], v147 offset:55296
	ds_read_b128 v[214:217], v147 offset:56320
	s_add_u32 s98, s24, 0x80
	s_addc_u32 s99, s25, 0
	global_load_lds_dwordx4 v160, s[98:99]
	s_add_i32 m0, s46, 0x2000
	s_add_u32 s24, s24, 0x20080
	s_addc_u32 s25, s25, 0
	s_add_i32 s46, s49, s93
	global_load_lds_dwordx4 v132, s[98:99]
	s_mov_b32 m0, s46
	s_nop 0
	global_load_lds_dwordx4 v160, s[24:25]
	s_add_i32 m0, s46, 0x2000
	s_nop 0
	global_load_lds_dwordx4 v132, s[24:25]
	s_mov_b32 m0, s96
	s_nop 0
	s_add_u32 s98, s82, 0x80
	s_addc_u32 s99, s83, 0
	global_load_lds_dwordx4 v128, s[98:99]
	s_mov_b32 m0, s97
	s_nop 0
	global_load_lds_dwordx4 v130, s[98:99]
	s_waitcnt vmcnt(8)
	s_waitcnt lgkmcnt(0)
	s_barrier
	s_setprio 1
	s_waitcnt lgkmcnt(0)
	v_mfma_f32_16x16x32_bf16 v[60:63], v[138:141], v[186:189], v[60:63]
	v_mfma_f32_16x16x32_bf16 v[56:59], v[152:155], v[186:189], v[56:59]
	v_mfma_f32_16x16x32_bf16 v[44:47], v[138:141], v[194:197], v[44:47]
	v_mfma_f32_16x16x32_bf16 v[40:43], v[152:155], v[194:197], v[40:43]
	v_mfma_f32_16x16x32_bf16 v[28:31], v[138:141], v[202:205], v[28:31]
	v_mfma_f32_16x16x32_bf16 v[24:27], v[152:155], v[202:205], v[24:27]
	v_mfma_f32_16x16x32_bf16 v[12:15], v[138:141], v[210:213], v[12:15]
	v_mfma_f32_16x16x32_bf16 v[8:11], v[152:155], v[210:213], v[8:11]
	v_mfma_f32_16x16x32_bf16 v[60:63], v[148:151], v[190:193], v[60:63]
	v_mfma_f32_16x16x32_bf16 v[56:59], v[156:159], v[190:193], v[56:59]
	v_mfma_f32_16x16x32_bf16 v[44:47], v[148:151], v[198:201], v[44:47]
	v_mfma_f32_16x16x32_bf16 v[40:43], v[156:159], v[198:201], v[40:43]
	v_mfma_f32_16x16x32_bf16 v[28:31], v[148:151], v[206:209], v[28:31]
	v_mfma_f32_16x16x32_bf16 v[24:27], v[156:159], v[206:209], v[24:27]
	v_mfma_f32_16x16x32_bf16 v[12:15], v[148:151], v[214:217], v[12:15]
	v_mfma_f32_16x16x32_bf16 v[8:11], v[156:159], v[214:217], v[8:11]
	s_setprio 0
	s_setprio 1
	v_mfma_f32_16x16x32_bf16 v[52:55], v[170:173], v[186:189], v[52:55]
	v_mfma_f32_16x16x32_bf16 v[48:51], v[178:181], v[186:189], v[48:51]
	v_mfma_f32_16x16x32_bf16 v[36:39], v[170:173], v[194:197], v[36:39]
	v_mfma_f32_16x16x32_bf16 v[32:35], v[178:181], v[194:197], v[32:35]
	v_mfma_f32_16x16x32_bf16 v[20:23], v[170:173], v[202:205], v[20:23]
	v_mfma_f32_16x16x32_bf16 v[16:19], v[178:181], v[202:205], v[16:19]
	v_mfma_f32_16x16x32_bf16 v[4:7], v[170:173], v[210:213], v[4:7]
	v_mfma_f32_16x16x32_bf16 v[0:3], v[178:181], v[210:213], v[0:3]
	v_mfma_f32_16x16x32_bf16 v[52:55], v[174:177], v[190:193], v[52:55]
	v_mfma_f32_16x16x32_bf16 v[48:51], v[182:185], v[190:193], v[48:51]
	v_mfma_f32_16x16x32_bf16 v[36:39], v[174:177], v[198:201], v[36:39]
	v_mfma_f32_16x16x32_bf16 v[32:35], v[182:185], v[198:201], v[32:35]
	v_mfma_f32_16x16x32_bf16 v[20:23], v[174:177], v[206:209], v[20:23]
	v_mfma_f32_16x16x32_bf16 v[16:19], v[182:185], v[206:209], v[16:19]
	v_mfma_f32_16x16x32_bf16 v[4:7], v[174:177], v[214:217], v[4:7]
	v_mfma_f32_16x16x32_bf16 v[0:3], v[182:185], v[214:217], v[0:3]
	s_setprio 0
	s_barrier
	s_add_i32 vcc_hi, vcc_hi, 2
	s_add_u32 s90, s90, 0x100
	s_addc_u32 s91, s91, 0
	s_add_u32 s55, s55, 0x100
	s_addc_u32 vcc_lo, vcc_lo, 0
	s_cmp_gt_u32 vcc_hi, 5
	s_cbranch_scc0 .LBB0_40
	s_and_b64 vcc, exec, s[30:31]
	s_cbranch_vccz .LBB0_43
	s_barrier

; #define PG8_STAGE(bufoff, gbase, voff) do { _Pragma("unroll") for (int _i = 0; _i < 2; ++_i) \
;         __builtin_amdgcn_global_load_lds((const unsigned*)((const char*)(gbase) + (voff)[_i]), (LAS unsigned*)(lds + (bufoff) + ldsw + _i * 8192), 16, 0, 0); } while (0)
; #define PG8_LDA(dst, b, h) do { _Pragma("unroll") for (int m = 0; m < 4; ++m) _Pragma("unroll") for (int k = 0; k < 2; ++k) dst[m][k] = *(const LAS bf16x8*)(lds + PG8_SA(b, h) + aoff + m * 2048 + k * 1024); } while (0)
; #define PG8_LDB(dst, b, h) do { _Pragma("unroll") for (int n = 0; n < 2; ++n) _Pragma("unroll") for (int k = 0; k < 2; ++k) dst[n][k] = *(const LAS bf16x8*)(lds + PG8_SB(b, h) + boff + n * 2048 + k * 1024); } while (0)
; #define PG8_MMA(ai, bj, At, Bt) do { __builtin_amdgcn_s_setprio(1); _Pragma("unroll") for (int m = 0; m < 4; ++m) _Pragma("unroll") for (int n = 0; n < 2; ++n) _Pragma("unroll") for (int k = 0; k < 2; ++k) \
;         acc[ai][bj][m][n] = __builtin_amdgcn_mfma_f32_16x16x32_bf16(Bt[n][k], At[m][k], acc[ai][bj][m][n], 0, 0, 0); __builtin_amdgcn_s_setprio(0); } while (0)
; #define PG8_WAIT_V(n) asm volatile("s_waitcnt vmcnt(" #n ")" ::: "memory")
; #define PG8_WAIT_L(n) asm volatile("s_waitcnt lgkmcnt(" #n ")" ::: "memory")
; #define PG8_BAR __builtin_amdgcn_s_barrier()
; #define PG8_SCHED __builtin_amdgcn_sched_barrier(0)
; template <class Epi, class Sched, bool ALIGN_EPI = true, bool SP2 = true>
; __device__ __forceinline__ void gemm_phase(LAS unsigned char* lds, const Gemm g, const Sched& S, const Epi& E) {
;     ...
;             PG8_LDB(B0, 0, 0); PG8_LDB(B1, 0, 1); PG8_SCHED; PG8_LDA(At, 0, 0); PG8_STAGE(PG8_SA(1, 1), a1 + hstep, voffA);
;             PG8_WAIT_V(8); PG8_WAIT_L(0); PG8_BAR; PG8_MMA(0, 0, At, B0); PG8_MMA(0, 1, At, B1); PG8_BAR; PG8_SCHED;
;             PG8_LDA(At, 0, 1); PG8_STAGE(PG8_SB(0, 0), b2, voffB); PG8_STAGE(PG8_SB(0, 1), b2 + hstep, voffB); PG8_STAGE(PG8_SA(0, 0), a2, voffA);
;             PG8_WAIT_V(8); PG8_WAIT_L(0); PG8_BAR; PG8_MMA(1, 0, At, B0); PG8_MMA(1, 1, At, B1); PG8_BAR; PG8_SCHED;
.LBB0_93:
	s_add_u32 s24, s62, 0xfff80080
	s_addc_u32 s25, s63, -1
	s_add_i32 s46, 0, 0x10000
	s_cmp_eq_u32 s93, 28
	s_cselect_b32 s67, s2, s25
	s_cselect_b32 s66, s3, s24
	s_cselect_b32 s25, s19, s92
	s_cselect_b32 s24, s31, s91
	s_add_i32 s47, 0, 0x14000
	v_add_u32_e32 v154, s46, v143
	v_add_u32_e32 v158, s47, v143
	ds_read_b128 v[138:141], v154
	ds_read_b128 v[146:149], v154 offset:1024
	ds_read_b128 v[150:153], v154 offset:2048
	ds_read_b128 v[154:157], v154 offset:3072
	ds_read_b128 v[170:173], v158
	ds_read_b128 v[174:177], v158 offset:1024
	ds_read_b128 v[178:181], v158 offset:2048
	ds_read_b128 v[182:185], v158 offset:3072
	s_add_i32 m0, s44, 0xc000
	ds_read_b128 v[186:189], v145
	ds_read_b128 v[190:193], v145 offset:1024
	ds_read_b128 v[194:197], v145 offset:2048
	ds_read_b128 v[198:201], v145 offset:3072
	ds_read_b128 v[202:205], v145 offset:4096
	ds_read_b128 v[206:209], v145 offset:5120
	ds_read_b128 v[210:213], v145 offset:6144
	ds_read_b128 v[214:217], v145 offset:7168
	global_load_lds_dwordx4 v134, s[62:63]
	s_add_i32 m0, s44, 0xe000
	s_nop 0
	global_load_lds_dwordx4 v136, s[62:63]
	s_waitcnt vmcnt(8)
	s_waitcnt lgkmcnt(0)
	s_barrier
	s_setprio 1
	s_waitcnt lgkmcnt(0)
	v_mfma_f32_16x16x32_bf16 v[124:127], v[138:141], v[186:189], v[124:127]
	v_mfma_f32_16x16x32_bf16 v[120:123], v[150:153], v[186:189], v[120:123]
	v_mfma_f32_16x16x32_bf16 v[108:111], v[138:141], v[194:197], v[108:111]
	v_mfma_f32_16x16x32_bf16 v[104:107], v[150:153], v[194:197], v[104:107]
	v_mfma_f32_16x16x32_bf16 v[92:95], v[138:141], v[202:205], v[92:95]
	v_mfma_f32_16x16x32_bf16 v[88:91], v[150:153], v[202:205], v[88:91]
	v_mfma_f32_16x16x32_bf16 v[76:79], v[138:141], v[210:213], v[76:79]
	v_mfma_f32_16x16x32_bf16 v[72:75], v[150:153], v[210:213], v[72:75]
	v_mfma_f32_16x16x32_bf16 v[124:127], v[146:149], v[190:193], v[124:127]
	v_mfma_f32_16x16x32_bf16 v[120:123], v[154:157], v[190:193], v[120:123]
	v_mfma_f32_16x16x32_bf16 v[108:111], v[146:149], v[198:201], v[108:111]
	v_mfma_f32_16x16x32_bf16 v[104:107], v[154:157], v[198:201], v[104:107]
	v_mfma_f32_16x16x32_bf16 v[92:95], v[146:149], v[206:209], v[92:95]
	v_mfma_f32_16x16x32_bf16 v[88:91], v[154:157], v[206:209], v[88:91]
	v_mfma_f32_16x16x32_bf16 v[76:79], v[146:149], v[214:217], v[76:79]
	v_mfma_f32_16x16x32_bf16 v[72:75], v[154:157], v[214:217], v[72:75]
	s_setprio 0
	s_setprio 1
	v_mfma_f32_16x16x32_bf16 v[116:119], v[170:173], v[186:189], v[116:119]
	v_mfma_f32_16x16x32_bf16 v[112:115], v[178:181], v[186:189], v[112:115]
	v_mfma_f32_16x16x32_bf16 v[100:103], v[170:173], v[194:197], v[100:103]
	v_mfma_f32_16x16x32_bf16 v[96:99], v[178:181], v[194:197], v[96:99]
	v_mfma_f32_16x16x32_bf16 v[84:87], v[170:173], v[202:205], v[84:87]
	v_mfma_f32_16x16x32_bf16 v[80:83], v[178:181], v[202:205], v[80:83]
	v_mfma_f32_16x16x32_bf16 v[68:71], v[170:173], v[210:213], v[68:71]
	v_mfma_f32_16x16x32_bf16 v[64:67], v[178:181], v[210:213], v[64:67]
	v_mfma_f32_16x16x32_bf16 v[116:119], v[174:177], v[190:193], v[116:119]
	v_mfma_f32_16x16x32_bf16 v[112:115], v[182:185], v[190:193], v[112:115]
	v_mfma_f32_16x16x32_bf16 v[100:103], v[174:177], v[198:201], v[100:103]
	v_mfma_f32_16x16x32_bf16 v[96:99], v[182:185], v[198:201], v[96:99]
	v_mfma_f32_16x16x32_bf16 v[84:87], v[174:177], v[206:209], v[84:87]
	v_mfma_f32_16x16x32_bf16 v[80:83], v[182:185], v[206:209], v[80:83]
	v_mfma_f32_16x16x32_bf16 v[68:71], v[174:177], v[214:217], v[68:71]
	v_mfma_f32_16x16x32_bf16 v[64:67], v[182:185], v[214:217], v[64:67]
	s_setprio 0
	s_barrier
	s_add_i32 s46, s46, s43
	s_mov_b32 m0, s46
	ds_read_b128 v[186:189], v145 offset:16384
	ds_read_b128 v[190:193], v145 offset:17408
	ds_read_b128 v[194:197], v145 offset:18432
	ds_read_b128 v[198:201], v145 offset:19456
	ds_read_b128 v[202:205], v145 offset:20480
	ds_read_b128 v[206:209], v145 offset:21504
	ds_read_b128 v[210:213], v145 offset:22528
	ds_read_b128 v[214:217], v145 offset:23552
	global_load_lds_dwordx4 v160, s[24:25]
	s_add_i32 m0, s46, 0x2000
	s_add_u32 s94, s24, 0x80000
	s_addc_u32 s95, s25, 0
	s_add_i32 s46, s47, s43
	global_load_lds_dwordx4 v132, s[24:25]
	s_mov_b32 m0, s46
	s_nop 0
	global_load_lds_dwordx4 v160, s[94:95]
	s_add_i32 m0, s46, 0x2000
	s_nop 0
	global_load_lds_dwordx4 v132, s[94:95]
	s_mov_b32 m0, s44
	s_nop 0
	global_load_lds_dwordx4 v128, s[66:67]
	s_mov_b32 m0, s45
	s_nop 0
	global_load_lds_dwordx4 v130, s[66:67]
	s_waitcnt vmcnt(8)
	s_waitcnt lgkmcnt(0)
	s_barrier
	s_setprio 1
	s_waitcnt lgkmcnt(0)
	v_mfma_f32_16x16x32_bf16 v[60:63], v[138:141], v[186:189], v[60:63]
	v_mfma_f32_16x16x32_bf16 v[56:59], v[150:153], v[186:189], v[56:59]
	v_mfma_f32_16x16x32_bf16 v[44:47], v[138:141], v[194:197], v[44:47]
	v_mfma_f32_16x16x32_bf16 v[40:43], v[150:153], v[194:197], v[40:43]
	v_mfma_f32_16x16x32_bf16 v[28:31], v[138:141], v[202:205], v[28:31]
	v_mfma_f32_16x16x32_bf16 v[24:27], v[150:153], v[202:205], v[24:27]
	v_mfma_f32_16x16x32_bf16 v[12:15], v[138:141], v[210:213], v[12:15]
	v_mfma_f32_16x16x32_bf16 v[8:11], v[150:153], v[210:213], v[8:11]
	v_mfma_f32_16x16x32_bf16 v[60:63], v[146:149], v[190:193], v[60:63]
	v_mfma_f32_16x16x32_bf16 v[56:59], v[154:157], v[190:193], v[56:59]
	v_mfma_f32_16x16x32_bf16 v[44:47], v[146:149], v[198:201], v[44:47]
	v_mfma_f32_16x16x32_bf16 v[40:43], v[154:157], v[198:201], v[40:43]
	v_mfma_f32_16x16x32_bf16 v[28:31], v[146:149], v[206:209], v[28:31]
	v_mfma_f32_16x16x32_bf16 v[24:27], v[154:157], v[206:209], v[24:27]
	v_mfma_f32_16x16x32_bf16 v[12:15], v[146:149], v[214:217], v[12:15]
	v_mfma_f32_16x16x32_bf16 v[8:11], v[154:157], v[214:217], v[8:11]
	s_setprio 0
	s_setprio 1
	v_mfma_f32_16x16x32_bf16 v[52:55], v[170:173], v[186:189], v[52:55]
	v_mfma_f32_16x16x32_bf16 v[48:51], v[178:181], v[186:189], v[48:51]
	v_mfma_f32_16x16x32_bf16 v[36:39], v[170:173], v[194:197], v[36:39]
	v_mfma_f32_16x16x32_bf16 v[32:35], v[178:181], v[194:197], v[32:35]
	v_mfma_f32_16x16x32_bf16 v[20:23], v[170:173], v[202:205], v[20:23]
	v_mfma_f32_16x16x32_bf16 v[16:19], v[178:181], v[202:205], v[16:19]
	v_mfma_f32_16x16x32_bf16 v[4:7], v[170:173], v[210:213], v[4:7]
	v_mfma_f32_16x16x32_bf16 v[0:3], v[178:181], v[210:213], v[0:3]
	v_mfma_f32_16x16x32_bf16 v[52:55], v[174:177], v[190:193], v[52:55]
	v_mfma_f32_16x16x32_bf16 v[48:51], v[182:185], v[190:193], v[48:51]
	v_mfma_f32_16x16x32_bf16 v[36:39], v[174:177], v[198:201], v[36:39]
	v_mfma_f32_16x16x32_bf16 v[32:35], v[182:185], v[198:201], v[32:35]
	v_mfma_f32_16x16x32_bf16 v[20:23], v[174:177], v[206:209], v[20:23]
	v_mfma_f32_16x16x32_bf16 v[16:19], v[182:185], v[206:209], v[16:19]
	v_mfma_f32_16x16x32_bf16 v[4:7], v[174:177], v[214:217], v[4:7]
	v_mfma_f32_16x16x32_bf16 v[0:3], v[182:185], v[214:217], v[0:3]
	s_setprio 0
	s_barrier
; #define PG8_STAGE(bufoff, gbase, voff) do { _Pragma("unroll") for (int _i = 0; _i < 2; ++_i) \
;         __builtin_amdgcn_global_load_lds((const unsigned*)((const char*)(gbase) + (voff)[_i]), (LAS unsigned*)(lds + (bufoff) + ldsw + _i * 8192), 16, 0, 0); } while (0)
; #define PG8_LDA(dst, b, h) do { _Pragma("unroll") for (int m = 0; m < 4; ++m) _Pragma("unroll") for (int k = 0; k < 2; ++k) dst[m][k] = *(const LAS bf16x8*)(lds + PG8_SA(b, h) + aoff + m * 2048 + k * 1024); } while (0)
; #define PG8_LDB(dst, b, h) do { _Pragma("unroll") for (int n = 0; n < 2; ++n) _Pragma("unroll") for (int k = 0; k < 2; ++k) dst[n][k] = *(const LAS bf16x8*)(lds + PG8_SB(b, h) + boff + n * 2048 + k * 1024); } while (0)
; #define PG8_MMA(ai, bj, At, Bt) do { __builtin_amdgcn_s_setprio(1); _Pragma("unroll") for (int m = 0; m < 4; ++m) _Pragma("unroll") for (int n = 0; n < 2; ++n) _Pragma("unroll") for (int k = 0; k < 2; ++k) \
;         acc[ai][bj][m][n] = __builtin_amdgcn_mfma_f32_16x16x32_bf16(Bt[n][k], At[m][k], acc[ai][bj][m][n], 0, 0, 0); __builtin_amdgcn_s_setprio(0); } while (0)
; #define PG8_WAIT_V(n) asm volatile("s_waitcnt vmcnt(" #n ")" ::: "memory")
; #define PG8_WAIT_L(n) asm volatile("s_waitcnt lgkmcnt(" #n ")" ::: "memory")
; #define PG8_BAR __builtin_amdgcn_s_barrier()
; #define PG8_SCHED __builtin_amdgcn_sched_barrier(0)
; template <class Epi, class Sched, bool ALIGN_EPI = true, bool SP2 = true>
; __device__ __forceinline__ void gemm_phase(LAS unsigned char* lds, const Gemm g, const Sched& S, const Epi& E) {
;     ...
;             PG8_LDB(B0, 1, 0); PG8_LDB(B1, 1, 1); PG8_SCHED; PG8_LDA(At, 1, 0); PG8_STAGE(PG8_SA(0, 1), a2 + hstep, voffA);
;             PG8_WAIT_V(8); PG8_WAIT_L(0); PG8_BAR; PG8_MMA(0, 0, At, B0); PG8_MMA(0, 1, At, B1); PG8_BAR; PG8_SCHED;
;             PG8_LDA(At, 1, 1); PG8_STAGE(PG8_SB(1, 0), b3, voffB); PG8_STAGE(PG8_SB(1, 1), b3 + hstep, voffB); PG8_STAGE(PG8_SA(1, 0), a3, voffA);
;             PG8_WAIT_V(8); PG8_WAIT_L(0); PG8_BAR; PG8_MMA(1, 0, At, B0); PG8_MMA(1, 1, At, B1); PG8_BAR; PG8_SCHED;
	s_add_i32 s46, 0, 0x18000
	s_add_i32 s47, 0, 0x1c000
	v_add_u32_e32 v154, s46, v143
	v_add_u32_e32 v182, s47, v143
	ds_read_b128 v[138:141], v154
	ds_read_b128 v[146:149], v154 offset:1024
	ds_read_b128 v[150:153], v154 offset:2048
	ds_read_b128 v[154:157], v154 offset:3072
	ds_read_b128 v[170:173], v182
	ds_read_b128 v[174:177], v182 offset:1024
	ds_read_b128 v[178:181], v182 offset:2048
	ds_read_b128 v[182:185], v182 offset:3072
	s_add_u32 s66, s66, 0x80000
	s_addc_u32 s67, s67, 0
	s_mov_b32 m0, s61
	ds_read_b128 v[186:189], v145 offset:32768
	ds_read_b128 v[190:193], v145 offset:33792
	ds_read_b128 v[194:197], v145 offset:34816
	ds_read_b128 v[198:201], v145 offset:35840
	ds_read_b128 v[202:205], v145 offset:36864
	ds_read_b128 v[206:209], v145 offset:37888
	ds_read_b128 v[210:213], v145 offset:38912
	ds_read_b128 v[214:217], v145 offset:39936
	global_load_lds_dwordx4 v128, s[66:67]
	s_mov_b32 m0, s72
	s_nop 0
	global_load_lds_dwordx4 v130, s[66:67]
	s_waitcnt vmcnt(8)
	s_waitcnt lgkmcnt(0)
	s_barrier
	s_setprio 1
	s_waitcnt lgkmcnt(0)
	v_mfma_f32_16x16x32_bf16 v[124:127], v[138:141], v[186:189], v[124:127]
	v_mfma_f32_16x16x32_bf16 v[120:123], v[150:153], v[186:189], v[120:123]
	v_mfma_f32_16x16x32_bf16 v[108:111], v[138:141], v[194:197], v[108:111]
	v_mfma_f32_16x16x32_bf16 v[104:107], v[150:153], v[194:197], v[104:107]
	v_mfma_f32_16x16x32_bf16 v[92:95], v[138:141], v[202:205], v[92:95]
	v_mfma_f32_16x16x32_bf16 v[88:91], v[150:153], v[202:205], v[88:91]
	v_mfma_f32_16x16x32_bf16 v[76:79], v[138:141], v[210:213], v[76:79]
	v_mfma_f32_16x16x32_bf16 v[72:75], v[150:153], v[210:213], v[72:75]
	v_mfma_f32_16x16x32_bf16 v[124:127], v[146:149], v[190:193], v[124:127]
	v_mfma_f32_16x16x32_bf16 v[120:123], v[154:157], v[190:193], v[120:123]
	v_mfma_f32_16x16x32_bf16 v[108:111], v[146:149], v[198:201], v[108:111]
	v_mfma_f32_16x16x32_bf16 v[104:107], v[154:157], v[198:201], v[104:107]
	v_mfma_f32_16x16x32_bf16 v[92:95], v[146:149], v[206:209], v[92:95]
	v_mfma_f32_16x16x32_bf16 v[88:91], v[154:157], v[206:209], v[88:91]
	v_mfma_f32_16x16x32_bf16 v[76:79], v[146:149], v[214:217], v[76:79]
	v_mfma_f32_16x16x32_bf16 v[72:75], v[154:157], v[214:217], v[72:75]
	s_setprio 0
	s_setprio 1
	v_mfma_f32_16x16x32_bf16 v[116:119], v[170:173], v[186:189], v[116:119]
	v_mfma_f32_16x16x32_bf16 v[112:115], v[178:181], v[186:189], v[112:115]
	v_mfma_f32_16x16x32_bf16 v[100:103], v[170:173], v[194:197], v[100:103]
	v_mfma_f32_16x16x32_bf16 v[96:99], v[178:181], v[194:197], v[96:99]
	v_mfma_f32_16x16x32_bf16 v[84:87], v[170:173], v[202:205], v[84:87]
	v_mfma_f32_16x16x32_bf16 v[80:83], v[178:181], v[202:205], v[80:83]
	v_mfma_f32_16x16x32_bf16 v[68:71], v[170:173], v[210:213], v[68:71]
	v_mfma_f32_16x16x32_bf16 v[64:67], v[178:181], v[210:213], v[64:67]
	v_mfma_f32_16x16x32_bf16 v[116:119], v[174:177], v[190:193], v[116:119]
	v_mfma_f32_16x16x32_bf16 v[112:115], v[182:185], v[190:193], v[112:115]
	v_mfma_f32_16x16x32_bf16 v[100:103], v[174:177], v[198:201], v[100:103]
	v_mfma_f32_16x16x32_bf16 v[96:99], v[182:185], v[198:201], v[96:99]
	v_mfma_f32_16x16x32_bf16 v[84:87], v[174:177], v[206:209], v[84:87]
	v_mfma_f32_16x16x32_bf16 v[80:83], v[182:185], v[206:209], v[80:83]
	v_mfma_f32_16x16x32_bf16 v[68:71], v[174:177], v[214:217], v[68:71]
	v_mfma_f32_16x16x32_bf16 v[64:67], v[182:185], v[214:217], v[64:67]
	s_setprio 0
	s_barrier
	s_add_i32 s46, s46, s43
	s_mov_b32 m0, s46
	ds_read_b128 v[186:189], v145 offset:49152
	ds_read_b128 v[190:193], v145 offset:50176
	ds_read_b128 v[194:197], v145 offset:51200
	ds_read_b128 v[198:201], v145 offset:52224
	ds_read_b128 v[202:205], v145 offset:53248
	ds_read_b128 v[206:209], v145 offset:54272
	ds_read_b128 v[210:213], v145 offset:55296
	ds_read_b128 v[214:217], v145 offset:56320
	s_add_u32 s98, s24, 0x80
	s_addc_u32 s99, s25, 0
	global_load_lds_dwordx4 v160, s[98:99]
	s_add_i32 m0, s46, 0x2000
	s_add_u32 s24, s24, 0x80080
	s_addc_u32 s25, s25, 0
	s_add_i32 s46, s47, s43
	global_load_lds_dwordx4 v132, s[98:99]
	s_mov_b32 m0, s46
	s_nop 0
	global_load_lds_dwordx4 v160, s[24:25]
	s_add_i32 m0, s46, 0x2000
	s_nop 0
	global_load_lds_dwordx4 v132, s[24:25]
	s_mov_b32 m0, s73
	s_nop 0
	s_add_u32 s98, s66, 0xfff80080
	s_addc_u32 s99, s67, -1
	global_load_lds_dwordx4 v128, s[98:99]
	s_mov_b32 m0, s79
	s_nop 0
	global_load_lds_dwordx4 v130, s[98:99]
	s_waitcnt vmcnt(8)
	s_waitcnt lgkmcnt(0)
	s_barrier
	s_setprio 1
	s_waitcnt lgkmcnt(0)
	v_mfma_f32_16x16x32_bf16 v[60:63], v[138:141], v[186:189], v[60:63]
	v_mfma_f32_16x16x32_bf16 v[56:59], v[150:153], v[186:189], v[56:59]
	v_mfma_f32_16x16x32_bf16 v[44:47], v[138:141], v[194:197], v[44:47]
	v_mfma_f32_16x16x32_bf16 v[40:43], v[150:153], v[194:197], v[40:43]
	v_mfma_f32_16x16x32_bf16 v[28:31], v[138:141], v[202:205], v[28:31]
	v_mfma_f32_16x16x32_bf16 v[24:27], v[150:153], v[202:205], v[24:27]
	v_mfma_f32_16x16x32_bf16 v[12:15], v[138:141], v[210:213], v[12:15]
	v_mfma_f32_16x16x32_bf16 v[8:11], v[150:153], v[210:213], v[8:11]
	v_mfma_f32_16x16x32_bf16 v[60:63], v[146:149], v[190:193], v[60:63]
	v_mfma_f32_16x16x32_bf16 v[56:59], v[154:157], v[190:193], v[56:59]
	v_mfma_f32_16x16x32_bf16 v[44:47], v[146:149], v[198:201], v[44:47]
	v_mfma_f32_16x16x32_bf16 v[40:43], v[154:157], v[198:201], v[40:43]
	v_mfma_f32_16x16x32_bf16 v[28:31], v[146:149], v[206:209], v[28:31]
	v_mfma_f32_16x16x32_bf16 v[24:27], v[154:157], v[206:209], v[24:27]
	v_mfma_f32_16x16x32_bf16 v[12:15], v[146:149], v[214:217], v[12:15]
	v_mfma_f32_16x16x32_bf16 v[8:11], v[154:157], v[214:217], v[8:11]
	s_setprio 0
	s_setprio 1
	v_mfma_f32_16x16x32_bf16 v[52:55], v[170:173], v[186:189], v[52:55]
	v_mfma_f32_16x16x32_bf16 v[48:51], v[178:181], v[186:189], v[48:51]
	v_mfma_f32_16x16x32_bf16 v[36:39], v[170:173], v[194:197], v[36:39]
	v_mfma_f32_16x16x32_bf16 v[32:35], v[178:181], v[194:197], v[32:35]
	v_mfma_f32_16x16x32_bf16 v[20:23], v[170:173], v[202:205], v[20:23]
	v_mfma_f32_16x16x32_bf16 v[16:19], v[178:181], v[202:205], v[16:19]
	v_mfma_f32_16x16x32_bf16 v[4:7], v[170:173], v[210:213], v[4:7]
	v_mfma_f32_16x16x32_bf16 v[0:3], v[178:181], v[210:213], v[0:3]
	v_mfma_f32_16x16x32_bf16 v[52:55], v[174:177], v[190:193], v[52:55]
	v_mfma_f32_16x16x32_bf16 v[48:51], v[182:185], v[190:193], v[48:51]
	v_mfma_f32_16x16x32_bf16 v[36:39], v[174:177], v[198:201], v[36:39]
	v_mfma_f32_16x16x32_bf16 v[32:35], v[182:185], v[198:201], v[32:35]
	v_mfma_f32_16x16x32_bf16 v[20:23], v[174:177], v[206:209], v[20:23]
	v_mfma_f32_16x16x32_bf16 v[16:19], v[182:185], v[206:209], v[16:19]
	v_mfma_f32_16x16x32_bf16 v[4:7], v[174:177], v[214:217], v[4:7]
	v_mfma_f32_16x16x32_bf16 v[0:3], v[182:185], v[214:217], v[0:3]
	s_setprio 0
	s_barrier
	s_add_i32 s93, s93, 2
	s_add_u32 s62, s62, 0x100
	s_addc_u32 s63, s63, 0
	s_add_u32 s91, s91, 0x100
	s_addc_u32 s92, s92, 0
	s_cmp_gt_u32 s93, 29
	s_cbranch_scc0 .LBB0_93
	s_and_b64 vcc, exec, s[16:17]
	s_movk_i32 s91, 0x161
	s_movk_i32 s92, 0x7ff
	s_cbranch_vccz .LBB0_96
	s_barrier

; #define PG8_STAGE(bufoff, gbase, voff) do { _Pragma("unroll") for (int _i = 0; _i < 2; ++_i) \
;         __builtin_amdgcn_global_load_lds((const unsigned*)((const char*)(gbase) + (voff)[_i]), (LAS unsigned*)(lds + (bufoff) + ldsw + _i * 8192), 16, 0, 0); } while (0)
; #define PG8_LDA(dst, b, h) do { _Pragma("unroll") for (int m = 0; m < 4; ++m) _Pragma("unroll") for (int k = 0; k < 2; ++k) dst[m][k] = *(const LAS bf16x8*)(lds + PG8_SA(b, h) + aoff + m * 2048 + k * 1024); } while (0)
; #define PG8_LDB(dst, b, h) do { _Pragma("unroll") for (int n = 0; n < 2; ++n) _Pragma("unroll") for (int k = 0; k < 2; ++k) dst[n][k] = *(const LAS bf16x8*)(lds + PG8_SB(b, h) + boff + n * 2048 + k * 1024); } while (0)
; #define PG8_MMA(ai, bj, At, Bt) do { __builtin_amdgcn_s_setprio(1); _Pragma("unroll") for (int m = 0; m < 4; ++m) _Pragma("unroll") for (int n = 0; n < 2; ++n) _Pragma("unroll") for (int k = 0; k < 2; ++k) \
;         acc[ai][bj][m][n] = __builtin_amdgcn_mfma_f32_16x16x32_bf16(Bt[n][k], At[m][k], acc[ai][bj][m][n], 0, 0, 0); __builtin_amdgcn_s_setprio(0); } while (0)
; #define PG8_WAIT_V(n) asm volatile("s_waitcnt vmcnt(" #n ")" ::: "memory")
; #define PG8_WAIT_L(n) asm volatile("s_waitcnt lgkmcnt(" #n ")" ::: "memory")
; #define PG8_BAR __builtin_amdgcn_s_barrier()
; #define PG8_SCHED __builtin_amdgcn_sched_barrier(0)
; template <class Epi, class Sched, bool ALIGN_EPI = true, bool SP2 = true>
; __device__ __forceinline__ void gemm_phase(LAS unsigned char* lds, const Gemm g, const Sched& S, const Epi& E) {
;     ...
;             const bool last = (t == nt - 2);
;             const char* a1 = cA + (size_t)(t + 1) * kstep;
;             const char* a2 = last ? nA : cA + (size_t)(t + 2) * kstep; const char* b2 = last ? nB : cB + (size_t)(t + 2) * kstep;
;             const char* a3 = a2 + kstep; const char* b3 = b2 + kstep;
;             if constexpr (SP2) {
;             PG8_LDB(B0, 0, 0); PG8_LDB(B1, 0, 1); PG8_SCHED; PG8_LDA(At, 0, 0); PG8_STAGE(PG8_SA(1, 1), a1 + hstep, voffA);
;             PG8_WAIT_V(8); PG8_WAIT_L(0); PG8_BAR; PG8_MMA(0, 0, At, B0); PG8_MMA(0, 1, At, B1); PG8_BAR; PG8_SCHED;
;             PG8_LDA(At, 0, 1); PG8_STAGE(PG8_SB(0, 0), b2, voffB); PG8_STAGE(PG8_SB(0, 1), b2 + hstep, voffB); PG8_STAGE(PG8_SA(0, 0), a2, voffA);
;             PG8_WAIT_V(8); PG8_WAIT_L(0); PG8_BAR; PG8_MMA(1, 0, At, B0); PG8_MMA(1, 1, At, B1); PG8_BAR; PG8_SCHED;
.LBB0_117:
	s_add_u32 s24, s62, 0xfff80080
	s_addc_u32 s25, s63, -1
	s_add_i32 s46, 0, 0x10000
	s_cmp_eq_u32 s96, 28
	s_cselect_b32 s67, s2, s25
	s_cselect_b32 s66, s3, s24
	s_cselect_b32 s25, s17, s95
	s_cselect_b32 s24, s19, s94
	s_add_i32 s47, 0, 0x14000
	v_add_u32_e32 v154, s46, v143
	v_add_u32_e32 v158, s47, v143
	ds_read_b128 v[138:141], v154
	ds_read_b128 v[146:149], v154 offset:1024
	ds_read_b128 v[150:153], v154 offset:2048
	ds_read_b128 v[154:157], v154 offset:3072
	ds_read_b128 v[170:173], v158
	ds_read_b128 v[174:177], v158 offset:1024
	ds_read_b128 v[178:181], v158 offset:2048
	ds_read_b128 v[182:185], v158 offset:3072
	s_add_i32 m0, s61, 0xc000
	ds_read_b128 v[186:189], v145
	ds_read_b128 v[190:193], v145 offset:1024
	ds_read_b128 v[194:197], v145 offset:2048
	ds_read_b128 v[198:201], v145 offset:3072
	ds_read_b128 v[202:205], v145 offset:4096
	ds_read_b128 v[206:209], v145 offset:5120
	ds_read_b128 v[210:213], v145 offset:6144
	ds_read_b128 v[214:217], v145 offset:7168
	global_load_lds_dwordx4 v134, s[62:63]
	s_add_i32 m0, s61, 0xe000
	s_nop 0
	global_load_lds_dwordx4 v136, s[62:63]
	s_waitcnt vmcnt(8)
	s_waitcnt lgkmcnt(0)
	s_barrier
	s_setprio 1
	s_waitcnt lgkmcnt(0)
	v_mfma_f32_16x16x32_bf16 v[124:127], v[138:141], v[186:189], v[124:127]
	v_mfma_f32_16x16x32_bf16 v[120:123], v[150:153], v[186:189], v[120:123]
	v_mfma_f32_16x16x32_bf16 v[108:111], v[138:141], v[194:197], v[108:111]
	v_mfma_f32_16x16x32_bf16 v[104:107], v[150:153], v[194:197], v[104:107]
	v_mfma_f32_16x16x32_bf16 v[92:95], v[138:141], v[202:205], v[92:95]
	v_mfma_f32_16x16x32_bf16 v[88:91], v[150:153], v[202:205], v[88:91]
	v_mfma_f32_16x16x32_bf16 v[76:79], v[138:141], v[210:213], v[76:79]
	v_mfma_f32_16x16x32_bf16 v[72:75], v[150:153], v[210:213], v[72:75]
	v_mfma_f32_16x16x32_bf16 v[124:127], v[146:149], v[190:193], v[124:127]
	v_mfma_f32_16x16x32_bf16 v[120:123], v[154:157], v[190:193], v[120:123]
	v_mfma_f32_16x16x32_bf16 v[108:111], v[146:149], v[198:201], v[108:111]
	v_mfma_f32_16x16x32_bf16 v[104:107], v[154:157], v[198:201], v[104:107]
	v_mfma_f32_16x16x32_bf16 v[92:95], v[146:149], v[206:209], v[92:95]
	v_mfma_f32_16x16x32_bf16 v[88:91], v[154:157], v[206:209], v[88:91]
	v_mfma_f32_16x16x32_bf16 v[76:79], v[146:149], v[214:217], v[76:79]
	v_mfma_f32_16x16x32_bf16 v[72:75], v[154:157], v[214:217], v[72:75]
	s_setprio 0
	s_setprio 1
	v_mfma_f32_16x16x32_bf16 v[116:119], v[170:173], v[186:189], v[116:119]
	v_mfma_f32_16x16x32_bf16 v[112:115], v[178:181], v[186:189], v[112:115]
	v_mfma_f32_16x16x32_bf16 v[100:103], v[170:173], v[194:197], v[100:103]
	v_mfma_f32_16x16x32_bf16 v[96:99], v[178:181], v[194:197], v[96:99]
	v_mfma_f32_16x16x32_bf16 v[84:87], v[170:173], v[202:205], v[84:87]
	v_mfma_f32_16x16x32_bf16 v[80:83], v[178:181], v[202:205], v[80:83]
	v_mfma_f32_16x16x32_bf16 v[68:71], v[170:173], v[210:213], v[68:71]
	v_mfma_f32_16x16x32_bf16 v[64:67], v[178:181], v[210:213], v[64:67]
	v_mfma_f32_16x16x32_bf16 v[116:119], v[174:177], v[190:193], v[116:119]
	v_mfma_f32_16x16x32_bf16 v[112:115], v[182:185], v[190:193], v[112:115]
	v_mfma_f32_16x16x32_bf16 v[100:103], v[174:177], v[198:201], v[100:103]
	v_mfma_f32_16x16x32_bf16 v[96:99], v[182:185], v[198:201], v[96:99]
	v_mfma_f32_16x16x32_bf16 v[84:87], v[174:177], v[206:209], v[84:87]
	v_mfma_f32_16x16x32_bf16 v[80:83], v[182:185], v[206:209], v[80:83]
	v_mfma_f32_16x16x32_bf16 v[68:71], v[174:177], v[214:217], v[68:71]
	v_mfma_f32_16x16x32_bf16 v[64:67], v[182:185], v[214:217], v[64:67]
	s_setprio 0
	s_barrier
	s_add_i32 s46, s46, s44
	s_mov_b32 m0, s46
	ds_read_b128 v[186:189], v145 offset:16384
	ds_read_b128 v[190:193], v145 offset:17408
	ds_read_b128 v[194:197], v145 offset:18432
	ds_read_b128 v[198:201], v145 offset:19456
	ds_read_b128 v[202:205], v145 offset:20480
	ds_read_b128 v[206:209], v145 offset:21504
	ds_read_b128 v[210:213], v145 offset:22528
	ds_read_b128 v[214:217], v145 offset:23552
	global_load_lds_dwordx4 v160, s[24:25]
	s_add_i32 m0, s46, 0x2000
	s_add_u32 vcc_lo, s24, 0x80000
	s_addc_u32 vcc_hi, s25, 0
	s_add_i32 s46, s47, s44
	global_load_lds_dwordx4 v132, s[24:25]
	v_lshl_add_u64 v[218:219], vcc, 0, v[160:161]
	s_mov_b32 m0, s46
	s_nop 0
	global_load_lds_dwordx4 v[218:219], off
	v_lshl_add_u64 v[218:219], vcc, 0, v[132:133]
	s_add_i32 m0, s46, 0x2000
	s_nop 0
	global_load_lds_dwordx4 v[218:219], off
	s_mov_b32 m0, s61
	s_nop 0
	global_load_lds_dwordx4 v128, s[66:67]
	s_mov_b32 m0, s73
	s_nop 0
	global_load_lds_dwordx4 v130, s[66:67]
	s_waitcnt vmcnt(8)
	s_waitcnt lgkmcnt(0)
	s_barrier
; #define PG8_STAGE(bufoff, gbase, voff) do { _Pragma("unroll") for (int _i = 0; _i < 2; ++_i) \
;         __builtin_amdgcn_global_load_lds((const unsigned*)((const char*)(gbase) + (voff)[_i]), (LAS unsigned*)(lds + (bufoff) + ldsw + _i * 8192), 16, 0, 0); } while (0)
; #define PG8_LDA(dst, b, h) do { _Pragma("unroll") for (int m = 0; m < 4; ++m) _Pragma("unroll") for (int k = 0; k < 2; ++k) dst[m][k] = *(const LAS bf16x8*)(lds + PG8_SA(b, h) + aoff + m * 2048 + k * 1024); } while (0)
; #define PG8_LDB(dst, b, h) do { _Pragma("unroll") for (int n = 0; n < 2; ++n) _Pragma("unroll") for (int k = 0; k < 2; ++k) dst[n][k] = *(const LAS bf16x8*)(lds + PG8_SB(b, h) + boff + n * 2048 + k * 1024); } while (0)
; #define PG8_MMA(ai, bj, At, Bt) do { __builtin_amdgcn_s_setprio(1); _Pragma("unroll") for (int m = 0; m < 4; ++m) _Pragma("unroll") for (int n = 0; n < 2; ++n) _Pragma("unroll") for (int k = 0; k < 2; ++k) \
;         acc[ai][bj][m][n] = __builtin_amdgcn_mfma_f32_16x16x32_bf16(Bt[n][k], At[m][k], acc[ai][bj][m][n], 0, 0, 0); __builtin_amdgcn_s_setprio(0); } while (0)
; #define PG8_WAIT_V(n) asm volatile("s_waitcnt vmcnt(" #n ")" ::: "memory")
; #define PG8_WAIT_L(n) asm volatile("s_waitcnt lgkmcnt(" #n ")" ::: "memory")
; #define PG8_BAR __builtin_amdgcn_s_barrier()
; #define PG8_SCHED __builtin_amdgcn_sched_barrier(0)
; template <class Epi, class Sched, bool ALIGN_EPI = true, bool SP2 = true>
; __device__ __forceinline__ void gemm_phase(LAS unsigned char* lds, const Gemm g, const Sched& S, const Epi& E) {
;     ...
;             PG8_WAIT_V(8); PG8_WAIT_L(0); PG8_BAR; PG8_MMA(1, 0, At, B0); PG8_MMA(1, 1, At, B1); PG8_BAR; PG8_SCHED;
;             PG8_LDB(B0, 1, 0); PG8_LDB(B1, 1, 1); PG8_SCHED; PG8_LDA(At, 1, 0); PG8_STAGE(PG8_SA(0, 1), a2 + hstep, voffA);
;             PG8_WAIT_V(8); PG8_WAIT_L(0); PG8_BAR; PG8_MMA(0, 0, At, B0); PG8_MMA(0, 1, At, B1); PG8_BAR; PG8_SCHED;
	s_setprio 1
	s_waitcnt lgkmcnt(0)
	v_mfma_f32_16x16x32_bf16 v[60:63], v[138:141], v[186:189], v[60:63]
	v_mfma_f32_16x16x32_bf16 v[56:59], v[150:153], v[186:189], v[56:59]
	v_mfma_f32_16x16x32_bf16 v[44:47], v[138:141], v[194:197], v[44:47]
	v_mfma_f32_16x16x32_bf16 v[40:43], v[150:153], v[194:197], v[40:43]
	v_mfma_f32_16x16x32_bf16 v[28:31], v[138:141], v[202:205], v[28:31]
	v_mfma_f32_16x16x32_bf16 v[24:27], v[150:153], v[202:205], v[24:27]
	v_mfma_f32_16x16x32_bf16 v[12:15], v[138:141], v[210:213], v[12:15]
	v_mfma_f32_16x16x32_bf16 v[8:11], v[150:153], v[210:213], v[8:11]
	v_mfma_f32_16x16x32_bf16 v[60:63], v[146:149], v[190:193], v[60:63]
	v_mfma_f32_16x16x32_bf16 v[56:59], v[154:157], v[190:193], v[56:59]
	v_mfma_f32_16x16x32_bf16 v[44:47], v[146:149], v[198:201], v[44:47]
	v_mfma_f32_16x16x32_bf16 v[40:43], v[154:157], v[198:201], v[40:43]
	v_mfma_f32_16x16x32_bf16 v[28:31], v[146:149], v[206:209], v[28:31]
	v_mfma_f32_16x16x32_bf16 v[24:27], v[154:157], v[206:209], v[24:27]
	v_mfma_f32_16x16x32_bf16 v[12:15], v[146:149], v[214:217], v[12:15]
	v_mfma_f32_16x16x32_bf16 v[8:11], v[154:157], v[214:217], v[8:11]
	s_setprio 0
	s_setprio 1
	v_mfma_f32_16x16x32_bf16 v[52:55], v[170:173], v[186:189], v[52:55]
	v_mfma_f32_16x16x32_bf16 v[48:51], v[178:181], v[186:189], v[48:51]
	v_mfma_f32_16x16x32_bf16 v[36:39], v[170:173], v[194:197], v[36:39]
	v_mfma_f32_16x16x32_bf16 v[32:35], v[178:181], v[194:197], v[32:35]
	v_mfma_f32_16x16x32_bf16 v[20:23], v[170:173], v[202:205], v[20:23]
	v_mfma_f32_16x16x32_bf16 v[16:19], v[178:181], v[202:205], v[16:19]
	v_mfma_f32_16x16x32_bf16 v[4:7], v[170:173], v[210:213], v[4:7]
	v_mfma_f32_16x16x32_bf16 v[0:3], v[178:181], v[210:213], v[0:3]
	v_mfma_f32_16x16x32_bf16 v[52:55], v[174:177], v[190:193], v[52:55]
	v_mfma_f32_16x16x32_bf16 v[48:51], v[182:185], v[190:193], v[48:51]
	v_mfma_f32_16x16x32_bf16 v[36:39], v[174:177], v[198:201], v[36:39]
	v_mfma_f32_16x16x32_bf16 v[32:35], v[182:185], v[198:201], v[32:35]
	v_mfma_f32_16x16x32_bf16 v[20:23], v[174:177], v[206:209], v[20:23]
	v_mfma_f32_16x16x32_bf16 v[16:19], v[182:185], v[206:209], v[16:19]
	v_mfma_f32_16x16x32_bf16 v[4:7], v[174:177], v[214:217], v[4:7]
	v_mfma_f32_16x16x32_bf16 v[0:3], v[182:185], v[214:217], v[0:3]
	s_setprio 0
	s_barrier
	s_add_i32 s46, 0, 0x18000
	s_add_i32 s47, 0, 0x1c000
	v_add_u32_e32 v154, s46, v143
	v_add_u32_e32 v182, s47, v143
	ds_read_b128 v[138:141], v154
	ds_read_b128 v[146:149], v154 offset:1024
	ds_read_b128 v[150:153], v154 offset:2048
	ds_read_b128 v[154:157], v154 offset:3072
	ds_read_b128 v[170:173], v182
	ds_read_b128 v[174:177], v182 offset:1024
	ds_read_b128 v[178:181], v182 offset:2048
	ds_read_b128 v[182:185], v182 offset:3072
	s_add_u32 s66, s66, 0x80000
	s_addc_u32 s67, s67, 0
	s_mov_b32 m0, s79
	ds_read_b128 v[186:189], v145 offset:32768
	ds_read_b128 v[190:193], v145 offset:33792
	ds_read_b128 v[194:197], v145 offset:34816
	ds_read_b128 v[198:201], v145 offset:35840
	ds_read_b128 v[202:205], v145 offset:36864
	ds_read_b128 v[206:209], v145 offset:37888
	ds_read_b128 v[210:213], v145 offset:38912
	ds_read_b128 v[214:217], v145 offset:39936
	global_load_lds_dwordx4 v128, s[66:67]
	s_mov_b32 m0, s82
	s_nop 0
	global_load_lds_dwordx4 v130, s[66:67]
	s_waitcnt vmcnt(8)
	s_waitcnt lgkmcnt(0)
	s_barrier
	s_setprio 1
	s_waitcnt lgkmcnt(0)
	v_mfma_f32_16x16x32_bf16 v[124:127], v[138:141], v[186:189], v[124:127]
	v_mfma_f32_16x16x32_bf16 v[120:123], v[150:153], v[186:189], v[120:123]
	v_mfma_f32_16x16x32_bf16 v[108:111], v[138:141], v[194:197], v[108:111]
	v_mfma_f32_16x16x32_bf16 v[104:107], v[150:153], v[194:197], v[104:107]
	v_mfma_f32_16x16x32_bf16 v[92:95], v[138:141], v[202:205], v[92:95]
	v_mfma_f32_16x16x32_bf16 v[88:91], v[150:153], v[202:205], v[88:91]
	v_mfma_f32_16x16x32_bf16 v[76:79], v[138:141], v[210:213], v[76:79]
	v_mfma_f32_16x16x32_bf16 v[72:75], v[150:153], v[210:213], v[72:75]
	v_mfma_f32_16x16x32_bf16 v[124:127], v[146:149], v[190:193], v[124:127]
	v_mfma_f32_16x16x32_bf16 v[120:123], v[154:157], v[190:193], v[120:123]
	v_mfma_f32_16x16x32_bf16 v[108:111], v[146:149], v[198:201], v[108:111]
	v_mfma_f32_16x16x32_bf16 v[104:107], v[154:157], v[198:201], v[104:107]
	v_mfma_f32_16x16x32_bf16 v[92:95], v[146:149], v[206:209], v[92:95]
	v_mfma_f32_16x16x32_bf16 v[88:91], v[154:157], v[206:209], v[88:91]
	v_mfma_f32_16x16x32_bf16 v[76:79], v[146:149], v[214:217], v[76:79]
	v_mfma_f32_16x16x32_bf16 v[72:75], v[154:157], v[214:217], v[72:75]
	s_setprio 0
	s_setprio 1
	v_mfma_f32_16x16x32_bf16 v[116:119], v[170:173], v[186:189], v[116:119]
	v_mfma_f32_16x16x32_bf16 v[112:115], v[178:181], v[186:189], v[112:115]
	v_mfma_f32_16x16x32_bf16 v[100:103], v[170:173], v[194:197], v[100:103]
	v_mfma_f32_16x16x32_bf16 v[96:99], v[178:181], v[194:197], v[96:99]
	v_mfma_f32_16x16x32_bf16 v[84:87], v[170:173], v[202:205], v[84:87]
	v_mfma_f32_16x16x32_bf16 v[80:83], v[178:181], v[202:205], v[80:83]
	v_mfma_f32_16x16x32_bf16 v[68:71], v[170:173], v[210:213], v[68:71]
	v_mfma_f32_16x16x32_bf16 v[64:67], v[178:181], v[210:213], v[64:67]
	v_mfma_f32_16x16x32_bf16 v[116:119], v[174:177], v[190:193], v[116:119]
	v_mfma_f32_16x16x32_bf16 v[112:115], v[182:185], v[190:193], v[112:115]
	v_mfma_f32_16x16x32_bf16 v[100:103], v[174:177], v[198:201], v[100:103]
	v_mfma_f32_16x16x32_bf16 v[96:99], v[182:185], v[198:201], v[96:99]
	v_mfma_f32_16x16x32_bf16 v[84:87], v[174:177], v[206:209], v[84:87]
	v_mfma_f32_16x16x32_bf16 v[80:83], v[182:185], v[206:209], v[80:83]
	v_mfma_f32_16x16x32_bf16 v[68:71], v[174:177], v[214:217], v[68:71]
	v_mfma_f32_16x16x32_bf16 v[64:67], v[182:185], v[214:217], v[64:67]
	s_setprio 0
	s_barrier
; #define PG8_STAGE(bufoff, gbase, voff) do { _Pragma("unroll") for (int _i = 0; _i < 2; ++_i) \
;         __builtin_amdgcn_global_load_lds((const unsigned*)((const char*)(gbase) + (voff)[_i]), (LAS unsigned*)(lds + (bufoff) + ldsw + _i * 8192), 16, 0, 0); } while (0)
; #define PG8_LDA(dst, b, h) do { _Pragma("unroll") for (int m = 0; m < 4; ++m) _Pragma("unroll") for (int k = 0; k < 2; ++k) dst[m][k] = *(const LAS bf16x8*)(lds + PG8_SA(b, h) + aoff + m * 2048 + k * 1024); } while (0)
; #define PG8_MMA(ai, bj, At, Bt) do { __builtin_amdgcn_s_setprio(1); _Pragma("unroll") for (int m = 0; m < 4; ++m) _Pragma("unroll") for (int n = 0; n < 2; ++n) _Pragma("unroll") for (int k = 0; k < 2; ++k) \
;         acc[ai][bj][m][n] = __builtin_amdgcn_mfma_f32_16x16x32_bf16(Bt[n][k], At[m][k], acc[ai][bj][m][n], 0, 0, 0); __builtin_amdgcn_s_setprio(0); } while (0)
; #define PG8_WAIT_V(n) asm volatile("s_waitcnt vmcnt(" #n ")" ::: "memory")
; #define PG8_WAIT_L(n) asm volatile("s_waitcnt lgkmcnt(" #n ")" ::: "memory")
; #define PG8_BAR __builtin_amdgcn_s_barrier()
; #define PG8_SCHED __builtin_amdgcn_sched_barrier(0)
; template <class Epi, class Sched, bool ALIGN_EPI = true, bool SP2 = true>
; __device__ __forceinline__ void gemm_phase(LAS unsigned char* lds, const Gemm g, const Sched& S, const Epi& E) {
;     ...
;         for (int t = 0; t < nt; t += 2) {
;     ...
;             PG8_LDA(At, 1, 1); PG8_STAGE(PG8_SB(1, 0), b3, voffB); PG8_STAGE(PG8_SB(1, 1), b3 + hstep, voffB); PG8_STAGE(PG8_SA(1, 0), a3, voffA);
;             PG8_WAIT_V(8); PG8_WAIT_L(0); PG8_BAR; PG8_MMA(1, 0, At, B0); PG8_MMA(1, 1, At, B1); PG8_BAR; PG8_SCHED;
	s_add_i32 s46, s46, s44
	s_mov_b32 m0, s46
	ds_read_b128 v[186:189], v145 offset:49152
	ds_read_b128 v[190:193], v145 offset:50176
	ds_read_b128 v[194:197], v145 offset:51200
	ds_read_b128 v[198:201], v145 offset:52224
	ds_read_b128 v[202:205], v145 offset:53248
	ds_read_b128 v[206:209], v145 offset:54272
	ds_read_b128 v[210:213], v145 offset:55296
	ds_read_b128 v[214:217], v145 offset:56320
	s_add_u32 s98, s24, 0x80
	s_addc_u32 s99, s25, 0
	global_load_lds_dwordx4 v160, s[98:99]
	s_add_i32 m0, s46, 0x2000
	s_add_u32 s24, s24, 0x80080
	s_addc_u32 s25, s25, 0
	s_add_i32 s46, s47, s44
	global_load_lds_dwordx4 v132, s[98:99]
	s_mov_b32 m0, s46
	s_nop 0
	global_load_lds_dwordx4 v160, s[24:25]
	s_add_i32 m0, s46, 0x2000
	s_nop 0
	global_load_lds_dwordx4 v132, s[24:25]
	s_mov_b32 m0, s83
	s_nop 0
	s_add_u32 s98, s66, 0xfff80080
	s_addc_u32 s99, s67, -1
	global_load_lds_dwordx4 v128, s[98:99]
	s_mov_b32 m0, s90
	s_nop 0
	global_load_lds_dwordx4 v130, s[98:99]
	s_waitcnt vmcnt(8)
	s_waitcnt lgkmcnt(0)
	s_barrier
	s_setprio 1
	s_waitcnt lgkmcnt(0)
	v_mfma_f32_16x16x32_bf16 v[60:63], v[138:141], v[186:189], v[60:63]
	v_mfma_f32_16x16x32_bf16 v[56:59], v[150:153], v[186:189], v[56:59]
	v_mfma_f32_16x16x32_bf16 v[44:47], v[138:141], v[194:197], v[44:47]
	v_mfma_f32_16x16x32_bf16 v[40:43], v[150:153], v[194:197], v[40:43]
	v_mfma_f32_16x16x32_bf16 v[28:31], v[138:141], v[202:205], v[28:31]
	v_mfma_f32_16x16x32_bf16 v[24:27], v[150:153], v[202:205], v[24:27]
	v_mfma_f32_16x16x32_bf16 v[12:15], v[138:141], v[210:213], v[12:15]
	v_mfma_f32_16x16x32_bf16 v[8:11], v[150:153], v[210:213], v[8:11]
	v_mfma_f32_16x16x32_bf16 v[60:63], v[146:149], v[190:193], v[60:63]
	v_mfma_f32_16x16x32_bf16 v[56:59], v[154:157], v[190:193], v[56:59]
	v_mfma_f32_16x16x32_bf16 v[44:47], v[146:149], v[198:201], v[44:47]
	v_mfma_f32_16x16x32_bf16 v[40:43], v[154:157], v[198:201], v[40:43]
	v_mfma_f32_16x16x32_bf16 v[28:31], v[146:149], v[206:209], v[28:31]
	v_mfma_f32_16x16x32_bf16 v[24:27], v[154:157], v[206:209], v[24:27]
	v_mfma_f32_16x16x32_bf16 v[12:15], v[146:149], v[214:217], v[12:15]
	v_mfma_f32_16x16x32_bf16 v[8:11], v[154:157], v[214:217], v[8:11]
	s_setprio 0
	s_setprio 1
	v_mfma_f32_16x16x32_bf16 v[52:55], v[170:173], v[186:189], v[52:55]
	v_mfma_f32_16x16x32_bf16 v[48:51], v[178:181], v[186:189], v[48:51]
	v_mfma_f32_16x16x32_bf16 v[36:39], v[170:173], v[194:197], v[36:39]
	v_mfma_f32_16x16x32_bf16 v[32:35], v[178:181], v[194:197], v[32:35]
	v_mfma_f32_16x16x32_bf16 v[20:23], v[170:173], v[202:205], v[20:23]
	v_mfma_f32_16x16x32_bf16 v[16:19], v[178:181], v[202:205], v[16:19]
	v_mfma_f32_16x16x32_bf16 v[4:7], v[170:173], v[210:213], v[4:7]
	v_mfma_f32_16x16x32_bf16 v[0:3], v[178:181], v[210:213], v[0:3]
	v_mfma_f32_16x16x32_bf16 v[52:55], v[174:177], v[190:193], v[52:55]
	v_mfma_f32_16x16x32_bf16 v[48:51], v[182:185], v[190:193], v[48:51]
	v_mfma_f32_16x16x32_bf16 v[36:39], v[174:177], v[198:201], v[36:39]
	v_mfma_f32_16x16x32_bf16 v[32:35], v[182:185], v[198:201], v[32:35]
	v_mfma_f32_16x16x32_bf16 v[20:23], v[174:177], v[206:209], v[20:23]
	v_mfma_f32_16x16x32_bf16 v[16:19], v[182:185], v[206:209], v[16:19]
	v_mfma_f32_16x16x32_bf16 v[4:7], v[174:177], v[214:217], v[4:7]
	v_mfma_f32_16x16x32_bf16 v[0:3], v[182:185], v[214:217], v[0:3]
	s_setprio 0
	s_barrier
	s_add_i32 s96, s96, 2
	s_add_u32 s62, s62, 0x100
	s_addc_u32 s63, s63, 0
	s_add_u32 s94, s94, 0x100
	s_addc_u32 s95, s95, 0
	s_cmp_gt_u32 s96, 29
	s_cbranch_scc0 .LBB0_117
	s_and_b64 vcc, exec, s[10:11]
	s_mov_b64 s[96:97], 0x80000
	s_cbranch_vccz .LBB0_120
	s_barrier

; #define PG8_STAGE(bufoff, gbase, voff) do { _Pragma("unroll") for (int _i = 0; _i < 2; ++_i) \
;         __builtin_amdgcn_global_load_lds((const unsigned*)((const char*)(gbase) + (voff)[_i]), (LAS unsigned*)(lds + (bufoff) + ldsw + _i * 8192), 16, 0, 0); } while (0)
; #define PG8_LDA(dst, b, h) do { _Pragma("unroll") for (int m = 0; m < 4; ++m) _Pragma("unroll") for (int k = 0; k < 2; ++k) dst[m][k] = *(const LAS bf16x8*)(lds + PG8_SA(b, h) + aoff + m * 2048 + k * 1024); } while (0)
; #define PG8_LDB(dst, b, h) do { _Pragma("unroll") for (int n = 0; n < 2; ++n) _Pragma("unroll") for (int k = 0; k < 2; ++k) dst[n][k] = *(const LAS bf16x8*)(lds + PG8_SB(b, h) + boff + n * 2048 + k * 1024); } while (0)
; #define PG8_MMA(ai, bj, At, Bt) do { __builtin_amdgcn_s_setprio(1); _Pragma("unroll") for (int m = 0; m < 4; ++m) _Pragma("unroll") for (int n = 0; n < 2; ++n) _Pragma("unroll") for (int k = 0; k < 2; ++k) \
;         acc[ai][bj][m][n] = __builtin_amdgcn_mfma_f32_16x16x32_bf16(Bt[n][k], At[m][k], acc[ai][bj][m][n], 0, 0, 0); __builtin_amdgcn_s_setprio(0); } while (0)
; #define PG8_WAIT_V(n) asm volatile("s_waitcnt vmcnt(" #n ")" ::: "memory")
; #define PG8_WAIT_L(n) asm volatile("s_waitcnt lgkmcnt(" #n ")" ::: "memory")
; #define PG8_BAR __builtin_amdgcn_s_barrier()
; #define PG8_SCHED __builtin_amdgcn_sched_barrier(0)
; template <class Epi, class Sched, bool ALIGN_EPI = true, bool SP2 = true>
; __device__ __forceinline__ void gemm_phase(LAS unsigned char* lds, const Gemm g, const Sched& S, const Epi& E) {
;     ...
;             const bool last = (t == nt - 2);
;             const char* a1 = cA + (size_t)(t + 1) * kstep;
;             const char* a2 = last ? nA : cA + (size_t)(t + 2) * kstep; const char* b2 = last ? nB : cB + (size_t)(t + 2) * kstep;
;             const char* a3 = a2 + kstep; const char* b3 = b2 + kstep;
;             if constexpr (SP2) {
;             PG8_LDB(B0, 0, 0); PG8_LDB(B1, 0, 1); PG8_SCHED; PG8_LDA(At, 0, 0); PG8_STAGE(PG8_SA(1, 1), a1 + hstep, voffA);
;             PG8_WAIT_V(8); PG8_WAIT_L(0); PG8_BAR; PG8_MMA(0, 0, At, B0); PG8_MMA(0, 1, At, B1); PG8_BAR; PG8_SCHED;
;             PG8_LDA(At, 0, 1); PG8_STAGE(PG8_SB(0, 0), b2, voffB); PG8_STAGE(PG8_SB(0, 1), b2 + hstep, voffB); PG8_STAGE(PG8_SA(0, 0), a2, voffA);
;             PG8_WAIT_V(8); PG8_WAIT_L(0); PG8_BAR; PG8_MMA(1, 0, At, B0); PG8_MMA(1, 1, At, B1); PG8_BAR; PG8_SCHED;
.LBB0_145:
	s_add_u32 s24, s72, 0xfff80080
	s_addc_u32 s25, s73, -1
	s_add_i32 s46, 0, 0x10000
	s_cmp_eq_u32 s95, 28
	s_cselect_b32 s83, s2, s25
	s_cselect_b32 s82, s3, s24
	v_add_u32_e32 v142, s46, v145
	s_cselect_b32 s25, s31, s53
	s_cselect_b32 s24, s44, s45
	s_add_i32 s47, 0, 0x14000
	ds_read_b128 v[138:141], v142
	ds_read_b128 v[148:151], v142 offset:1024
	ds_read_b128 v[152:155], v142 offset:2048
	ds_read_b128 v[156:159], v142 offset:3072
	v_add_u32_e32 v142, s47, v145
	ds_read_b128 v[170:173], v142
	ds_read_b128 v[174:177], v142 offset:1024
	ds_read_b128 v[178:181], v142 offset:2048
	ds_read_b128 v[182:185], v142 offset:3072
	s_add_i32 m0, s63, 0xc000
	ds_read_b128 v[186:189], v147
	ds_read_b128 v[190:193], v147 offset:1024
	ds_read_b128 v[194:197], v147 offset:2048
	ds_read_b128 v[198:201], v147 offset:3072
	ds_read_b128 v[202:205], v147 offset:4096
	ds_read_b128 v[206:209], v147 offset:5120
	ds_read_b128 v[210:213], v147 offset:6144
	ds_read_b128 v[214:217], v147 offset:7168
	global_load_lds_dwordx4 v134, s[72:73]
	s_add_i32 m0, s63, 0xe000
	s_nop 0
	global_load_lds_dwordx4 v136, s[72:73]
	s_waitcnt vmcnt(8)
	s_waitcnt lgkmcnt(0)
	s_barrier
	s_setprio 1
	s_waitcnt lgkmcnt(0)
	v_mfma_f32_16x16x32_bf16 v[124:127], v[138:141], v[186:189], v[124:127]
	v_mfma_f32_16x16x32_bf16 v[120:123], v[152:155], v[186:189], v[120:123]
	v_mfma_f32_16x16x32_bf16 v[108:111], v[138:141], v[194:197], v[108:111]
	v_mfma_f32_16x16x32_bf16 v[104:107], v[152:155], v[194:197], v[104:107]
	v_mfma_f32_16x16x32_bf16 v[92:95], v[138:141], v[202:205], v[92:95]
	v_mfma_f32_16x16x32_bf16 v[88:91], v[152:155], v[202:205], v[88:91]
	v_mfma_f32_16x16x32_bf16 v[76:79], v[138:141], v[210:213], v[76:79]
	v_mfma_f32_16x16x32_bf16 v[72:75], v[152:155], v[210:213], v[72:75]
	v_mfma_f32_16x16x32_bf16 v[124:127], v[148:151], v[190:193], v[124:127]
	v_mfma_f32_16x16x32_bf16 v[120:123], v[156:159], v[190:193], v[120:123]
	v_mfma_f32_16x16x32_bf16 v[108:111], v[148:151], v[198:201], v[108:111]
	v_mfma_f32_16x16x32_bf16 v[104:107], v[156:159], v[198:201], v[104:107]
	v_mfma_f32_16x16x32_bf16 v[92:95], v[148:151], v[206:209], v[92:95]
	v_mfma_f32_16x16x32_bf16 v[88:91], v[156:159], v[206:209], v[88:91]
	v_mfma_f32_16x16x32_bf16 v[76:79], v[148:151], v[214:217], v[76:79]
	v_mfma_f32_16x16x32_bf16 v[72:75], v[156:159], v[214:217], v[72:75]
	s_setprio 0
	s_setprio 1
	v_mfma_f32_16x16x32_bf16 v[116:119], v[170:173], v[186:189], v[116:119]
	v_mfma_f32_16x16x32_bf16 v[112:115], v[178:181], v[186:189], v[112:115]
	v_mfma_f32_16x16x32_bf16 v[100:103], v[170:173], v[194:197], v[100:103]
	v_mfma_f32_16x16x32_bf16 v[96:99], v[178:181], v[194:197], v[96:99]
	v_mfma_f32_16x16x32_bf16 v[84:87], v[170:173], v[202:205], v[84:87]
	v_mfma_f32_16x16x32_bf16 v[80:83], v[178:181], v[202:205], v[80:83]
	v_mfma_f32_16x16x32_bf16 v[68:71], v[170:173], v[210:213], v[68:71]
	v_mfma_f32_16x16x32_bf16 v[64:67], v[178:181], v[210:213], v[64:67]
	v_mfma_f32_16x16x32_bf16 v[116:119], v[174:177], v[190:193], v[116:119]
	v_mfma_f32_16x16x32_bf16 v[112:115], v[182:185], v[190:193], v[112:115]
	v_mfma_f32_16x16x32_bf16 v[100:103], v[174:177], v[198:201], v[100:103]
	v_mfma_f32_16x16x32_bf16 v[96:99], v[182:185], v[198:201], v[96:99]
	v_mfma_f32_16x16x32_bf16 v[84:87], v[174:177], v[206:209], v[84:87]
	v_mfma_f32_16x16x32_bf16 v[80:83], v[182:185], v[206:209], v[80:83]
	v_mfma_f32_16x16x32_bf16 v[68:71], v[174:177], v[214:217], v[68:71]
	v_mfma_f32_16x16x32_bf16 v[64:67], v[182:185], v[214:217], v[64:67]
	s_setprio 0
	s_barrier
	s_add_i32 s46, s46, s79
	s_mov_b32 m0, s46
	ds_read_b128 v[186:189], v147 offset:16384
	ds_read_b128 v[190:193], v147 offset:17408
	ds_read_b128 v[194:197], v147 offset:18432
	ds_read_b128 v[198:201], v147 offset:19456
	ds_read_b128 v[202:205], v147 offset:20480
	ds_read_b128 v[206:209], v147 offset:21504
	ds_read_b128 v[210:213], v147 offset:22528
	ds_read_b128 v[214:217], v147 offset:23552
	global_load_lds_dwordx4 v160, s[24:25]
	s_add_i32 m0, s46, 0x2000
	s_add_u32 s96, s24, 0x80000
	s_addc_u32 s97, s25, 0
	s_add_i32 s46, s47, s79
	global_load_lds_dwordx4 v132, s[24:25]
	s_mov_b32 m0, s46
	s_nop 0
	global_load_lds_dwordx4 v160, s[96:97]
	s_add_i32 m0, s46, 0x2000
	s_nop 0
	global_load_lds_dwordx4 v132, s[96:97]
	s_mov_b32 m0, s63
	s_nop 0
	global_load_lds_dwordx4 v128, s[82:83]
	s_mov_b32 m0, s67
	s_nop 0
	global_load_lds_dwordx4 v130, s[82:83]
	s_waitcnt vmcnt(8)
	s_waitcnt lgkmcnt(0)
	s_barrier
	s_setprio 1
	s_waitcnt lgkmcnt(0)
	v_mfma_f32_16x16x32_bf16 v[60:63], v[138:141], v[186:189], v[60:63]
	v_mfma_f32_16x16x32_bf16 v[56:59], v[152:155], v[186:189], v[56:59]
	v_mfma_f32_16x16x32_bf16 v[44:47], v[138:141], v[194:197], v[44:47]
	v_mfma_f32_16x16x32_bf16 v[40:43], v[152:155], v[194:197], v[40:43]
	v_mfma_f32_16x16x32_bf16 v[28:31], v[138:141], v[202:205], v[28:31]
	v_mfma_f32_16x16x32_bf16 v[24:27], v[152:155], v[202:205], v[24:27]
	v_mfma_f32_16x16x32_bf16 v[12:15], v[138:141], v[210:213], v[12:15]
	v_mfma_f32_16x16x32_bf16 v[8:11], v[152:155], v[210:213], v[8:11]
	v_mfma_f32_16x16x32_bf16 v[60:63], v[148:151], v[190:193], v[60:63]
	v_mfma_f32_16x16x32_bf16 v[56:59], v[156:159], v[190:193], v[56:59]
	v_mfma_f32_16x16x32_bf16 v[44:47], v[148:151], v[198:201], v[44:47]
	v_mfma_f32_16x16x32_bf16 v[40:43], v[156:159], v[198:201], v[40:43]
	v_mfma_f32_16x16x32_bf16 v[28:31], v[148:151], v[206:209], v[28:31]
	v_mfma_f32_16x16x32_bf16 v[24:27], v[156:159], v[206:209], v[24:27]
	v_mfma_f32_16x16x32_bf16 v[12:15], v[148:151], v[214:217], v[12:15]
	v_mfma_f32_16x16x32_bf16 v[8:11], v[156:159], v[214:217], v[8:11]
	s_setprio 0
	s_setprio 1
	v_mfma_f32_16x16x32_bf16 v[52:55], v[170:173], v[186:189], v[52:55]
	v_mfma_f32_16x16x32_bf16 v[48:51], v[178:181], v[186:189], v[48:51]
	v_mfma_f32_16x16x32_bf16 v[36:39], v[170:173], v[194:197], v[36:39]
	v_mfma_f32_16x16x32_bf16 v[32:35], v[178:181], v[194:197], v[32:35]
	v_mfma_f32_16x16x32_bf16 v[20:23], v[170:173], v[202:205], v[20:23]
	v_mfma_f32_16x16x32_bf16 v[16:19], v[178:181], v[202:205], v[16:19]
	v_mfma_f32_16x16x32_bf16 v[4:7], v[170:173], v[210:213], v[4:7]
	v_mfma_f32_16x16x32_bf16 v[0:3], v[178:181], v[210:213], v[0:3]
	v_mfma_f32_16x16x32_bf16 v[52:55], v[174:177], v[190:193], v[52:55]
	v_mfma_f32_16x16x32_bf16 v[48:51], v[182:185], v[190:193], v[48:51]
	v_mfma_f32_16x16x32_bf16 v[36:39], v[174:177], v[198:201], v[36:39]
	v_mfma_f32_16x16x32_bf16 v[32:35], v[182:185], v[198:201], v[32:35]
	v_mfma_f32_16x16x32_bf16 v[20:23], v[174:177], v[206:209], v[20:23]
	v_mfma_f32_16x16x32_bf16 v[16:19], v[182:185], v[206:209], v[16:19]
	v_mfma_f32_16x16x32_bf16 v[4:7], v[174:177], v[214:217], v[4:7]
	v_mfma_f32_16x16x32_bf16 v[0:3], v[182:185], v[214:217], v[0:3]
	s_setprio 0
	s_barrier
; #define PG8_STAGE(bufoff, gbase, voff) do { _Pragma("unroll") for (int _i = 0; _i < 2; ++_i) \
;         __builtin_amdgcn_global_load_lds((const unsigned*)((const char*)(gbase) + (voff)[_i]), (LAS unsigned*)(lds + (bufoff) + ldsw + _i * 8192), 16, 0, 0); } while (0)
; #define PG8_LDA(dst, b, h) do { _Pragma("unroll") for (int m = 0; m < 4; ++m) _Pragma("unroll") for (int k = 0; k < 2; ++k) dst[m][k] = *(const LAS bf16x8*)(lds + PG8_SA(b, h) + aoff + m * 2048 + k * 1024); } while (0)
; #define PG8_LDB(dst, b, h) do { _Pragma("unroll") for (int n = 0; n < 2; ++n) _Pragma("unroll") for (int k = 0; k < 2; ++k) dst[n][k] = *(const LAS bf16x8*)(lds + PG8_SB(b, h) + boff + n * 2048 + k * 1024); } while (0)
; #define PG8_MMA(ai, bj, At, Bt) do { __builtin_amdgcn_s_setprio(1); _Pragma("unroll") for (int m = 0; m < 4; ++m) _Pragma("unroll") for (int n = 0; n < 2; ++n) _Pragma("unroll") for (int k = 0; k < 2; ++k) \
;         acc[ai][bj][m][n] = __builtin_amdgcn_mfma_f32_16x16x32_bf16(Bt[n][k], At[m][k], acc[ai][bj][m][n], 0, 0, 0); __builtin_amdgcn_s_setprio(0); } while (0)
; #define PG8_WAIT_V(n) asm volatile("s_waitcnt vmcnt(" #n ")" ::: "memory")
; #define PG8_WAIT_L(n) asm volatile("s_waitcnt lgkmcnt(" #n ")" ::: "memory")
; #define PG8_BAR __builtin_amdgcn_s_barrier()
; #define PG8_SCHED __builtin_amdgcn_sched_barrier(0)
; template <class Epi, class Sched, bool ALIGN_EPI = true, bool SP2 = true>
; __device__ __forceinline__ void gemm_phase(LAS unsigned char* lds, const Gemm g, const Sched& S, const Epi& E) {
;     ...
;         for (int t = 0; t < nt; t += 2) {
;     ...
;             PG8_LDB(B0, 1, 0); PG8_LDB(B1, 1, 1); PG8_SCHED; PG8_LDA(At, 1, 0); PG8_STAGE(PG8_SA(0, 1), a2 + hstep, voffA);
;             PG8_WAIT_V(8); PG8_WAIT_L(0); PG8_BAR; PG8_MMA(0, 0, At, B0); PG8_MMA(0, 1, At, B1); PG8_BAR; PG8_SCHED;
;             PG8_LDA(At, 1, 1); PG8_STAGE(PG8_SB(1, 0), b3, voffB); PG8_STAGE(PG8_SB(1, 1), b3 + hstep, voffB); PG8_STAGE(PG8_SA(1, 0), a3, voffA);
;             PG8_WAIT_V(8); PG8_WAIT_L(0); PG8_BAR; PG8_MMA(1, 0, At, B0); PG8_MMA(1, 1, At, B1); PG8_BAR; PG8_SCHED;
	s_add_i32 s46, 0, 0x18000
	s_add_i32 s47, 0, 0x1c000
	v_add_u32_e32 v156, s46, v145
	v_add_u32_e32 v182, s47, v145
	ds_read_b128 v[138:141], v156
	ds_read_b128 v[148:151], v156 offset:1024
	ds_read_b128 v[152:155], v156 offset:2048
	ds_read_b128 v[156:159], v156 offset:3072
	ds_read_b128 v[170:173], v182
	ds_read_b128 v[174:177], v182 offset:1024
	ds_read_b128 v[178:181], v182 offset:2048
	ds_read_b128 v[182:185], v182 offset:3072
	s_add_u32 s82, s82, 0x80000
	s_addc_u32 s83, s83, 0
	s_mov_b32 m0, s90
	ds_read_b128 v[186:189], v147 offset:32768
	ds_read_b128 v[190:193], v147 offset:33792
	ds_read_b128 v[194:197], v147 offset:34816
	ds_read_b128 v[198:201], v147 offset:35840
	ds_read_b128 v[202:205], v147 offset:36864
	ds_read_b128 v[206:209], v147 offset:37888
	ds_read_b128 v[210:213], v147 offset:38912
	ds_read_b128 v[214:217], v147 offset:39936
	global_load_lds_dwordx4 v128, s[82:83]
	s_mov_b32 m0, s91
	s_nop 0
	global_load_lds_dwordx4 v130, s[82:83]
	s_waitcnt vmcnt(8)
	s_waitcnt lgkmcnt(0)
	s_barrier
	s_setprio 1
	s_waitcnt lgkmcnt(0)
	v_mfma_f32_16x16x32_bf16 v[124:127], v[138:141], v[186:189], v[124:127]
	v_mfma_f32_16x16x32_bf16 v[120:123], v[152:155], v[186:189], v[120:123]
	v_mfma_f32_16x16x32_bf16 v[108:111], v[138:141], v[194:197], v[108:111]
	v_mfma_f32_16x16x32_bf16 v[104:107], v[152:155], v[194:197], v[104:107]
	v_mfma_f32_16x16x32_bf16 v[92:95], v[138:141], v[202:205], v[92:95]
	v_mfma_f32_16x16x32_bf16 v[88:91], v[152:155], v[202:205], v[88:91]
	v_mfma_f32_16x16x32_bf16 v[76:79], v[138:141], v[210:213], v[76:79]
	v_mfma_f32_16x16x32_bf16 v[72:75], v[152:155], v[210:213], v[72:75]
	v_mfma_f32_16x16x32_bf16 v[124:127], v[148:151], v[190:193], v[124:127]
	v_mfma_f32_16x16x32_bf16 v[120:123], v[156:159], v[190:193], v[120:123]
	v_mfma_f32_16x16x32_bf16 v[108:111], v[148:151], v[198:201], v[108:111]
	v_mfma_f32_16x16x32_bf16 v[104:107], v[156:159], v[198:201], v[104:107]
	v_mfma_f32_16x16x32_bf16 v[92:95], v[148:151], v[206:209], v[92:95]
	v_mfma_f32_16x16x32_bf16 v[88:91], v[156:159], v[206:209], v[88:91]
	v_mfma_f32_16x16x32_bf16 v[76:79], v[148:151], v[214:217], v[76:79]
	v_mfma_f32_16x16x32_bf16 v[72:75], v[156:159], v[214:217], v[72:75]
	s_setprio 0
	s_setprio 1
	v_mfma_f32_16x16x32_bf16 v[116:119], v[170:173], v[186:189], v[116:119]
	v_mfma_f32_16x16x32_bf16 v[112:115], v[178:181], v[186:189], v[112:115]
	v_mfma_f32_16x16x32_bf16 v[100:103], v[170:173], v[194:197], v[100:103]
	v_mfma_f32_16x16x32_bf16 v[96:99], v[178:181], v[194:197], v[96:99]
	v_mfma_f32_16x16x32_bf16 v[84:87], v[170:173], v[202:205], v[84:87]
	v_mfma_f32_16x16x32_bf16 v[80:83], v[178:181], v[202:205], v[80:83]
	v_mfma_f32_16x16x32_bf16 v[68:71], v[170:173], v[210:213], v[68:71]
	v_mfma_f32_16x16x32_bf16 v[64:67], v[178:181], v[210:213], v[64:67]
	v_mfma_f32_16x16x32_bf16 v[116:119], v[174:177], v[190:193], v[116:119]
	v_mfma_f32_16x16x32_bf16 v[112:115], v[182:185], v[190:193], v[112:115]
	v_mfma_f32_16x16x32_bf16 v[100:103], v[174:177], v[198:201], v[100:103]
	v_mfma_f32_16x16x32_bf16 v[96:99], v[182:185], v[198:201], v[96:99]
	v_mfma_f32_16x16x32_bf16 v[84:87], v[174:177], v[206:209], v[84:87]
	v_mfma_f32_16x16x32_bf16 v[80:83], v[182:185], v[206:209], v[80:83]
	v_mfma_f32_16x16x32_bf16 v[68:71], v[174:177], v[214:217], v[68:71]
	v_mfma_f32_16x16x32_bf16 v[64:67], v[182:185], v[214:217], v[64:67]
	s_setprio 0
	s_barrier
	s_add_i32 s46, s46, s79
	s_mov_b32 m0, s46
	ds_read_b128 v[186:189], v147 offset:49152
	ds_read_b128 v[190:193], v147 offset:50176
	ds_read_b128 v[194:197], v147 offset:51200
	ds_read_b128 v[198:201], v147 offset:52224
	ds_read_b128 v[202:205], v147 offset:53248
	ds_read_b128 v[206:209], v147 offset:54272
	ds_read_b128 v[210:213], v147 offset:55296
	ds_read_b128 v[214:217], v147 offset:56320
	s_add_u32 s98, s24, 0x80
	s_addc_u32 s99, s25, 0
	global_load_lds_dwordx4 v160, s[98:99]
	s_add_i32 m0, s46, 0x2000
	s_add_u32 s24, s24, 0x80080
	s_addc_u32 s25, s25, 0
	s_add_i32 s46, s47, s79
	global_load_lds_dwordx4 v132, s[98:99]
	s_mov_b32 m0, s46
	s_nop 0
	global_load_lds_dwordx4 v160, s[24:25]
	s_add_i32 m0, s46, 0x2000
	s_nop 0
	global_load_lds_dwordx4 v132, s[24:25]
	s_mov_b32 m0, s92
	s_nop 0
	s_add_u32 s98, s82, 0xfff80080
	s_addc_u32 s99, s83, -1
	global_load_lds_dwordx4 v128, s[98:99]
	s_mov_b32 m0, s93
	s_nop 0
	global_load_lds_dwordx4 v130, s[98:99]
	s_waitcnt vmcnt(8)
	s_waitcnt lgkmcnt(0)
	s_barrier
	s_setprio 1
	s_waitcnt lgkmcnt(0)
	v_mfma_f32_16x16x32_bf16 v[60:63], v[138:141], v[186:189], v[60:63]
	v_mfma_f32_16x16x32_bf16 v[56:59], v[152:155], v[186:189], v[56:59]
	v_mfma_f32_16x16x32_bf16 v[44:47], v[138:141], v[194:197], v[44:47]
	v_mfma_f32_16x16x32_bf16 v[40:43], v[152:155], v[194:197], v[40:43]
	v_mfma_f32_16x16x32_bf16 v[28:31], v[138:141], v[202:205], v[28:31]
	v_mfma_f32_16x16x32_bf16 v[24:27], v[152:155], v[202:205], v[24:27]
	v_mfma_f32_16x16x32_bf16 v[12:15], v[138:141], v[210:213], v[12:15]
	v_mfma_f32_16x16x32_bf16 v[8:11], v[152:155], v[210:213], v[8:11]
	v_mfma_f32_16x16x32_bf16 v[60:63], v[148:151], v[190:193], v[60:63]
	v_mfma_f32_16x16x32_bf16 v[56:59], v[156:159], v[190:193], v[56:59]
	v_mfma_f32_16x16x32_bf16 v[44:47], v[148:151], v[198:201], v[44:47]
	v_mfma_f32_16x16x32_bf16 v[40:43], v[156:159], v[198:201], v[40:43]
	v_mfma_f32_16x16x32_bf16 v[28:31], v[148:151], v[206:209], v[28:31]
	v_mfma_f32_16x16x32_bf16 v[24:27], v[156:159], v[206:209], v[24:27]
	v_mfma_f32_16x16x32_bf16 v[12:15], v[148:151], v[214:217], v[12:15]
	v_mfma_f32_16x16x32_bf16 v[8:11], v[156:159], v[214:217], v[8:11]
	s_setprio 0
	s_setprio 1
	v_mfma_f32_16x16x32_bf16 v[52:55], v[170:173], v[186:189], v[52:55]
	v_mfma_f32_16x16x32_bf16 v[48:51], v[178:181], v[186:189], v[48:51]
	v_mfma_f32_16x16x32_bf16 v[36:39], v[170:173], v[194:197], v[36:39]
	v_mfma_f32_16x16x32_bf16 v[32:35], v[178:181], v[194:197], v[32:35]
	v_mfma_f32_16x16x32_bf16 v[20:23], v[170:173], v[202:205], v[20:23]
	v_mfma_f32_16x16x32_bf16 v[16:19], v[178:181], v[202:205], v[16:19]
	v_mfma_f32_16x16x32_bf16 v[4:7], v[170:173], v[210:213], v[4:7]
	v_mfma_f32_16x16x32_bf16 v[0:3], v[178:181], v[210:213], v[0:3]
	v_mfma_f32_16x16x32_bf16 v[52:55], v[174:177], v[190:193], v[52:55]
	v_mfma_f32_16x16x32_bf16 v[48:51], v[182:185], v[190:193], v[48:51]
	v_mfma_f32_16x16x32_bf16 v[36:39], v[174:177], v[198:201], v[36:39]
	v_mfma_f32_16x16x32_bf16 v[32:35], v[182:185], v[198:201], v[32:35]
	v_mfma_f32_16x16x32_bf16 v[20:23], v[174:177], v[206:209], v[20:23]
	v_mfma_f32_16x16x32_bf16 v[16:19], v[182:185], v[206:209], v[16:19]
	v_mfma_f32_16x16x32_bf16 v[4:7], v[174:177], v[214:217], v[4:7]
	v_mfma_f32_16x16x32_bf16 v[0:3], v[182:185], v[214:217], v[0:3]
	s_setprio 0
	s_barrier
	s_add_i32 s95, s95, 2
	s_add_u32 s72, s72, 0x100
	s_addc_u32 s73, s73, 0
	s_add_u32 s45, s45, 0x100
	s_addc_u32 s53, s53, 0
	s_cmp_gt_u32 s95, 29
	s_cbranch_scc0 .LBB0_145
	s_and_b64 vcc, exec, s[18:19]
	s_cbranch_vccz .LBB0_148
	s_barrier

; #define PG8_STAGE(bufoff, gbase, voff) do { _Pragma("unroll") for (int _i = 0; _i < 2; ++_i) \
;         __builtin_amdgcn_global_load_lds((const unsigned*)((const char*)(gbase) + (voff)[_i]), (LAS unsigned*)(lds + (bufoff) + ldsw + _i * 8192), 16, 0, 0); } while (0)
; #define PG8_LDA(dst, b, h) do { _Pragma("unroll") for (int m = 0; m < 4; ++m) _Pragma("unroll") for (int k = 0; k < 2; ++k) dst[m][k] = *(const LAS bf16x8*)(lds + PG8_SA(b, h) + aoff + m * 2048 + k * 1024); } while (0)
; #define PG8_LDB(dst, b, h) do { _Pragma("unroll") for (int n = 0; n < 2; ++n) _Pragma("unroll") for (int k = 0; k < 2; ++k) dst[n][k] = *(const LAS bf16x8*)(lds + PG8_SB(b, h) + boff + n * 2048 + k * 1024); } while (0)
; #define PG8_MMA(ai, bj, At, Bt) do { __builtin_amdgcn_s_setprio(1); _Pragma("unroll") for (int m = 0; m < 4; ++m) _Pragma("unroll") for (int n = 0; n < 2; ++n) _Pragma("unroll") for (int k = 0; k < 2; ++k) \
;         acc[ai][bj][m][n] = __builtin_amdgcn_mfma_f32_16x16x32_bf16(Bt[n][k], At[m][k], acc[ai][bj][m][n], 0, 0, 0); __builtin_amdgcn_s_setprio(0); } while (0)
; #define PG8_WAIT_V(n) asm volatile("s_waitcnt vmcnt(" #n ")" ::: "memory")
; #define PG8_WAIT_L(n) asm volatile("s_waitcnt lgkmcnt(" #n ")" ::: "memory")
; #define PG8_BAR __builtin_amdgcn_s_barrier()
; #define PG8_SCHED __builtin_amdgcn_sched_barrier(0)
; template <class Epi, class Sched, bool ALIGN_EPI = true, bool SP2 = true>
; __device__ __forceinline__ void gemm_phase(LAS unsigned char* lds, const Gemm g, const Sched& S, const Epi& E) {
;     ...
;             const bool last = (t == nt - 2);
;             const char* a1 = cA + (size_t)(t + 1) * kstep;
;             const char* a2 = last ? nA : cA + (size_t)(t + 2) * kstep; const char* b2 = last ? nB : cB + (size_t)(t + 2) * kstep;
;             const char* a3 = a2 + kstep; const char* b3 = b2 + kstep;
;             if constexpr (SP2) {
;             PG8_LDB(B0, 0, 0); PG8_LDB(B1, 0, 1); PG8_SCHED; PG8_LDA(At, 0, 0); PG8_STAGE(PG8_SA(1, 1), a1 + hstep, voffA);
;             PG8_WAIT_V(8); PG8_WAIT_L(0); PG8_BAR; PG8_MMA(0, 0, At, B0); PG8_MMA(0, 1, At, B1); PG8_BAR; PG8_SCHED;
;             PG8_LDA(At, 0, 1); PG8_STAGE(PG8_SB(0, 0), b2, voffB); PG8_STAGE(PG8_SB(0, 1), b2 + hstep, voffB); PG8_STAGE(PG8_SA(0, 0), a2, voffA);
;             PG8_WAIT_V(8); PG8_WAIT_L(0); PG8_BAR; PG8_MMA(1, 0, At, B0); PG8_MMA(1, 1, At, B1); PG8_BAR; PG8_SCHED;
.LBB0_187:
	s_add_u32 s24, s66, 0xfffc0080
	s_addc_u32 s25, s67, -1
	s_add_i32 s46, 0, 0x10000
	s_cmp_eq_u32 s53, 12
	s_cselect_b32 s73, s2, s25
	s_cselect_b32 s72, s3, s24
	s_cselect_b32 s25, s31, s45
	s_cselect_b32 s24, s43, s44
	s_add_i32 s47, 0, 0x14000
	v_add_u32_e32 v154, s46, v147
	v_add_u32_e32 v158, s47, v147
	ds_read_b128 v[138:141], v154
	ds_read_b128 v[142:145], v154 offset:1024
	ds_read_b128 v[150:153], v154 offset:2048
	ds_read_b128 v[154:157], v154 offset:3072
	ds_read_b128 v[170:173], v158
	ds_read_b128 v[174:177], v158 offset:1024
	ds_read_b128 v[178:181], v158 offset:2048
	ds_read_b128 v[182:185], v158 offset:3072
	s_add_i32 m0, s63, 0xc000
	ds_read_b128 v[186:189], v149
	ds_read_b128 v[190:193], v149 offset:1024
	ds_read_b128 v[194:197], v149 offset:2048
	ds_read_b128 v[198:201], v149 offset:3072
	ds_read_b128 v[202:205], v149 offset:4096
	ds_read_b128 v[206:209], v149 offset:5120
	ds_read_b128 v[210:213], v149 offset:6144
	ds_read_b128 v[214:217], v149 offset:7168
	global_load_lds_dwordx4 v134, s[66:67]
	s_add_i32 m0, s63, 0xe000
	s_nop 0
	global_load_lds_dwordx4 v136, s[66:67]
	s_waitcnt vmcnt(8)
	s_waitcnt lgkmcnt(0)
	s_barrier
	s_setprio 1
	s_waitcnt lgkmcnt(0)
	v_mfma_f32_16x16x32_bf16 v[124:127], v[138:141], v[186:189], v[124:127]
	v_mfma_f32_16x16x32_bf16 v[120:123], v[150:153], v[186:189], v[120:123]
	v_mfma_f32_16x16x32_bf16 v[108:111], v[138:141], v[194:197], v[108:111]
	v_mfma_f32_16x16x32_bf16 v[104:107], v[150:153], v[194:197], v[104:107]
	v_mfma_f32_16x16x32_bf16 v[92:95], v[138:141], v[202:205], v[92:95]
	v_mfma_f32_16x16x32_bf16 v[88:91], v[150:153], v[202:205], v[88:91]
	v_mfma_f32_16x16x32_bf16 v[76:79], v[138:141], v[210:213], v[76:79]
	v_mfma_f32_16x16x32_bf16 v[72:75], v[150:153], v[210:213], v[72:75]
	v_mfma_f32_16x16x32_bf16 v[124:127], v[142:145], v[190:193], v[124:127]
	v_mfma_f32_16x16x32_bf16 v[120:123], v[154:157], v[190:193], v[120:123]
	v_mfma_f32_16x16x32_bf16 v[108:111], v[142:145], v[198:201], v[108:111]
	v_mfma_f32_16x16x32_bf16 v[104:107], v[154:157], v[198:201], v[104:107]
	v_mfma_f32_16x16x32_bf16 v[92:95], v[142:145], v[206:209], v[92:95]
	v_mfma_f32_16x16x32_bf16 v[88:91], v[154:157], v[206:209], v[88:91]
	v_mfma_f32_16x16x32_bf16 v[76:79], v[142:145], v[214:217], v[76:79]
	v_mfma_f32_16x16x32_bf16 v[72:75], v[154:157], v[214:217], v[72:75]
	s_setprio 0
	s_setprio 1
	v_mfma_f32_16x16x32_bf16 v[116:119], v[170:173], v[186:189], v[116:119]
	v_mfma_f32_16x16x32_bf16 v[112:115], v[178:181], v[186:189], v[112:115]
	v_mfma_f32_16x16x32_bf16 v[100:103], v[170:173], v[194:197], v[100:103]
	v_mfma_f32_16x16x32_bf16 v[96:99], v[178:181], v[194:197], v[96:99]
	v_mfma_f32_16x16x32_bf16 v[84:87], v[170:173], v[202:205], v[84:87]
	v_mfma_f32_16x16x32_bf16 v[80:83], v[178:181], v[202:205], v[80:83]
	v_mfma_f32_16x16x32_bf16 v[68:71], v[170:173], v[210:213], v[68:71]
	v_mfma_f32_16x16x32_bf16 v[64:67], v[178:181], v[210:213], v[64:67]
	v_mfma_f32_16x16x32_bf16 v[116:119], v[174:177], v[190:193], v[116:119]
	v_mfma_f32_16x16x32_bf16 v[112:115], v[182:185], v[190:193], v[112:115]
	v_mfma_f32_16x16x32_bf16 v[100:103], v[174:177], v[198:201], v[100:103]
	v_mfma_f32_16x16x32_bf16 v[96:99], v[182:185], v[198:201], v[96:99]
	v_mfma_f32_16x16x32_bf16 v[84:87], v[174:177], v[206:209], v[84:87]
	v_mfma_f32_16x16x32_bf16 v[80:83], v[182:185], v[206:209], v[80:83]
	v_mfma_f32_16x16x32_bf16 v[68:71], v[174:177], v[214:217], v[68:71]
	v_mfma_f32_16x16x32_bf16 v[64:67], v[182:185], v[214:217], v[64:67]
	s_setprio 0
	s_barrier
	s_add_i32 s46, s46, s90
	s_mov_b32 m0, s46
	ds_read_b128 v[186:189], v149 offset:16384
	ds_read_b128 v[190:193], v149 offset:17408
	ds_read_b128 v[194:197], v149 offset:18432
	ds_read_b128 v[198:201], v149 offset:19456
	ds_read_b128 v[202:205], v149 offset:20480
	ds_read_b128 v[206:209], v149 offset:21504
	ds_read_b128 v[210:213], v149 offset:22528
	ds_read_b128 v[214:217], v149 offset:23552
	global_load_lds_dwordx4 v160, s[24:25]
	s_add_i32 m0, s46, 0x2000
	s_add_u32 vcc_lo, s24, 0x40000
	s_addc_u32 vcc_hi, s25, 0
	s_add_i32 s46, s47, s90
	global_load_lds_dwordx4 v132, s[24:25]
	v_lshl_add_u64 v[218:219], vcc, 0, v[160:161]
	s_mov_b32 m0, s46
	s_nop 0
	global_load_lds_dwordx4 v[218:219], off
	v_lshl_add_u64 v[218:219], vcc, 0, v[132:133]
	s_add_i32 m0, s46, 0x2000
	s_nop 0
	global_load_lds_dwordx4 v[218:219], off
	s_mov_b32 m0, s63
	s_nop 0
	global_load_lds_dwordx4 v128, s[72:73]
	s_mov_b32 m0, s91
	s_nop 0
	global_load_lds_dwordx4 v130, s[72:73]
	s_waitcnt vmcnt(8)
	s_waitcnt lgkmcnt(0)
	s_barrier
; #define PG8_STAGE(bufoff, gbase, voff) do { _Pragma("unroll") for (int _i = 0; _i < 2; ++_i) \
;         __builtin_amdgcn_global_load_lds((const unsigned*)((const char*)(gbase) + (voff)[_i]), (LAS unsigned*)(lds + (bufoff) + ldsw + _i * 8192), 16, 0, 0); } while (0)
; #define PG8_LDA(dst, b, h) do { _Pragma("unroll") for (int m = 0; m < 4; ++m) _Pragma("unroll") for (int k = 0; k < 2; ++k) dst[m][k] = *(const LAS bf16x8*)(lds + PG8_SA(b, h) + aoff + m * 2048 + k * 1024); } while (0)
; #define PG8_LDB(dst, b, h) do { _Pragma("unroll") for (int n = 0; n < 2; ++n) _Pragma("unroll") for (int k = 0; k < 2; ++k) dst[n][k] = *(const LAS bf16x8*)(lds + PG8_SB(b, h) + boff + n * 2048 + k * 1024); } while (0)
; #define PG8_MMA(ai, bj, At, Bt) do { __builtin_amdgcn_s_setprio(1); _Pragma("unroll") for (int m = 0; m < 4; ++m) _Pragma("unroll") for (int n = 0; n < 2; ++n) _Pragma("unroll") for (int k = 0; k < 2; ++k) \
;         acc[ai][bj][m][n] = __builtin_amdgcn_mfma_f32_16x16x32_bf16(Bt[n][k], At[m][k], acc[ai][bj][m][n], 0, 0, 0); __builtin_amdgcn_s_setprio(0); } while (0)
; #define PG8_WAIT_V(n) asm volatile("s_waitcnt vmcnt(" #n ")" ::: "memory")
; #define PG8_WAIT_L(n) asm volatile("s_waitcnt lgkmcnt(" #n ")" ::: "memory")
; #define PG8_BAR __builtin_amdgcn_s_barrier()
; #define PG8_SCHED __builtin_amdgcn_sched_barrier(0)
; template <class Epi, class Sched, bool ALIGN_EPI = true, bool SP2 = true>
; __device__ __forceinline__ void gemm_phase(LAS unsigned char* lds, const Gemm g, const Sched& S, const Epi& E) {
;     ...
;             PG8_WAIT_V(8); PG8_WAIT_L(0); PG8_BAR; PG8_MMA(1, 0, At, B0); PG8_MMA(1, 1, At, B1); PG8_BAR; PG8_SCHED;
;             PG8_LDB(B0, 1, 0); PG8_LDB(B1, 1, 1); PG8_SCHED; PG8_LDA(At, 1, 0); PG8_STAGE(PG8_SA(0, 1), a2 + hstep, voffA);
;             PG8_WAIT_V(8); PG8_WAIT_L(0); PG8_BAR; PG8_MMA(0, 0, At, B0); PG8_MMA(0, 1, At, B1); PG8_BAR; PG8_SCHED;
	s_setprio 1
	s_waitcnt lgkmcnt(0)
	v_mfma_f32_16x16x32_bf16 v[60:63], v[138:141], v[186:189], v[60:63]
	v_mfma_f32_16x16x32_bf16 v[56:59], v[150:153], v[186:189], v[56:59]
	v_mfma_f32_16x16x32_bf16 v[44:47], v[138:141], v[194:197], v[44:47]
	v_mfma_f32_16x16x32_bf16 v[40:43], v[150:153], v[194:197], v[40:43]
	v_mfma_f32_16x16x32_bf16 v[28:31], v[138:141], v[202:205], v[28:31]
	v_mfma_f32_16x16x32_bf16 v[24:27], v[150:153], v[202:205], v[24:27]
	v_mfma_f32_16x16x32_bf16 v[12:15], v[138:141], v[210:213], v[12:15]
	v_mfma_f32_16x16x32_bf16 v[8:11], v[150:153], v[210:213], v[8:11]
	v_mfma_f32_16x16x32_bf16 v[60:63], v[142:145], v[190:193], v[60:63]
	v_mfma_f32_16x16x32_bf16 v[56:59], v[154:157], v[190:193], v[56:59]
	v_mfma_f32_16x16x32_bf16 v[44:47], v[142:145], v[198:201], v[44:47]
	v_mfma_f32_16x16x32_bf16 v[40:43], v[154:157], v[198:201], v[40:43]
	v_mfma_f32_16x16x32_bf16 v[28:31], v[142:145], v[206:209], v[28:31]
	v_mfma_f32_16x16x32_bf16 v[24:27], v[154:157], v[206:209], v[24:27]
	v_mfma_f32_16x16x32_bf16 v[12:15], v[142:145], v[214:217], v[12:15]
	v_mfma_f32_16x16x32_bf16 v[8:11], v[154:157], v[214:217], v[8:11]
	s_setprio 0
	s_setprio 1
	v_mfma_f32_16x16x32_bf16 v[52:55], v[170:173], v[186:189], v[52:55]
	v_mfma_f32_16x16x32_bf16 v[48:51], v[178:181], v[186:189], v[48:51]
	v_mfma_f32_16x16x32_bf16 v[36:39], v[170:173], v[194:197], v[36:39]
	v_mfma_f32_16x16x32_bf16 v[32:35], v[178:181], v[194:197], v[32:35]
	v_mfma_f32_16x16x32_bf16 v[20:23], v[170:173], v[202:205], v[20:23]
	v_mfma_f32_16x16x32_bf16 v[16:19], v[178:181], v[202:205], v[16:19]
	v_mfma_f32_16x16x32_bf16 v[4:7], v[170:173], v[210:213], v[4:7]
	v_mfma_f32_16x16x32_bf16 v[0:3], v[178:181], v[210:213], v[0:3]
	v_mfma_f32_16x16x32_bf16 v[52:55], v[174:177], v[190:193], v[52:55]
	v_mfma_f32_16x16x32_bf16 v[48:51], v[182:185], v[190:193], v[48:51]
	v_mfma_f32_16x16x32_bf16 v[36:39], v[174:177], v[198:201], v[36:39]
	v_mfma_f32_16x16x32_bf16 v[32:35], v[182:185], v[198:201], v[32:35]
	v_mfma_f32_16x16x32_bf16 v[20:23], v[174:177], v[206:209], v[20:23]
	v_mfma_f32_16x16x32_bf16 v[16:19], v[182:185], v[206:209], v[16:19]
	v_mfma_f32_16x16x32_bf16 v[4:7], v[174:177], v[214:217], v[4:7]
	v_mfma_f32_16x16x32_bf16 v[0:3], v[182:185], v[214:217], v[0:3]
	s_setprio 0
	s_barrier
	s_add_i32 s46, 0, 0x18000
	s_add_i32 s47, 0, 0x1c000
	v_add_u32_e32 v154, s46, v147
	v_add_u32_e32 v182, s47, v147
	ds_read_b128 v[138:141], v154
	ds_read_b128 v[142:145], v154 offset:1024
	ds_read_b128 v[150:153], v154 offset:2048
	ds_read_b128 v[154:157], v154 offset:3072
	ds_read_b128 v[170:173], v182
	ds_read_b128 v[174:177], v182 offset:1024
	ds_read_b128 v[178:181], v182 offset:2048
	ds_read_b128 v[182:185], v182 offset:3072
	s_add_u32 s72, s72, 0x40000
	s_addc_u32 s73, s73, 0
	s_mov_b32 m0, s92
	ds_read_b128 v[186:189], v149 offset:32768
	ds_read_b128 v[190:193], v149 offset:33792
	ds_read_b128 v[194:197], v149 offset:34816
	ds_read_b128 v[198:201], v149 offset:35840
	ds_read_b128 v[202:205], v149 offset:36864
	ds_read_b128 v[206:209], v149 offset:37888
	ds_read_b128 v[210:213], v149 offset:38912
	ds_read_b128 v[214:217], v149 offset:39936
	global_load_lds_dwordx4 v128, s[72:73]
	s_mov_b32 m0, s93
	s_nop 0
	global_load_lds_dwordx4 v130, s[72:73]
	s_waitcnt vmcnt(8)
	s_waitcnt lgkmcnt(0)
	s_barrier
	s_setprio 1
	s_waitcnt lgkmcnt(0)
	v_mfma_f32_16x16x32_bf16 v[124:127], v[138:141], v[186:189], v[124:127]
	v_mfma_f32_16x16x32_bf16 v[120:123], v[150:153], v[186:189], v[120:123]
	v_mfma_f32_16x16x32_bf16 v[108:111], v[138:141], v[194:197], v[108:111]
	v_mfma_f32_16x16x32_bf16 v[104:107], v[150:153], v[194:197], v[104:107]
	v_mfma_f32_16x16x32_bf16 v[92:95], v[138:141], v[202:205], v[92:95]
	v_mfma_f32_16x16x32_bf16 v[88:91], v[150:153], v[202:205], v[88:91]
	v_mfma_f32_16x16x32_bf16 v[76:79], v[138:141], v[210:213], v[76:79]
	v_mfma_f32_16x16x32_bf16 v[72:75], v[150:153], v[210:213], v[72:75]
	v_mfma_f32_16x16x32_bf16 v[124:127], v[142:145], v[190:193], v[124:127]
	v_mfma_f32_16x16x32_bf16 v[120:123], v[154:157], v[190:193], v[120:123]
	v_mfma_f32_16x16x32_bf16 v[108:111], v[142:145], v[198:201], v[108:111]
	v_mfma_f32_16x16x32_bf16 v[104:107], v[154:157], v[198:201], v[104:107]
	v_mfma_f32_16x16x32_bf16 v[92:95], v[142:145], v[206:209], v[92:95]
	v_mfma_f32_16x16x32_bf16 v[88:91], v[154:157], v[206:209], v[88:91]
	v_mfma_f32_16x16x32_bf16 v[76:79], v[142:145], v[214:217], v[76:79]
	v_mfma_f32_16x16x32_bf16 v[72:75], v[154:157], v[214:217], v[72:75]
	s_setprio 0
	s_setprio 1
	v_mfma_f32_16x16x32_bf16 v[116:119], v[170:173], v[186:189], v[116:119]
	v_mfma_f32_16x16x32_bf16 v[112:115], v[178:181], v[186:189], v[112:115]
	v_mfma_f32_16x16x32_bf16 v[100:103], v[170:173], v[194:197], v[100:103]
	v_mfma_f32_16x16x32_bf16 v[96:99], v[178:181], v[194:197], v[96:99]
	v_mfma_f32_16x16x32_bf16 v[84:87], v[170:173], v[202:205], v[84:87]
	v_mfma_f32_16x16x32_bf16 v[80:83], v[178:181], v[202:205], v[80:83]
	v_mfma_f32_16x16x32_bf16 v[68:71], v[170:173], v[210:213], v[68:71]
	v_mfma_f32_16x16x32_bf16 v[64:67], v[178:181], v[210:213], v[64:67]
	v_mfma_f32_16x16x32_bf16 v[116:119], v[174:177], v[190:193], v[116:119]
	v_mfma_f32_16x16x32_bf16 v[112:115], v[182:185], v[190:193], v[112:115]
	v_mfma_f32_16x16x32_bf16 v[100:103], v[174:177], v[198:201], v[100:103]
	v_mfma_f32_16x16x32_bf16 v[96:99], v[182:185], v[198:201], v[96:99]
	v_mfma_f32_16x16x32_bf16 v[84:87], v[174:177], v[206:209], v[84:87]
	v_mfma_f32_16x16x32_bf16 v[80:83], v[182:185], v[206:209], v[80:83]
	v_mfma_f32_16x16x32_bf16 v[68:71], v[174:177], v[214:217], v[68:71]
	v_mfma_f32_16x16x32_bf16 v[64:67], v[182:185], v[214:217], v[64:67]
	s_setprio 0
	s_barrier
; #define PG8_STAGE(bufoff, gbase, voff) do { _Pragma("unroll") for (int _i = 0; _i < 2; ++_i) \
;         __builtin_amdgcn_global_load_lds((const unsigned*)((const char*)(gbase) + (voff)[_i]), (LAS unsigned*)(lds + (bufoff) + ldsw + _i * 8192), 16, 0, 0); } while (0)
; #define PG8_LDA(dst, b, h) do { _Pragma("unroll") for (int m = 0; m < 4; ++m) _Pragma("unroll") for (int k = 0; k < 2; ++k) dst[m][k] = *(const LAS bf16x8*)(lds + PG8_SA(b, h) + aoff + m * 2048 + k * 1024); } while (0)
; #define PG8_MMA(ai, bj, At, Bt) do { __builtin_amdgcn_s_setprio(1); _Pragma("unroll") for (int m = 0; m < 4; ++m) _Pragma("unroll") for (int n = 0; n < 2; ++n) _Pragma("unroll") for (int k = 0; k < 2; ++k) \
;         acc[ai][bj][m][n] = __builtin_amdgcn_mfma_f32_16x16x32_bf16(Bt[n][k], At[m][k], acc[ai][bj][m][n], 0, 0, 0); __builtin_amdgcn_s_setprio(0); } while (0)
; #define PG8_WAIT_V(n) asm volatile("s_waitcnt vmcnt(" #n ")" ::: "memory")
; #define PG8_WAIT_L(n) asm volatile("s_waitcnt lgkmcnt(" #n ")" ::: "memory")
; #define PG8_BAR __builtin_amdgcn_s_barrier()
; #define PG8_SCHED __builtin_amdgcn_sched_barrier(0)
; template <class Epi, class Sched, bool ALIGN_EPI = true, bool SP2 = true>
; __device__ __forceinline__ void gemm_phase(LAS unsigned char* lds, const Gemm g, const Sched& S, const Epi& E) {
;     ...
;         for (int t = 0; t < nt; t += 2) {
;     ...
;             PG8_LDA(At, 1, 1); PG8_STAGE(PG8_SB(1, 0), b3, voffB); PG8_STAGE(PG8_SB(1, 1), b3 + hstep, voffB); PG8_STAGE(PG8_SA(1, 0), a3, voffA);
;             PG8_WAIT_V(8); PG8_WAIT_L(0); PG8_BAR; PG8_MMA(1, 0, At, B0); PG8_MMA(1, 1, At, B1); PG8_BAR; PG8_SCHED;
	s_add_i32 s46, s46, s90
	s_mov_b32 m0, s46
	ds_read_b128 v[186:189], v149 offset:49152
	ds_read_b128 v[190:193], v149 offset:50176
	ds_read_b128 v[194:197], v149 offset:51200
	ds_read_b128 v[198:201], v149 offset:52224
	ds_read_b128 v[202:205], v149 offset:53248
	ds_read_b128 v[206:209], v149 offset:54272
	ds_read_b128 v[210:213], v149 offset:55296
	ds_read_b128 v[214:217], v149 offset:56320
	s_add_u32 s98, s24, 0x80
	s_addc_u32 s99, s25, 0
	global_load_lds_dwordx4 v160, s[98:99]
	s_add_i32 m0, s46, 0x2000
	s_add_u32 s24, s24, 0x40080
	s_addc_u32 s25, s25, 0
	s_add_i32 s46, s47, s90
	global_load_lds_dwordx4 v132, s[98:99]
	s_mov_b32 m0, s46
	s_nop 0
	global_load_lds_dwordx4 v160, s[24:25]
	s_add_i32 m0, s46, 0x2000
	s_nop 0
	global_load_lds_dwordx4 v132, s[24:25]
	s_mov_b32 m0, s94
	s_nop 0
	s_add_u32 s98, s72, 0xfffc0080
	s_addc_u32 s99, s73, -1
	global_load_lds_dwordx4 v128, s[98:99]
	s_mov_b32 m0, s95
	s_nop 0
	global_load_lds_dwordx4 v130, s[98:99]
	s_waitcnt vmcnt(8)
	s_waitcnt lgkmcnt(0)
	s_barrier
	s_setprio 1
	s_waitcnt lgkmcnt(0)
	v_mfma_f32_16x16x32_bf16 v[60:63], v[138:141], v[186:189], v[60:63]
	v_mfma_f32_16x16x32_bf16 v[56:59], v[150:153], v[186:189], v[56:59]
	v_mfma_f32_16x16x32_bf16 v[44:47], v[138:141], v[194:197], v[44:47]
	v_mfma_f32_16x16x32_bf16 v[40:43], v[150:153], v[194:197], v[40:43]
	v_mfma_f32_16x16x32_bf16 v[28:31], v[138:141], v[202:205], v[28:31]
	v_mfma_f32_16x16x32_bf16 v[24:27], v[150:153], v[202:205], v[24:27]
	v_mfma_f32_16x16x32_bf16 v[12:15], v[138:141], v[210:213], v[12:15]
	v_mfma_f32_16x16x32_bf16 v[8:11], v[150:153], v[210:213], v[8:11]
	v_mfma_f32_16x16x32_bf16 v[60:63], v[142:145], v[190:193], v[60:63]
	v_mfma_f32_16x16x32_bf16 v[56:59], v[154:157], v[190:193], v[56:59]
	v_mfma_f32_16x16x32_bf16 v[44:47], v[142:145], v[198:201], v[44:47]
	v_mfma_f32_16x16x32_bf16 v[40:43], v[154:157], v[198:201], v[40:43]
	v_mfma_f32_16x16x32_bf16 v[28:31], v[142:145], v[206:209], v[28:31]
	v_mfma_f32_16x16x32_bf16 v[24:27], v[154:157], v[206:209], v[24:27]
	v_mfma_f32_16x16x32_bf16 v[12:15], v[142:145], v[214:217], v[12:15]
	v_mfma_f32_16x16x32_bf16 v[8:11], v[154:157], v[214:217], v[8:11]
	s_setprio 0
	s_setprio 1
	v_mfma_f32_16x16x32_bf16 v[52:55], v[170:173], v[186:189], v[52:55]
	v_mfma_f32_16x16x32_bf16 v[48:51], v[178:181], v[186:189], v[48:51]
	v_mfma_f32_16x16x32_bf16 v[36:39], v[170:173], v[194:197], v[36:39]
	v_mfma_f32_16x16x32_bf16 v[32:35], v[178:181], v[194:197], v[32:35]
	v_mfma_f32_16x16x32_bf16 v[20:23], v[170:173], v[202:205], v[20:23]
	v_mfma_f32_16x16x32_bf16 v[16:19], v[178:181], v[202:205], v[16:19]
	v_mfma_f32_16x16x32_bf16 v[4:7], v[170:173], v[210:213], v[4:7]
	v_mfma_f32_16x16x32_bf16 v[0:3], v[178:181], v[210:213], v[0:3]
	v_mfma_f32_16x16x32_bf16 v[52:55], v[174:177], v[190:193], v[52:55]
	v_mfma_f32_16x16x32_bf16 v[48:51], v[182:185], v[190:193], v[48:51]
	v_mfma_f32_16x16x32_bf16 v[36:39], v[174:177], v[198:201], v[36:39]
	v_mfma_f32_16x16x32_bf16 v[32:35], v[182:185], v[198:201], v[32:35]
	v_mfma_f32_16x16x32_bf16 v[20:23], v[174:177], v[206:209], v[20:23]
	v_mfma_f32_16x16x32_bf16 v[16:19], v[182:185], v[206:209], v[16:19]
	v_mfma_f32_16x16x32_bf16 v[4:7], v[174:177], v[214:217], v[4:7]
	v_mfma_f32_16x16x32_bf16 v[0:3], v[182:185], v[214:217], v[0:3]
	s_setprio 0
	s_barrier
	s_add_i32 s53, s53, 2
	s_add_u32 s66, s66, 0x100
	s_addc_u32 s67, s67, 0
	s_add_u32 s44, s44, 0x100
	s_addc_u32 s45, s45, 0
	s_cmp_gt_u32 s53, 13
	s_cbranch_scc0 .LBB0_187
	s_and_b64 vcc, exec, s[18:19]
	s_cbranch_vccz .LBB0_190
	s_barrier

; #define PG8_STAGE(bufoff, gbase, voff) do { _Pragma("unroll") for (int _i = 0; _i < 2; ++_i) \
;         __builtin_amdgcn_global_load_lds((const unsigned*)((const char*)(gbase) + (voff)[_i]), (LAS unsigned*)(lds + (bufoff) + ldsw + _i * 8192), 16, 0, 0); } while (0)
; #define PG8_LDA(dst, b, h) do { _Pragma("unroll") for (int m = 0; m < 4; ++m) _Pragma("unroll") for (int k = 0; k < 2; ++k) dst[m][k] = *(const LAS bf16x8*)(lds + PG8_SA(b, h) + aoff + m * 2048 + k * 1024); } while (0)
; #define PG8_LDB(dst, b, h) do { _Pragma("unroll") for (int n = 0; n < 2; ++n) _Pragma("unroll") for (int k = 0; k < 2; ++k) dst[n][k] = *(const LAS bf16x8*)(lds + PG8_SB(b, h) + boff + n * 2048 + k * 1024); } while (0)
; #define PG8_MMA(ai, bj, At, Bt) do { __builtin_amdgcn_s_setprio(1); _Pragma("unroll") for (int m = 0; m < 4; ++m) _Pragma("unroll") for (int n = 0; n < 2; ++n) _Pragma("unroll") for (int k = 0; k < 2; ++k) \
;         acc[ai][bj][m][n] = __builtin_amdgcn_mfma_f32_16x16x32_bf16(Bt[n][k], At[m][k], acc[ai][bj][m][n], 0, 0, 0); __builtin_amdgcn_s_setprio(0); } while (0)
; #define PG8_WAIT_V(n) asm volatile("s_waitcnt vmcnt(" #n ")" ::: "memory")
; #define PG8_WAIT_L(n) asm volatile("s_waitcnt lgkmcnt(" #n ")" ::: "memory")
; #define PG8_BAR __builtin_amdgcn_s_barrier()
; #define PG8_SCHED __builtin_amdgcn_sched_barrier(0)
; template <class Epi, class Sched, bool ALIGN_EPI = true, bool SP2 = true>
; __device__ __forceinline__ void gemm_phase(LAS unsigned char* lds, const Gemm g, const Sched& S, const Epi& E) {
;     ...
;             const bool last = (t == nt - 2);
;             const char* a1 = cA + (size_t)(t + 1) * kstep;
;             const char* a2 = last ? nA : cA + (size_t)(t + 2) * kstep; const char* b2 = last ? nB : cB + (size_t)(t + 2) * kstep;
;             const char* a3 = a2 + kstep; const char* b3 = b2 + kstep;
;             if constexpr (SP2) {
;             PG8_LDB(B0, 0, 0); PG8_LDB(B1, 0, 1); PG8_SCHED; PG8_LDA(At, 0, 0); PG8_STAGE(PG8_SA(1, 1), a1 + hstep, voffA);
;             PG8_WAIT_V(8); PG8_WAIT_L(0); PG8_BAR; PG8_MMA(0, 0, At, B0); PG8_MMA(0, 1, At, B1); PG8_BAR; PG8_SCHED;
;             PG8_LDA(At, 0, 1); PG8_STAGE(PG8_SB(0, 0), b2, voffB); PG8_STAGE(PG8_SB(0, 1), b2 + hstep, voffB); PG8_STAGE(PG8_SA(0, 0), a2, voffA);
;             PG8_WAIT_V(8); PG8_WAIT_L(0); PG8_BAR; PG8_MMA(1, 0, At, B0); PG8_MMA(1, 1, At, B1); PG8_BAR; PG8_SCHED;
.LBB0_211:
	s_add_u32 s24, s60, 0xfffc0080
	s_addc_u32 s25, s61, -1
	s_add_i32 s46, 0, 0x10000
	s_cmp_eq_u32 s45, 12
	s_cselect_b32 s63, s2, s25
	s_cselect_b32 s62, s3, s24
	s_cselect_b32 s25, s17, s44
	s_cselect_b32 s24, s19, s43
	s_add_i32 s47, 0, 0x14000
	v_add_u32_e32 v154, s46, v147
	v_add_u32_e32 v158, s47, v147
	ds_read_b128 v[138:141], v154
	ds_read_b128 v[142:145], v154 offset:1024
	ds_read_b128 v[150:153], v154 offset:2048
	ds_read_b128 v[154:157], v154 offset:3072
	ds_read_b128 v[170:173], v158
	ds_read_b128 v[174:177], v158 offset:1024
	ds_read_b128 v[178:181], v158 offset:2048
	ds_read_b128 v[182:185], v158 offset:3072
	s_add_i32 m0, s55, 0xc000
	ds_read_b128 v[186:189], v149
	ds_read_b128 v[190:193], v149 offset:1024
	ds_read_b128 v[194:197], v149 offset:2048
	ds_read_b128 v[198:201], v149 offset:3072
	ds_read_b128 v[202:205], v149 offset:4096
	ds_read_b128 v[206:209], v149 offset:5120
	ds_read_b128 v[210:213], v149 offset:6144
	ds_read_b128 v[214:217], v149 offset:7168
	global_load_lds_dwordx4 v134, s[60:61]
	s_add_i32 m0, s55, 0xe000
	s_nop 0
	global_load_lds_dwordx4 v136, s[60:61]
	s_waitcnt vmcnt(8)
	s_waitcnt lgkmcnt(0)
	s_barrier
	s_setprio 1
	s_waitcnt lgkmcnt(0)
	v_mfma_f32_16x16x32_bf16 v[124:127], v[138:141], v[186:189], v[124:127]
	v_mfma_f32_16x16x32_bf16 v[120:123], v[150:153], v[186:189], v[120:123]
	v_mfma_f32_16x16x32_bf16 v[108:111], v[138:141], v[194:197], v[108:111]
	v_mfma_f32_16x16x32_bf16 v[104:107], v[150:153], v[194:197], v[104:107]
	v_mfma_f32_16x16x32_bf16 v[92:95], v[138:141], v[202:205], v[92:95]
	v_mfma_f32_16x16x32_bf16 v[88:91], v[150:153], v[202:205], v[88:91]
	v_mfma_f32_16x16x32_bf16 v[76:79], v[138:141], v[210:213], v[76:79]
	v_mfma_f32_16x16x32_bf16 v[72:75], v[150:153], v[210:213], v[72:75]
	v_mfma_f32_16x16x32_bf16 v[124:127], v[142:145], v[190:193], v[124:127]
	v_mfma_f32_16x16x32_bf16 v[120:123], v[154:157], v[190:193], v[120:123]
	v_mfma_f32_16x16x32_bf16 v[108:111], v[142:145], v[198:201], v[108:111]
	v_mfma_f32_16x16x32_bf16 v[104:107], v[154:157], v[198:201], v[104:107]
	v_mfma_f32_16x16x32_bf16 v[92:95], v[142:145], v[206:209], v[92:95]
	v_mfma_f32_16x16x32_bf16 v[88:91], v[154:157], v[206:209], v[88:91]
	v_mfma_f32_16x16x32_bf16 v[76:79], v[142:145], v[214:217], v[76:79]
	v_mfma_f32_16x16x32_bf16 v[72:75], v[154:157], v[214:217], v[72:75]
	s_setprio 0
	s_setprio 1
	v_mfma_f32_16x16x32_bf16 v[116:119], v[170:173], v[186:189], v[116:119]
	v_mfma_f32_16x16x32_bf16 v[112:115], v[178:181], v[186:189], v[112:115]
	v_mfma_f32_16x16x32_bf16 v[100:103], v[170:173], v[194:197], v[100:103]
	v_mfma_f32_16x16x32_bf16 v[96:99], v[178:181], v[194:197], v[96:99]
	v_mfma_f32_16x16x32_bf16 v[84:87], v[170:173], v[202:205], v[84:87]
	v_mfma_f32_16x16x32_bf16 v[80:83], v[178:181], v[202:205], v[80:83]
	v_mfma_f32_16x16x32_bf16 v[68:71], v[170:173], v[210:213], v[68:71]
	v_mfma_f32_16x16x32_bf16 v[64:67], v[178:181], v[210:213], v[64:67]
	v_mfma_f32_16x16x32_bf16 v[116:119], v[174:177], v[190:193], v[116:119]
	v_mfma_f32_16x16x32_bf16 v[112:115], v[182:185], v[190:193], v[112:115]
	v_mfma_f32_16x16x32_bf16 v[100:103], v[174:177], v[198:201], v[100:103]
	v_mfma_f32_16x16x32_bf16 v[96:99], v[182:185], v[198:201], v[96:99]
	v_mfma_f32_16x16x32_bf16 v[84:87], v[174:177], v[206:209], v[84:87]
	v_mfma_f32_16x16x32_bf16 v[80:83], v[182:185], v[206:209], v[80:83]
	v_mfma_f32_16x16x32_bf16 v[68:71], v[174:177], v[214:217], v[68:71]
	v_mfma_f32_16x16x32_bf16 v[64:67], v[182:185], v[214:217], v[64:67]
	s_setprio 0
	s_barrier
	s_add_i32 s46, s46, s73
	s_mov_b32 m0, s46
	ds_read_b128 v[186:189], v149 offset:16384
	ds_read_b128 v[190:193], v149 offset:17408
	ds_read_b128 v[194:197], v149 offset:18432
	ds_read_b128 v[198:201], v149 offset:19456
	ds_read_b128 v[202:205], v149 offset:20480
	ds_read_b128 v[206:209], v149 offset:21504
	ds_read_b128 v[210:213], v149 offset:22528
	ds_read_b128 v[214:217], v149 offset:23552
	global_load_lds_dwordx4 v160, s[24:25]
	s_add_i32 m0, s46, 0x2000
	s_add_u32 s94, s24, 0x40000
	s_addc_u32 s95, s25, 0
	s_add_i32 s46, s47, s73
	global_load_lds_dwordx4 v132, s[24:25]
	s_mov_b32 m0, s46
	s_nop 0
	global_load_lds_dwordx4 v160, s[94:95]
	s_add_i32 m0, s46, 0x2000
	s_nop 0
	global_load_lds_dwordx4 v132, s[94:95]
	s_mov_b32 m0, s55
	s_nop 0
	global_load_lds_dwordx4 v128, s[62:63]
	s_mov_b32 m0, s79
	s_nop 0
	global_load_lds_dwordx4 v130, s[62:63]
	s_waitcnt vmcnt(8)
	s_waitcnt lgkmcnt(0)
	s_barrier
	s_setprio 1
	s_waitcnt lgkmcnt(0)
	v_mfma_f32_16x16x32_bf16 v[60:63], v[138:141], v[186:189], v[60:63]
	v_mfma_f32_16x16x32_bf16 v[56:59], v[150:153], v[186:189], v[56:59]
	v_mfma_f32_16x16x32_bf16 v[44:47], v[138:141], v[194:197], v[44:47]
	v_mfma_f32_16x16x32_bf16 v[40:43], v[150:153], v[194:197], v[40:43]
	v_mfma_f32_16x16x32_bf16 v[28:31], v[138:141], v[202:205], v[28:31]
	v_mfma_f32_16x16x32_bf16 v[24:27], v[150:153], v[202:205], v[24:27]
	v_mfma_f32_16x16x32_bf16 v[12:15], v[138:141], v[210:213], v[12:15]
	v_mfma_f32_16x16x32_bf16 v[8:11], v[150:153], v[210:213], v[8:11]
	v_mfma_f32_16x16x32_bf16 v[60:63], v[142:145], v[190:193], v[60:63]
	v_mfma_f32_16x16x32_bf16 v[56:59], v[154:157], v[190:193], v[56:59]
	v_mfma_f32_16x16x32_bf16 v[44:47], v[142:145], v[198:201], v[44:47]
	v_mfma_f32_16x16x32_bf16 v[40:43], v[154:157], v[198:201], v[40:43]
	v_mfma_f32_16x16x32_bf16 v[28:31], v[142:145], v[206:209], v[28:31]
	v_mfma_f32_16x16x32_bf16 v[24:27], v[154:157], v[206:209], v[24:27]
	v_mfma_f32_16x16x32_bf16 v[12:15], v[142:145], v[214:217], v[12:15]
	v_mfma_f32_16x16x32_bf16 v[8:11], v[154:157], v[214:217], v[8:11]
	s_setprio 0
	s_setprio 1
	v_mfma_f32_16x16x32_bf16 v[52:55], v[170:173], v[186:189], v[52:55]
	v_mfma_f32_16x16x32_bf16 v[48:51], v[178:181], v[186:189], v[48:51]
	v_mfma_f32_16x16x32_bf16 v[36:39], v[170:173], v[194:197], v[36:39]
	v_mfma_f32_16x16x32_bf16 v[32:35], v[178:181], v[194:197], v[32:35]
	v_mfma_f32_16x16x32_bf16 v[20:23], v[170:173], v[202:205], v[20:23]
	v_mfma_f32_16x16x32_bf16 v[16:19], v[178:181], v[202:205], v[16:19]
	v_mfma_f32_16x16x32_bf16 v[4:7], v[170:173], v[210:213], v[4:7]
	v_mfma_f32_16x16x32_bf16 v[0:3], v[178:181], v[210:213], v[0:3]
	v_mfma_f32_16x16x32_bf16 v[52:55], v[174:177], v[190:193], v[52:55]
	v_mfma_f32_16x16x32_bf16 v[48:51], v[182:185], v[190:193], v[48:51]
	v_mfma_f32_16x16x32_bf16 v[36:39], v[174:177], v[198:201], v[36:39]
	v_mfma_f32_16x16x32_bf16 v[32:35], v[182:185], v[198:201], v[32:35]
	v_mfma_f32_16x16x32_bf16 v[20:23], v[174:177], v[206:209], v[20:23]
	v_mfma_f32_16x16x32_bf16 v[16:19], v[182:185], v[206:209], v[16:19]
	v_mfma_f32_16x16x32_bf16 v[4:7], v[174:177], v[214:217], v[4:7]
	v_mfma_f32_16x16x32_bf16 v[0:3], v[182:185], v[214:217], v[0:3]
	s_setprio 0
	s_barrier
; #define PG8_STAGE(bufoff, gbase, voff) do { _Pragma("unroll") for (int _i = 0; _i < 2; ++_i) \
;         __builtin_amdgcn_global_load_lds((const unsigned*)((const char*)(gbase) + (voff)[_i]), (LAS unsigned*)(lds + (bufoff) + ldsw + _i * 8192), 16, 0, 0); } while (0)
; #define PG8_LDA(dst, b, h) do { _Pragma("unroll") for (int m = 0; m < 4; ++m) _Pragma("unroll") for (int k = 0; k < 2; ++k) dst[m][k] = *(const LAS bf16x8*)(lds + PG8_SA(b, h) + aoff + m * 2048 + k * 1024); } while (0)
; #define PG8_LDB(dst, b, h) do { _Pragma("unroll") for (int n = 0; n < 2; ++n) _Pragma("unroll") for (int k = 0; k < 2; ++k) dst[n][k] = *(const LAS bf16x8*)(lds + PG8_SB(b, h) + boff + n * 2048 + k * 1024); } while (0)
; #define PG8_MMA(ai, bj, At, Bt) do { __builtin_amdgcn_s_setprio(1); _Pragma("unroll") for (int m = 0; m < 4; ++m) _Pragma("unroll") for (int n = 0; n < 2; ++n) _Pragma("unroll") for (int k = 0; k < 2; ++k) \
;         acc[ai][bj][m][n] = __builtin_amdgcn_mfma_f32_16x16x32_bf16(Bt[n][k], At[m][k], acc[ai][bj][m][n], 0, 0, 0); __builtin_amdgcn_s_setprio(0); } while (0)
; #define PG8_WAIT_V(n) asm volatile("s_waitcnt vmcnt(" #n ")" ::: "memory")
; #define PG8_WAIT_L(n) asm volatile("s_waitcnt lgkmcnt(" #n ")" ::: "memory")
; #define PG8_BAR __builtin_amdgcn_s_barrier()
; #define PG8_SCHED __builtin_amdgcn_sched_barrier(0)
; template <class Epi, class Sched, bool ALIGN_EPI = true, bool SP2 = true>
; __device__ __forceinline__ void gemm_phase(LAS unsigned char* lds, const Gemm g, const Sched& S, const Epi& E) {
;     ...
;         for (int t = 0; t < nt; t += 2) {
;     ...
;             PG8_LDB(B0, 1, 0); PG8_LDB(B1, 1, 1); PG8_SCHED; PG8_LDA(At, 1, 0); PG8_STAGE(PG8_SA(0, 1), a2 + hstep, voffA);
;             PG8_WAIT_V(8); PG8_WAIT_L(0); PG8_BAR; PG8_MMA(0, 0, At, B0); PG8_MMA(0, 1, At, B1); PG8_BAR; PG8_SCHED;
;             PG8_LDA(At, 1, 1); PG8_STAGE(PG8_SB(1, 0), b3, voffB); PG8_STAGE(PG8_SB(1, 1), b3 + hstep, voffB); PG8_STAGE(PG8_SA(1, 0), a3, voffA);
;             PG8_WAIT_V(8); PG8_WAIT_L(0); PG8_BAR; PG8_MMA(1, 0, At, B0); PG8_MMA(1, 1, At, B1); PG8_BAR; PG8_SCHED;
	s_add_i32 s46, 0, 0x18000
	s_add_i32 s47, 0, 0x1c000
	v_add_u32_e32 v154, s46, v147
	v_add_u32_e32 v182, s47, v147
	ds_read_b128 v[138:141], v154
	ds_read_b128 v[142:145], v154 offset:1024
	ds_read_b128 v[150:153], v154 offset:2048
	ds_read_b128 v[154:157], v154 offset:3072
	ds_read_b128 v[170:173], v182
	ds_read_b128 v[174:177], v182 offset:1024
	ds_read_b128 v[178:181], v182 offset:2048
	ds_read_b128 v[182:185], v182 offset:3072
	s_add_u32 s62, s62, 0x40000
	s_addc_u32 s63, s63, 0
	s_mov_b32 m0, s82
	ds_read_b128 v[186:189], v149 offset:32768
	ds_read_b128 v[190:193], v149 offset:33792
	ds_read_b128 v[194:197], v149 offset:34816
	ds_read_b128 v[198:201], v149 offset:35840
	ds_read_b128 v[202:205], v149 offset:36864
	ds_read_b128 v[206:209], v149 offset:37888
	ds_read_b128 v[210:213], v149 offset:38912
	ds_read_b128 v[214:217], v149 offset:39936
	global_load_lds_dwordx4 v128, s[62:63]
	s_mov_b32 m0, s83
	s_nop 0
	global_load_lds_dwordx4 v130, s[62:63]
	s_waitcnt vmcnt(8)
	s_waitcnt lgkmcnt(0)
	s_barrier
	s_setprio 1
	s_waitcnt lgkmcnt(0)
	v_mfma_f32_16x16x32_bf16 v[124:127], v[138:141], v[186:189], v[124:127]
	v_mfma_f32_16x16x32_bf16 v[120:123], v[150:153], v[186:189], v[120:123]
	v_mfma_f32_16x16x32_bf16 v[108:111], v[138:141], v[194:197], v[108:111]
	v_mfma_f32_16x16x32_bf16 v[104:107], v[150:153], v[194:197], v[104:107]
	v_mfma_f32_16x16x32_bf16 v[92:95], v[138:141], v[202:205], v[92:95]
	v_mfma_f32_16x16x32_bf16 v[88:91], v[150:153], v[202:205], v[88:91]
	v_mfma_f32_16x16x32_bf16 v[76:79], v[138:141], v[210:213], v[76:79]
	v_mfma_f32_16x16x32_bf16 v[72:75], v[150:153], v[210:213], v[72:75]
	v_mfma_f32_16x16x32_bf16 v[124:127], v[142:145], v[190:193], v[124:127]
	v_mfma_f32_16x16x32_bf16 v[120:123], v[154:157], v[190:193], v[120:123]
	v_mfma_f32_16x16x32_bf16 v[108:111], v[142:145], v[198:201], v[108:111]
	v_mfma_f32_16x16x32_bf16 v[104:107], v[154:157], v[198:201], v[104:107]
	v_mfma_f32_16x16x32_bf16 v[92:95], v[142:145], v[206:209], v[92:95]
	v_mfma_f32_16x16x32_bf16 v[88:91], v[154:157], v[206:209], v[88:91]
	v_mfma_f32_16x16x32_bf16 v[76:79], v[142:145], v[214:217], v[76:79]
	v_mfma_f32_16x16x32_bf16 v[72:75], v[154:157], v[214:217], v[72:75]
	s_setprio 0
	s_setprio 1
	v_mfma_f32_16x16x32_bf16 v[116:119], v[170:173], v[186:189], v[116:119]
	v_mfma_f32_16x16x32_bf16 v[112:115], v[178:181], v[186:189], v[112:115]
	v_mfma_f32_16x16x32_bf16 v[100:103], v[170:173], v[194:197], v[100:103]
	v_mfma_f32_16x16x32_bf16 v[96:99], v[178:181], v[194:197], v[96:99]
	v_mfma_f32_16x16x32_bf16 v[84:87], v[170:173], v[202:205], v[84:87]
	v_mfma_f32_16x16x32_bf16 v[80:83], v[178:181], v[202:205], v[80:83]
	v_mfma_f32_16x16x32_bf16 v[68:71], v[170:173], v[210:213], v[68:71]
	v_mfma_f32_16x16x32_bf16 v[64:67], v[178:181], v[210:213], v[64:67]
	v_mfma_f32_16x16x32_bf16 v[116:119], v[174:177], v[190:193], v[116:119]
	v_mfma_f32_16x16x32_bf16 v[112:115], v[182:185], v[190:193], v[112:115]
	v_mfma_f32_16x16x32_bf16 v[100:103], v[174:177], v[198:201], v[100:103]
	v_mfma_f32_16x16x32_bf16 v[96:99], v[182:185], v[198:201], v[96:99]
	v_mfma_f32_16x16x32_bf16 v[84:87], v[174:177], v[206:209], v[84:87]
	v_mfma_f32_16x16x32_bf16 v[80:83], v[182:185], v[206:209], v[80:83]
	v_mfma_f32_16x16x32_bf16 v[68:71], v[174:177], v[214:217], v[68:71]
	v_mfma_f32_16x16x32_bf16 v[64:67], v[182:185], v[214:217], v[64:67]
	s_setprio 0
	s_barrier
	s_add_i32 s46, s46, s73
	s_mov_b32 m0, s46
	ds_read_b128 v[186:189], v149 offset:49152
	ds_read_b128 v[190:193], v149 offset:50176
	ds_read_b128 v[194:197], v149 offset:51200
	ds_read_b128 v[198:201], v149 offset:52224
	ds_read_b128 v[202:205], v149 offset:53248
	ds_read_b128 v[206:209], v149 offset:54272
	ds_read_b128 v[210:213], v149 offset:55296
	ds_read_b128 v[214:217], v149 offset:56320
	s_add_u32 s98, s24, 0x80
	s_addc_u32 s99, s25, 0
	global_load_lds_dwordx4 v160, s[98:99]
	s_add_i32 m0, s46, 0x2000
	s_add_u32 s24, s24, 0x40080
	s_addc_u32 s25, s25, 0
	s_add_i32 s46, s47, s73
	global_load_lds_dwordx4 v132, s[98:99]
	s_mov_b32 m0, s46
	s_nop 0
	global_load_lds_dwordx4 v160, s[24:25]
	s_add_i32 m0, s46, 0x2000
	s_nop 0
	global_load_lds_dwordx4 v132, s[24:25]
	s_mov_b32 m0, s90
	s_nop 0
	s_add_u32 s98, s62, 0xfffc0080
	s_addc_u32 s99, s63, -1
	global_load_lds_dwordx4 v128, s[98:99]
	s_mov_b32 m0, s91
	s_nop 0
	global_load_lds_dwordx4 v130, s[98:99]
	s_waitcnt vmcnt(8)
	s_waitcnt lgkmcnt(0)
	s_barrier
	s_setprio 1
	s_waitcnt lgkmcnt(0)
	v_mfma_f32_16x16x32_bf16 v[60:63], v[138:141], v[186:189], v[60:63]
	v_mfma_f32_16x16x32_bf16 v[56:59], v[150:153], v[186:189], v[56:59]
	v_mfma_f32_16x16x32_bf16 v[44:47], v[138:141], v[194:197], v[44:47]
	v_mfma_f32_16x16x32_bf16 v[40:43], v[150:153], v[194:197], v[40:43]
	v_mfma_f32_16x16x32_bf16 v[28:31], v[138:141], v[202:205], v[28:31]
	v_mfma_f32_16x16x32_bf16 v[24:27], v[150:153], v[202:205], v[24:27]
	v_mfma_f32_16x16x32_bf16 v[12:15], v[138:141], v[210:213], v[12:15]
	v_mfma_f32_16x16x32_bf16 v[8:11], v[150:153], v[210:213], v[8:11]
	v_mfma_f32_16x16x32_bf16 v[60:63], v[142:145], v[190:193], v[60:63]
	v_mfma_f32_16x16x32_bf16 v[56:59], v[154:157], v[190:193], v[56:59]
	v_mfma_f32_16x16x32_bf16 v[44:47], v[142:145], v[198:201], v[44:47]
	v_mfma_f32_16x16x32_bf16 v[40:43], v[154:157], v[198:201], v[40:43]
	v_mfma_f32_16x16x32_bf16 v[28:31], v[142:145], v[206:209], v[28:31]
	v_mfma_f32_16x16x32_bf16 v[24:27], v[154:157], v[206:209], v[24:27]
	v_mfma_f32_16x16x32_bf16 v[12:15], v[142:145], v[214:217], v[12:15]
	v_mfma_f32_16x16x32_bf16 v[8:11], v[154:157], v[214:217], v[8:11]
	s_setprio 0
	s_setprio 1
	v_mfma_f32_16x16x32_bf16 v[52:55], v[170:173], v[186:189], v[52:55]
	v_mfma_f32_16x16x32_bf16 v[48:51], v[178:181], v[186:189], v[48:51]
	v_mfma_f32_16x16x32_bf16 v[36:39], v[170:173], v[194:197], v[36:39]
	v_mfma_f32_16x16x32_bf16 v[32:35], v[178:181], v[194:197], v[32:35]
	v_mfma_f32_16x16x32_bf16 v[20:23], v[170:173], v[202:205], v[20:23]
	v_mfma_f32_16x16x32_bf16 v[16:19], v[178:181], v[202:205], v[16:19]
	v_mfma_f32_16x16x32_bf16 v[4:7], v[170:173], v[210:213], v[4:7]
	v_mfma_f32_16x16x32_bf16 v[0:3], v[178:181], v[210:213], v[0:3]
	v_mfma_f32_16x16x32_bf16 v[52:55], v[174:177], v[190:193], v[52:55]
	v_mfma_f32_16x16x32_bf16 v[48:51], v[182:185], v[190:193], v[48:51]
	v_mfma_f32_16x16x32_bf16 v[36:39], v[174:177], v[198:201], v[36:39]
	v_mfma_f32_16x16x32_bf16 v[32:35], v[182:185], v[198:201], v[32:35]
	v_mfma_f32_16x16x32_bf16 v[20:23], v[174:177], v[206:209], v[20:23]
	v_mfma_f32_16x16x32_bf16 v[16:19], v[182:185], v[206:209], v[16:19]
	v_mfma_f32_16x16x32_bf16 v[4:7], v[174:177], v[214:217], v[4:7]
	v_mfma_f32_16x16x32_bf16 v[0:3], v[182:185], v[214:217], v[0:3]
	s_setprio 0
	s_barrier
	s_add_i32 s45, s45, 2
	s_add_u32 s60, s60, 0x100
	s_addc_u32 s61, s61, 0
	s_add_u32 s43, s43, 0x100
	s_addc_u32 s44, s44, 0
	s_cmp_gt_u32 s45, 13
	s_cbranch_scc0 .LBB0_211
	s_and_b64 vcc, exec, s[14:15]
	s_cbranch_vccz .LBB0_214
	s_barrier

; #define PG8_STAGE(bufoff, gbase, voff) do { _Pragma("unroll") for (int _i = 0; _i < 2; ++_i) \
;         __builtin_amdgcn_global_load_lds((const unsigned*)((const char*)(gbase) + (voff)[_i]), (LAS unsigned*)(lds + (bufoff) + ldsw + _i * 8192), 16, 0, 0); } while (0)
; #define PG8_LDA(dst, b, h) do { _Pragma("unroll") for (int m = 0; m < 4; ++m) _Pragma("unroll") for (int k = 0; k < 2; ++k) dst[m][k] = *(const LAS bf16x8*)(lds + PG8_SA(b, h) + aoff + m * 2048 + k * 1024); } while (0)
; #define PG8_LDB(dst, b, h) do { _Pragma("unroll") for (int n = 0; n < 2; ++n) _Pragma("unroll") for (int k = 0; k < 2; ++k) dst[n][k] = *(const LAS bf16x8*)(lds + PG8_SB(b, h) + boff + n * 2048 + k * 1024); } while (0)
; #define PG8_MMA(ai, bj, At, Bt) do { __builtin_amdgcn_s_setprio(1); _Pragma("unroll") for (int m = 0; m < 4; ++m) _Pragma("unroll") for (int n = 0; n < 2; ++n) _Pragma("unroll") for (int k = 0; k < 2; ++k) \
;         acc[ai][bj][m][n] = __builtin_amdgcn_mfma_f32_16x16x32_bf16(Bt[n][k], At[m][k], acc[ai][bj][m][n], 0, 0, 0); __builtin_amdgcn_s_setprio(0); } while (0)
; #define PG8_WAIT_V(n) asm volatile("s_waitcnt vmcnt(" #n ")" ::: "memory")
; #define PG8_WAIT_L(n) asm volatile("s_waitcnt lgkmcnt(" #n ")" ::: "memory")
; #define PG8_BAR __builtin_amdgcn_s_barrier()
; #define PG8_SCHED __builtin_amdgcn_sched_barrier(0)
; template <class Epi, class Sched, bool ALIGN_EPI = true, bool SP2 = true>
; __device__ __forceinline__ void gemm_phase(LAS unsigned char* lds, const Gemm g, const Sched& S, const Epi& E) {
;     ...
;             const bool last = (t == nt - 2);
;             const char* a1 = cA + (size_t)(t + 1) * kstep;
;             const char* a2 = last ? nA : cA + (size_t)(t + 2) * kstep; const char* b2 = last ? nB : cB + (size_t)(t + 2) * kstep;
;             const char* a3 = a2 + kstep; const char* b3 = b2 + kstep;
;             if constexpr (SP2) {
;             PG8_LDB(B0, 0, 0); PG8_LDB(B1, 0, 1); PG8_SCHED; PG8_LDA(At, 0, 0); PG8_STAGE(PG8_SA(1, 1), a1 + hstep, voffA);
;             PG8_WAIT_V(8); PG8_WAIT_L(0); PG8_BAR; PG8_MMA(0, 0, At, B0); PG8_MMA(0, 1, At, B1); PG8_BAR; PG8_SCHED;
;             PG8_LDA(At, 0, 1); PG8_STAGE(PG8_SB(0, 0), b2, voffB); PG8_STAGE(PG8_SB(0, 1), b2 + hstep, voffB); PG8_STAGE(PG8_SA(0, 0), a2, voffA);
;             PG8_WAIT_V(8); PG8_WAIT_L(0); PG8_BAR; PG8_MMA(1, 0, At, B0); PG8_MMA(1, 1, At, B1); PG8_BAR; PG8_SCHED;
.LBB0_237:
	s_add_u32 s24, s54, 0xfffc0080
	s_addc_u32 s25, s55, -1
	s_add_i32 s46, 0, 0x10000
	s_cmp_eq_u32 s92, 12
	s_cselect_b32 s61, s2, s25
	s_cselect_b32 s60, s3, s24
	v_add_u32_e32 v142, s46, v145
	s_cselect_b32 s25, s17, s91
	s_cselect_b32 s24, s19, s90
	s_add_i32 s47, 0, 0x14000
	ds_read_b128 v[138:141], v142
	ds_read_b128 v[148:151], v142 offset:1024
	ds_read_b128 v[152:155], v142 offset:2048
	ds_read_b128 v[156:159], v142 offset:3072
	v_add_u32_e32 v142, s47, v145
	ds_read_b128 v[170:173], v142
	ds_read_b128 v[174:177], v142 offset:1024
	ds_read_b128 v[178:181], v142 offset:2048
	ds_read_b128 v[182:185], v142 offset:3072
	s_add_i32 m0, s44, 0xc000
	ds_read_b128 v[186:189], v147
	ds_read_b128 v[190:193], v147 offset:1024
	ds_read_b128 v[194:197], v147 offset:2048
	ds_read_b128 v[198:201], v147 offset:3072
	ds_read_b128 v[202:205], v147 offset:4096
	ds_read_b128 v[206:209], v147 offset:5120
	ds_read_b128 v[210:213], v147 offset:6144
	ds_read_b128 v[214:217], v147 offset:7168
	global_load_lds_dwordx4 v134, s[54:55]
	s_add_i32 m0, s44, 0xe000
	s_nop 0
	global_load_lds_dwordx4 v136, s[54:55]
	s_waitcnt vmcnt(8)
	s_waitcnt lgkmcnt(0)
	s_barrier
	s_setprio 1
	s_waitcnt lgkmcnt(0)
	v_mfma_f32_16x16x32_bf16 v[124:127], v[138:141], v[186:189], v[124:127]
	v_mfma_f32_16x16x32_bf16 v[120:123], v[152:155], v[186:189], v[120:123]
	v_mfma_f32_16x16x32_bf16 v[108:111], v[138:141], v[194:197], v[108:111]
	v_mfma_f32_16x16x32_bf16 v[104:107], v[152:155], v[194:197], v[104:107]
	v_mfma_f32_16x16x32_bf16 v[92:95], v[138:141], v[202:205], v[92:95]
	v_mfma_f32_16x16x32_bf16 v[88:91], v[152:155], v[202:205], v[88:91]
	v_mfma_f32_16x16x32_bf16 v[76:79], v[138:141], v[210:213], v[76:79]
	v_mfma_f32_16x16x32_bf16 v[72:75], v[152:155], v[210:213], v[72:75]
	v_mfma_f32_16x16x32_bf16 v[124:127], v[148:151], v[190:193], v[124:127]
	v_mfma_f32_16x16x32_bf16 v[120:123], v[156:159], v[190:193], v[120:123]
	v_mfma_f32_16x16x32_bf16 v[108:111], v[148:151], v[198:201], v[108:111]
	v_mfma_f32_16x16x32_bf16 v[104:107], v[156:159], v[198:201], v[104:107]
	v_mfma_f32_16x16x32_bf16 v[92:95], v[148:151], v[206:209], v[92:95]
	v_mfma_f32_16x16x32_bf16 v[88:91], v[156:159], v[206:209], v[88:91]
	v_mfma_f32_16x16x32_bf16 v[76:79], v[148:151], v[214:217], v[76:79]
	v_mfma_f32_16x16x32_bf16 v[72:75], v[156:159], v[214:217], v[72:75]
	s_setprio 0
	s_setprio 1
	v_mfma_f32_16x16x32_bf16 v[116:119], v[170:173], v[186:189], v[116:119]
	v_mfma_f32_16x16x32_bf16 v[112:115], v[178:181], v[186:189], v[112:115]
	v_mfma_f32_16x16x32_bf16 v[100:103], v[170:173], v[194:197], v[100:103]
	v_mfma_f32_16x16x32_bf16 v[96:99], v[178:181], v[194:197], v[96:99]
	v_mfma_f32_16x16x32_bf16 v[84:87], v[170:173], v[202:205], v[84:87]
	v_mfma_f32_16x16x32_bf16 v[80:83], v[178:181], v[202:205], v[80:83]
	v_mfma_f32_16x16x32_bf16 v[68:71], v[170:173], v[210:213], v[68:71]
	v_mfma_f32_16x16x32_bf16 v[64:67], v[178:181], v[210:213], v[64:67]
	v_mfma_f32_16x16x32_bf16 v[116:119], v[174:177], v[190:193], v[116:119]
	v_mfma_f32_16x16x32_bf16 v[112:115], v[182:185], v[190:193], v[112:115]
	v_mfma_f32_16x16x32_bf16 v[100:103], v[174:177], v[198:201], v[100:103]
	v_mfma_f32_16x16x32_bf16 v[96:99], v[182:185], v[198:201], v[96:99]
	v_mfma_f32_16x16x32_bf16 v[84:87], v[174:177], v[206:209], v[84:87]
	v_mfma_f32_16x16x32_bf16 v[80:83], v[182:185], v[206:209], v[80:83]
	v_mfma_f32_16x16x32_bf16 v[68:71], v[174:177], v[214:217], v[68:71]
	v_mfma_f32_16x16x32_bf16 v[64:67], v[182:185], v[214:217], v[64:67]
	s_setprio 0
	s_barrier
	s_add_i32 s46, s46, s43
	s_mov_b32 m0, s46
	ds_read_b128 v[186:189], v147 offset:16384
	ds_read_b128 v[190:193], v147 offset:17408
	ds_read_b128 v[194:197], v147 offset:18432
	ds_read_b128 v[198:201], v147 offset:19456
	ds_read_b128 v[202:205], v147 offset:20480
	ds_read_b128 v[206:209], v147 offset:21504
	ds_read_b128 v[210:213], v147 offset:22528
	ds_read_b128 v[214:217], v147 offset:23552
	global_load_lds_dwordx4 v160, s[24:25]
	s_add_i32 m0, s46, 0x2000
	s_add_u32 s94, s24, 0x40000
	s_addc_u32 s95, s25, 0
	s_add_i32 s46, s47, s43
	global_load_lds_dwordx4 v128, s[24:25]
	s_mov_b32 m0, s46
	s_nop 0
	global_load_lds_dwordx4 v160, s[94:95]
	s_add_i32 m0, s46, 0x2000
	s_nop 0
	global_load_lds_dwordx4 v128, s[94:95]
	s_mov_b32 m0, s44
	s_nop 0
	global_load_lds_dwordx4 v132, s[60:61]
	s_mov_b32 m0, s45
	s_nop 0
	global_load_lds_dwordx4 v130, s[60:61]
	s_waitcnt vmcnt(8)
	s_waitcnt lgkmcnt(0)
	s_barrier
	s_setprio 1
	s_waitcnt lgkmcnt(0)
	v_mfma_f32_16x16x32_bf16 v[60:63], v[138:141], v[186:189], v[60:63]
	v_mfma_f32_16x16x32_bf16 v[56:59], v[152:155], v[186:189], v[56:59]
	v_mfma_f32_16x16x32_bf16 v[44:47], v[138:141], v[194:197], v[44:47]
	v_mfma_f32_16x16x32_bf16 v[40:43], v[152:155], v[194:197], v[40:43]
	v_mfma_f32_16x16x32_bf16 v[28:31], v[138:141], v[202:205], v[28:31]
	v_mfma_f32_16x16x32_bf16 v[24:27], v[152:155], v[202:205], v[24:27]
	v_mfma_f32_16x16x32_bf16 v[12:15], v[138:141], v[210:213], v[12:15]
	v_mfma_f32_16x16x32_bf16 v[8:11], v[152:155], v[210:213], v[8:11]
	v_mfma_f32_16x16x32_bf16 v[60:63], v[148:151], v[190:193], v[60:63]
	v_mfma_f32_16x16x32_bf16 v[56:59], v[156:159], v[190:193], v[56:59]
	v_mfma_f32_16x16x32_bf16 v[44:47], v[148:151], v[198:201], v[44:47]
	v_mfma_f32_16x16x32_bf16 v[40:43], v[156:159], v[198:201], v[40:43]
	v_mfma_f32_16x16x32_bf16 v[28:31], v[148:151], v[206:209], v[28:31]
	v_mfma_f32_16x16x32_bf16 v[24:27], v[156:159], v[206:209], v[24:27]
	v_mfma_f32_16x16x32_bf16 v[12:15], v[148:151], v[214:217], v[12:15]
	v_mfma_f32_16x16x32_bf16 v[8:11], v[156:159], v[214:217], v[8:11]
	s_setprio 0
	s_setprio 1
	v_mfma_f32_16x16x32_bf16 v[52:55], v[170:173], v[186:189], v[52:55]
	v_mfma_f32_16x16x32_bf16 v[48:51], v[178:181], v[186:189], v[48:51]
	v_mfma_f32_16x16x32_bf16 v[36:39], v[170:173], v[194:197], v[36:39]
	v_mfma_f32_16x16x32_bf16 v[32:35], v[178:181], v[194:197], v[32:35]
	v_mfma_f32_16x16x32_bf16 v[20:23], v[170:173], v[202:205], v[20:23]
	v_mfma_f32_16x16x32_bf16 v[16:19], v[178:181], v[202:205], v[16:19]
	v_mfma_f32_16x16x32_bf16 v[4:7], v[170:173], v[210:213], v[4:7]
	v_mfma_f32_16x16x32_bf16 v[0:3], v[178:181], v[210:213], v[0:3]
	v_mfma_f32_16x16x32_bf16 v[52:55], v[174:177], v[190:193], v[52:55]
	v_mfma_f32_16x16x32_bf16 v[48:51], v[182:185], v[190:193], v[48:51]
	v_mfma_f32_16x16x32_bf16 v[36:39], v[174:177], v[198:201], v[36:39]
	v_mfma_f32_16x16x32_bf16 v[32:35], v[182:185], v[198:201], v[32:35]
	v_mfma_f32_16x16x32_bf16 v[20:23], v[174:177], v[206:209], v[20:23]
	v_mfma_f32_16x16x32_bf16 v[16:19], v[182:185], v[206:209], v[16:19]
	v_mfma_f32_16x16x32_bf16 v[4:7], v[174:177], v[214:217], v[4:7]
	v_mfma_f32_16x16x32_bf16 v[0:3], v[182:185], v[214:217], v[0:3]
	s_setprio 0
	s_barrier
; #define PG8_STAGE(bufoff, gbase, voff) do { _Pragma("unroll") for (int _i = 0; _i < 2; ++_i) \
;         __builtin_amdgcn_global_load_lds((const unsigned*)((const char*)(gbase) + (voff)[_i]), (LAS unsigned*)(lds + (bufoff) + ldsw + _i * 8192), 16, 0, 0); } while (0)
; #define PG8_LDA(dst, b, h) do { _Pragma("unroll") for (int m = 0; m < 4; ++m) _Pragma("unroll") for (int k = 0; k < 2; ++k) dst[m][k] = *(const LAS bf16x8*)(lds + PG8_SA(b, h) + aoff + m * 2048 + k * 1024); } while (0)
; #define PG8_LDB(dst, b, h) do { _Pragma("unroll") for (int n = 0; n < 2; ++n) _Pragma("unroll") for (int k = 0; k < 2; ++k) dst[n][k] = *(const LAS bf16x8*)(lds + PG8_SB(b, h) + boff + n * 2048 + k * 1024); } while (0)
; #define PG8_MMA(ai, bj, At, Bt) do { __builtin_amdgcn_s_setprio(1); _Pragma("unroll") for (int m = 0; m < 4; ++m) _Pragma("unroll") for (int n = 0; n < 2; ++n) _Pragma("unroll") for (int k = 0; k < 2; ++k) \
;         acc[ai][bj][m][n] = __builtin_amdgcn_mfma_f32_16x16x32_bf16(Bt[n][k], At[m][k], acc[ai][bj][m][n], 0, 0, 0); __builtin_amdgcn_s_setprio(0); } while (0)
; #define PG8_WAIT_V(n) asm volatile("s_waitcnt vmcnt(" #n ")" ::: "memory")
; #define PG8_WAIT_L(n) asm volatile("s_waitcnt lgkmcnt(" #n ")" ::: "memory")
; #define PG8_BAR __builtin_amdgcn_s_barrier()
; #define PG8_SCHED __builtin_amdgcn_sched_barrier(0)
; template <class Epi, class Sched, bool ALIGN_EPI = true, bool SP2 = true>
; __device__ __forceinline__ void gemm_phase(LAS unsigned char* lds, const Gemm g, const Sched& S, const Epi& E) {
;     ...
;         for (int t = 0; t < nt; t += 2) {
;     ...
;             PG8_LDB(B0, 1, 0); PG8_LDB(B1, 1, 1); PG8_SCHED; PG8_LDA(At, 1, 0); PG8_STAGE(PG8_SA(0, 1), a2 + hstep, voffA);
;             PG8_WAIT_V(8); PG8_WAIT_L(0); PG8_BAR; PG8_MMA(0, 0, At, B0); PG8_MMA(0, 1, At, B1); PG8_BAR; PG8_SCHED;
;             PG8_LDA(At, 1, 1); PG8_STAGE(PG8_SB(1, 0), b3, voffB); PG8_STAGE(PG8_SB(1, 1), b3 + hstep, voffB); PG8_STAGE(PG8_SA(1, 0), a3, voffA);
;             PG8_WAIT_V(8); PG8_WAIT_L(0); PG8_BAR; PG8_MMA(1, 0, At, B0); PG8_MMA(1, 1, At, B1); PG8_BAR; PG8_SCHED;
	s_add_i32 s46, 0, 0x18000
	s_add_i32 s47, 0, 0x1c000
	v_add_u32_e32 v156, s46, v145
	v_add_u32_e32 v182, s47, v145
	ds_read_b128 v[138:141], v156
	ds_read_b128 v[148:151], v156 offset:1024
	ds_read_b128 v[152:155], v156 offset:2048
	ds_read_b128 v[156:159], v156 offset:3072
	ds_read_b128 v[170:173], v182
	ds_read_b128 v[174:177], v182 offset:1024
	ds_read_b128 v[178:181], v182 offset:2048
	ds_read_b128 v[182:185], v182 offset:3072
	s_add_u32 s60, s60, 0x40000
	s_addc_u32 s61, s61, 0
	s_mov_b32 m0, s62
	ds_read_b128 v[186:189], v147 offset:32768
	ds_read_b128 v[190:193], v147 offset:33792
	ds_read_b128 v[194:197], v147 offset:34816
	ds_read_b128 v[198:201], v147 offset:35840
	ds_read_b128 v[202:205], v147 offset:36864
	ds_read_b128 v[206:209], v147 offset:37888
	ds_read_b128 v[210:213], v147 offset:38912
	ds_read_b128 v[214:217], v147 offset:39936
	global_load_lds_dwordx4 v132, s[60:61]
	s_mov_b32 m0, s63
	s_nop 0
	global_load_lds_dwordx4 v130, s[60:61]
	s_waitcnt vmcnt(8)
	s_waitcnt lgkmcnt(0)
	s_barrier
	s_setprio 1
	s_waitcnt lgkmcnt(0)
	v_mfma_f32_16x16x32_bf16 v[124:127], v[138:141], v[186:189], v[124:127]
	v_mfma_f32_16x16x32_bf16 v[120:123], v[152:155], v[186:189], v[120:123]
	v_mfma_f32_16x16x32_bf16 v[108:111], v[138:141], v[194:197], v[108:111]
	v_mfma_f32_16x16x32_bf16 v[104:107], v[152:155], v[194:197], v[104:107]
	v_mfma_f32_16x16x32_bf16 v[92:95], v[138:141], v[202:205], v[92:95]
	v_mfma_f32_16x16x32_bf16 v[88:91], v[152:155], v[202:205], v[88:91]
	v_mfma_f32_16x16x32_bf16 v[76:79], v[138:141], v[210:213], v[76:79]
	v_mfma_f32_16x16x32_bf16 v[72:75], v[152:155], v[210:213], v[72:75]
	v_mfma_f32_16x16x32_bf16 v[124:127], v[148:151], v[190:193], v[124:127]
	v_mfma_f32_16x16x32_bf16 v[120:123], v[156:159], v[190:193], v[120:123]
	v_mfma_f32_16x16x32_bf16 v[108:111], v[148:151], v[198:201], v[108:111]
	v_mfma_f32_16x16x32_bf16 v[104:107], v[156:159], v[198:201], v[104:107]
	v_mfma_f32_16x16x32_bf16 v[92:95], v[148:151], v[206:209], v[92:95]
	v_mfma_f32_16x16x32_bf16 v[88:91], v[156:159], v[206:209], v[88:91]
	v_mfma_f32_16x16x32_bf16 v[76:79], v[148:151], v[214:217], v[76:79]
	v_mfma_f32_16x16x32_bf16 v[72:75], v[156:159], v[214:217], v[72:75]
	s_setprio 0
	s_setprio 1
	v_mfma_f32_16x16x32_bf16 v[116:119], v[170:173], v[186:189], v[116:119]
	v_mfma_f32_16x16x32_bf16 v[112:115], v[178:181], v[186:189], v[112:115]
	v_mfma_f32_16x16x32_bf16 v[100:103], v[170:173], v[194:197], v[100:103]
	v_mfma_f32_16x16x32_bf16 v[96:99], v[178:181], v[194:197], v[96:99]
	v_mfma_f32_16x16x32_bf16 v[84:87], v[170:173], v[202:205], v[84:87]
	v_mfma_f32_16x16x32_bf16 v[80:83], v[178:181], v[202:205], v[80:83]
	v_mfma_f32_16x16x32_bf16 v[68:71], v[170:173], v[210:213], v[68:71]
	v_mfma_f32_16x16x32_bf16 v[64:67], v[178:181], v[210:213], v[64:67]
	v_mfma_f32_16x16x32_bf16 v[116:119], v[174:177], v[190:193], v[116:119]
	v_mfma_f32_16x16x32_bf16 v[112:115], v[182:185], v[190:193], v[112:115]
	v_mfma_f32_16x16x32_bf16 v[100:103], v[174:177], v[198:201], v[100:103]
	v_mfma_f32_16x16x32_bf16 v[96:99], v[182:185], v[198:201], v[96:99]
	v_mfma_f32_16x16x32_bf16 v[84:87], v[174:177], v[206:209], v[84:87]
	v_mfma_f32_16x16x32_bf16 v[80:83], v[182:185], v[206:209], v[80:83]
	v_mfma_f32_16x16x32_bf16 v[68:71], v[174:177], v[214:217], v[68:71]
	v_mfma_f32_16x16x32_bf16 v[64:67], v[182:185], v[214:217], v[64:67]
	s_setprio 0
	s_barrier
	s_add_i32 s46, s46, s43
	s_mov_b32 m0, s46
	ds_read_b128 v[186:189], v147 offset:49152
	ds_read_b128 v[190:193], v147 offset:50176
	ds_read_b128 v[194:197], v147 offset:51200
	ds_read_b128 v[198:201], v147 offset:52224
	ds_read_b128 v[202:205], v147 offset:53248
	ds_read_b128 v[206:209], v147 offset:54272
	ds_read_b128 v[210:213], v147 offset:55296
	ds_read_b128 v[214:217], v147 offset:56320
	s_add_u32 s98, s24, 0x80
	s_addc_u32 s99, s25, 0
	global_load_lds_dwordx4 v160, s[98:99]
	s_add_i32 m0, s46, 0x2000
	s_add_u32 s24, s24, 0x40080
	s_addc_u32 s25, s25, 0
	s_add_i32 s46, s47, s43
	global_load_lds_dwordx4 v128, s[98:99]
	s_mov_b32 m0, s46
	s_nop 0
	global_load_lds_dwordx4 v160, s[24:25]
	s_add_i32 m0, s46, 0x2000
	s_nop 0
	global_load_lds_dwordx4 v128, s[24:25]
	s_mov_b32 m0, s67
	s_nop 0
	s_add_u32 s98, s60, 0xfffc0080
	s_addc_u32 s99, s61, -1
	global_load_lds_dwordx4 v132, s[98:99]
	s_mov_b32 m0, s72
	s_nop 0
	global_load_lds_dwordx4 v130, s[98:99]
	s_waitcnt vmcnt(8)
	s_waitcnt lgkmcnt(0)
	s_barrier
	s_setprio 1
	s_waitcnt lgkmcnt(0)
	v_mfma_f32_16x16x32_bf16 v[60:63], v[138:141], v[186:189], v[60:63]
	v_mfma_f32_16x16x32_bf16 v[56:59], v[152:155], v[186:189], v[56:59]
	v_mfma_f32_16x16x32_bf16 v[44:47], v[138:141], v[194:197], v[44:47]
	v_mfma_f32_16x16x32_bf16 v[40:43], v[152:155], v[194:197], v[40:43]
	v_mfma_f32_16x16x32_bf16 v[28:31], v[138:141], v[202:205], v[28:31]
	v_mfma_f32_16x16x32_bf16 v[24:27], v[152:155], v[202:205], v[24:27]
	v_mfma_f32_16x16x32_bf16 v[12:15], v[138:141], v[210:213], v[12:15]
	v_mfma_f32_16x16x32_bf16 v[8:11], v[152:155], v[210:213], v[8:11]
	v_mfma_f32_16x16x32_bf16 v[60:63], v[148:151], v[190:193], v[60:63]
	v_mfma_f32_16x16x32_bf16 v[56:59], v[156:159], v[190:193], v[56:59]
	v_mfma_f32_16x16x32_bf16 v[44:47], v[148:151], v[198:201], v[44:47]
	v_mfma_f32_16x16x32_bf16 v[40:43], v[156:159], v[198:201], v[40:43]
	v_mfma_f32_16x16x32_bf16 v[28:31], v[148:151], v[206:209], v[28:31]
	v_mfma_f32_16x16x32_bf16 v[24:27], v[156:159], v[206:209], v[24:27]
	v_mfma_f32_16x16x32_bf16 v[12:15], v[148:151], v[214:217], v[12:15]
	v_mfma_f32_16x16x32_bf16 v[8:11], v[156:159], v[214:217], v[8:11]
	s_setprio 0
	s_setprio 1
	v_mfma_f32_16x16x32_bf16 v[52:55], v[170:173], v[186:189], v[52:55]
	v_mfma_f32_16x16x32_bf16 v[48:51], v[178:181], v[186:189], v[48:51]
	v_mfma_f32_16x16x32_bf16 v[36:39], v[170:173], v[194:197], v[36:39]
	v_mfma_f32_16x16x32_bf16 v[32:35], v[178:181], v[194:197], v[32:35]
	v_mfma_f32_16x16x32_bf16 v[20:23], v[170:173], v[202:205], v[20:23]
	v_mfma_f32_16x16x32_bf16 v[16:19], v[178:181], v[202:205], v[16:19]
	v_mfma_f32_16x16x32_bf16 v[4:7], v[170:173], v[210:213], v[4:7]
	v_mfma_f32_16x16x32_bf16 v[0:3], v[178:181], v[210:213], v[0:3]
	v_mfma_f32_16x16x32_bf16 v[52:55], v[174:177], v[190:193], v[52:55]
	v_mfma_f32_16x16x32_bf16 v[48:51], v[182:185], v[190:193], v[48:51]
	v_mfma_f32_16x16x32_bf16 v[36:39], v[174:177], v[198:201], v[36:39]
	v_mfma_f32_16x16x32_bf16 v[32:35], v[182:185], v[198:201], v[32:35]
	v_mfma_f32_16x16x32_bf16 v[20:23], v[174:177], v[206:209], v[20:23]
	v_mfma_f32_16x16x32_bf16 v[16:19], v[182:185], v[206:209], v[16:19]
	v_mfma_f32_16x16x32_bf16 v[4:7], v[174:177], v[214:217], v[4:7]
	v_mfma_f32_16x16x32_bf16 v[0:3], v[182:185], v[214:217], v[0:3]
	s_setprio 0
	s_barrier
	s_add_i32 s92, s92, 2
	s_add_u32 s54, s54, 0x100
	s_addc_u32 s55, s55, 0
	s_add_u32 s90, s90, 0x100
	s_addc_u32 s91, s91, 0
	s_cmp_gt_u32 s92, 13
	s_cbranch_scc0 .LBB0_237
	s_and_b64 vcc, exec, s[14:15]
	s_cbranch_vccz .LBB0_240
	s_barrier

; #define PG8_STAGE(bufoff, gbase, voff) do { _Pragma("unroll") for (int _i = 0; _i < 2; ++_i) \
;         __builtin_amdgcn_global_load_lds((const unsigned*)((const char*)(gbase) + (voff)[_i]), (LAS unsigned*)(lds + (bufoff) + ldsw + _i * 8192), 16, 0, 0); } while (0)
; #define PG8_LDA(dst, b, h) do { _Pragma("unroll") for (int m = 0; m < 4; ++m) _Pragma("unroll") for (int k = 0; k < 2; ++k) dst[m][k] = *(const LAS bf16x8*)(lds + PG8_SA(b, h) + aoff + m * 2048 + k * 1024); } while (0)
; #define PG8_LDB(dst, b, h) do { _Pragma("unroll") for (int n = 0; n < 2; ++n) _Pragma("unroll") for (int k = 0; k < 2; ++k) dst[n][k] = *(const LAS bf16x8*)(lds + PG8_SB(b, h) + boff + n * 2048 + k * 1024); } while (0)
; #define PG8_MMA(ai, bj, At, Bt) do { __builtin_amdgcn_s_setprio(1); _Pragma("unroll") for (int m = 0; m < 4; ++m) _Pragma("unroll") for (int n = 0; n < 2; ++n) _Pragma("unroll") for (int k = 0; k < 2; ++k) \
;         acc[ai][bj][m][n] = __builtin_amdgcn_mfma_f32_16x16x32_bf16(Bt[n][k], At[m][k], acc[ai][bj][m][n], 0, 0, 0); __builtin_amdgcn_s_setprio(0); } while (0)
; #define PG8_WAIT_V(n) asm volatile("s_waitcnt vmcnt(" #n ")" ::: "memory")
; #define PG8_WAIT_L(n) asm volatile("s_waitcnt lgkmcnt(" #n ")" ::: "memory")
; #define PG8_BAR __builtin_amdgcn_s_barrier()
; #define PG8_SCHED __builtin_amdgcn_sched_barrier(0)
; template <class Epi, class Sched, bool ALIGN_EPI = true, bool SP2 = true>
; __device__ __forceinline__ void gemm_phase(LAS unsigned char* lds, const Gemm g, const Sched& S, const Epi& E) {
;     ...
;             const bool last = (t == nt - 2);
;             const char* a1 = cA + (size_t)(t + 1) * kstep;
;             const char* a2 = last ? nA : cA + (size_t)(t + 2) * kstep; const char* b2 = last ? nB : cB + (size_t)(t + 2) * kstep;
;             const char* a3 = a2 + kstep; const char* b3 = b2 + kstep;
;             if constexpr (SP2) {
;             PG8_LDB(B0, 0, 0); PG8_LDB(B1, 0, 1); PG8_SCHED; PG8_LDA(At, 0, 0); PG8_STAGE(PG8_SA(1, 1), a1 + hstep, voffA);
;             PG8_WAIT_V(8); PG8_WAIT_L(0); PG8_BAR; PG8_MMA(0, 0, At, B0); PG8_MMA(0, 1, At, B1); PG8_BAR; PG8_SCHED;
;             PG8_LDA(At, 0, 1); PG8_STAGE(PG8_SB(0, 0), b2, voffB); PG8_STAGE(PG8_SB(0, 1), b2 + hstep, voffB); PG8_STAGE(PG8_SA(0, 0), a2, voffA);
;             PG8_WAIT_V(8); PG8_WAIT_L(0); PG8_BAR; PG8_MMA(1, 0, At, B0); PG8_MMA(1, 1, At, B1); PG8_BAR; PG8_SCHED;
.LBB0_354:
	s_add_u32 s24, s62, 0xfff80080
	s_addc_u32 s25, s63, -1
	s_add_i32 s43, 0, 0x10000
	s_cmp_eq_u32 s42, 28
	s_cselect_b32 s83, s2, s25
	s_cselect_b32 s82, s3, s24
	s_cselect_b32 s25, s7, s19
	s_cselect_b32 s24, s9, s18
	s_add_i32 s46, 0, 0x14000
	v_add_u32_e32 v150, s43, v155
	v_add_u32_e32 v158, s46, v155
	ds_read_b128 v[138:141], v150
	ds_read_b128 v[142:145], v150 offset:1024
	ds_read_b128 v[146:149], v150 offset:2048
	ds_read_b128 v[150:153], v150 offset:3072
	ds_read_b128 v[170:173], v158
	ds_read_b128 v[174:177], v158 offset:1024
	ds_read_b128 v[178:181], v158 offset:2048
	ds_read_b128 v[182:185], v158 offset:3072
	s_add_i32 m0, s16, 0xc000
	ds_read_b128 v[186:189], v157
	ds_read_b128 v[190:193], v157 offset:1024
	ds_read_b128 v[194:197], v157 offset:2048
	ds_read_b128 v[198:201], v157 offset:3072
	ds_read_b128 v[202:205], v157 offset:4096
	ds_read_b128 v[206:209], v157 offset:5120
	ds_read_b128 v[210:213], v157 offset:6144
	ds_read_b128 v[214:217], v157 offset:7168
	global_load_lds_dwordx4 v134, s[62:63]
	s_add_i32 m0, s16, 0xe000
	s_nop 0
	global_load_lds_dwordx4 v136, s[62:63]
	s_waitcnt vmcnt(8)
	s_waitcnt lgkmcnt(0)
	s_barrier
	s_setprio 1
	s_waitcnt lgkmcnt(0)
	v_mfma_f32_16x16x32_bf16 v[124:127], v[138:141], v[186:189], v[124:127]
	v_mfma_f32_16x16x32_bf16 v[120:123], v[146:149], v[186:189], v[120:123]
	v_mfma_f32_16x16x32_bf16 v[108:111], v[138:141], v[194:197], v[108:111]
	v_mfma_f32_16x16x32_bf16 v[104:107], v[146:149], v[194:197], v[104:107]
	v_mfma_f32_16x16x32_bf16 v[92:95], v[138:141], v[202:205], v[92:95]
	v_mfma_f32_16x16x32_bf16 v[88:91], v[146:149], v[202:205], v[88:91]
	v_mfma_f32_16x16x32_bf16 v[76:79], v[138:141], v[210:213], v[76:79]
	v_mfma_f32_16x16x32_bf16 v[72:75], v[146:149], v[210:213], v[72:75]
	v_mfma_f32_16x16x32_bf16 v[124:127], v[142:145], v[190:193], v[124:127]
	v_mfma_f32_16x16x32_bf16 v[120:123], v[150:153], v[190:193], v[120:123]
	v_mfma_f32_16x16x32_bf16 v[108:111], v[142:145], v[198:201], v[108:111]
	v_mfma_f32_16x16x32_bf16 v[104:107], v[150:153], v[198:201], v[104:107]
	v_mfma_f32_16x16x32_bf16 v[92:95], v[142:145], v[206:209], v[92:95]
	v_mfma_f32_16x16x32_bf16 v[88:91], v[150:153], v[206:209], v[88:91]
	v_mfma_f32_16x16x32_bf16 v[76:79], v[142:145], v[214:217], v[76:79]
	v_mfma_f32_16x16x32_bf16 v[72:75], v[150:153], v[214:217], v[72:75]
	s_setprio 0
	s_setprio 1
	v_mfma_f32_16x16x32_bf16 v[116:119], v[170:173], v[186:189], v[116:119]
	v_mfma_f32_16x16x32_bf16 v[112:115], v[178:181], v[186:189], v[112:115]
	v_mfma_f32_16x16x32_bf16 v[100:103], v[170:173], v[194:197], v[100:103]
	v_mfma_f32_16x16x32_bf16 v[96:99], v[178:181], v[194:197], v[96:99]
	v_mfma_f32_16x16x32_bf16 v[84:87], v[170:173], v[202:205], v[84:87]
	v_mfma_f32_16x16x32_bf16 v[80:83], v[178:181], v[202:205], v[80:83]
	v_mfma_f32_16x16x32_bf16 v[68:71], v[170:173], v[210:213], v[68:71]
	v_mfma_f32_16x16x32_bf16 v[64:67], v[178:181], v[210:213], v[64:67]
	v_mfma_f32_16x16x32_bf16 v[116:119], v[174:177], v[190:193], v[116:119]
	v_mfma_f32_16x16x32_bf16 v[112:115], v[182:185], v[190:193], v[112:115]
	v_mfma_f32_16x16x32_bf16 v[100:103], v[174:177], v[198:201], v[100:103]
	v_mfma_f32_16x16x32_bf16 v[96:99], v[182:185], v[198:201], v[96:99]
	v_mfma_f32_16x16x32_bf16 v[84:87], v[174:177], v[206:209], v[84:87]
	v_mfma_f32_16x16x32_bf16 v[80:83], v[182:185], v[206:209], v[80:83]
	v_mfma_f32_16x16x32_bf16 v[68:71], v[174:177], v[214:217], v[68:71]
	v_mfma_f32_16x16x32_bf16 v[64:67], v[182:185], v[214:217], v[64:67]
	s_setprio 0
	s_barrier
	s_add_i32 s43, s43, s41
	s_mov_b32 m0, s43
	ds_read_b128 v[186:189], v157 offset:16384
	ds_read_b128 v[190:193], v157 offset:17408
	ds_read_b128 v[194:197], v157 offset:18432
	ds_read_b128 v[198:201], v157 offset:19456
	ds_read_b128 v[202:205], v157 offset:20480
	ds_read_b128 v[206:209], v157 offset:21504
	ds_read_b128 v[210:213], v157 offset:22528
	ds_read_b128 v[214:217], v157 offset:23552
	global_load_lds_dwordx4 v160, s[24:25]
	s_add_i32 m0, s43, 0x2000
	s_add_u32 s44, s24, 0x80000
	s_addc_u32 s45, s25, 0
	s_add_i32 s43, s46, s41
	global_load_lds_dwordx4 v132, s[24:25]
	s_mov_b32 m0, s43
	s_nop 0
	global_load_lds_dwordx4 v160, s[44:45]
	s_add_i32 m0, s43, 0x2000
	s_nop 0
	global_load_lds_dwordx4 v132, s[44:45]
	s_mov_b32 m0, s16
	s_nop 0
	global_load_lds_dwordx4 v128, s[82:83]
	s_mov_b32 m0, s17
	s_nop 0
	global_load_lds_dwordx4 v130, s[82:83]
	s_waitcnt vmcnt(8)
	s_waitcnt lgkmcnt(0)
	s_barrier
	s_setprio 1
	s_waitcnt lgkmcnt(0)
	v_mfma_f32_16x16x32_bf16 v[60:63], v[138:141], v[186:189], v[60:63]
	v_mfma_f32_16x16x32_bf16 v[56:59], v[146:149], v[186:189], v[56:59]
	v_mfma_f32_16x16x32_bf16 v[44:47], v[138:141], v[194:197], v[44:47]
	v_mfma_f32_16x16x32_bf16 v[40:43], v[146:149], v[194:197], v[40:43]
	v_mfma_f32_16x16x32_bf16 v[28:31], v[138:141], v[202:205], v[28:31]
	v_mfma_f32_16x16x32_bf16 v[24:27], v[146:149], v[202:205], v[24:27]
	v_mfma_f32_16x16x32_bf16 v[12:15], v[138:141], v[210:213], v[12:15]
	v_mfma_f32_16x16x32_bf16 v[8:11], v[146:149], v[210:213], v[8:11]
	v_mfma_f32_16x16x32_bf16 v[60:63], v[142:145], v[190:193], v[60:63]
	v_mfma_f32_16x16x32_bf16 v[56:59], v[150:153], v[190:193], v[56:59]
	v_mfma_f32_16x16x32_bf16 v[44:47], v[142:145], v[198:201], v[44:47]
	v_mfma_f32_16x16x32_bf16 v[40:43], v[150:153], v[198:201], v[40:43]
	v_mfma_f32_16x16x32_bf16 v[28:31], v[142:145], v[206:209], v[28:31]
	v_mfma_f32_16x16x32_bf16 v[24:27], v[150:153], v[206:209], v[24:27]
	v_mfma_f32_16x16x32_bf16 v[12:15], v[142:145], v[214:217], v[12:15]
	v_mfma_f32_16x16x32_bf16 v[8:11], v[150:153], v[214:217], v[8:11]
	s_setprio 0
	s_setprio 1
	v_mfma_f32_16x16x32_bf16 v[52:55], v[170:173], v[186:189], v[52:55]
	v_mfma_f32_16x16x32_bf16 v[48:51], v[178:181], v[186:189], v[48:51]
	v_mfma_f32_16x16x32_bf16 v[36:39], v[170:173], v[194:197], v[36:39]
	v_mfma_f32_16x16x32_bf16 v[32:35], v[178:181], v[194:197], v[32:35]
	v_mfma_f32_16x16x32_bf16 v[20:23], v[170:173], v[202:205], v[20:23]
	v_mfma_f32_16x16x32_bf16 v[16:19], v[178:181], v[202:205], v[16:19]
	v_mfma_f32_16x16x32_bf16 v[4:7], v[170:173], v[210:213], v[4:7]
	v_mfma_f32_16x16x32_bf16 v[0:3], v[178:181], v[210:213], v[0:3]
	v_mfma_f32_16x16x32_bf16 v[52:55], v[174:177], v[190:193], v[52:55]
	v_mfma_f32_16x16x32_bf16 v[48:51], v[182:185], v[190:193], v[48:51]
	v_mfma_f32_16x16x32_bf16 v[36:39], v[174:177], v[198:201], v[36:39]
	v_mfma_f32_16x16x32_bf16 v[32:35], v[182:185], v[198:201], v[32:35]
	v_mfma_f32_16x16x32_bf16 v[20:23], v[174:177], v[206:209], v[20:23]
	v_mfma_f32_16x16x32_bf16 v[16:19], v[182:185], v[206:209], v[16:19]
	v_mfma_f32_16x16x32_bf16 v[4:7], v[174:177], v[214:217], v[4:7]
	v_mfma_f32_16x16x32_bf16 v[0:3], v[182:185], v[214:217], v[0:3]
	s_setprio 0
	s_barrier
; #define PG8_STAGE(bufoff, gbase, voff) do { _Pragma("unroll") for (int _i = 0; _i < 2; ++_i) \
;         __builtin_amdgcn_global_load_lds((const unsigned*)((const char*)(gbase) + (voff)[_i]), (LAS unsigned*)(lds + (bufoff) + ldsw + _i * 8192), 16, 0, 0); } while (0)
; #define PG8_LDA(dst, b, h) do { _Pragma("unroll") for (int m = 0; m < 4; ++m) _Pragma("unroll") for (int k = 0; k < 2; ++k) dst[m][k] = *(const LAS bf16x8*)(lds + PG8_SA(b, h) + aoff + m * 2048 + k * 1024); } while (0)
; #define PG8_LDB(dst, b, h) do { _Pragma("unroll") for (int n = 0; n < 2; ++n) _Pragma("unroll") for (int k = 0; k < 2; ++k) dst[n][k] = *(const LAS bf16x8*)(lds + PG8_SB(b, h) + boff + n * 2048 + k * 1024); } while (0)
; #define PG8_MMA(ai, bj, At, Bt) do { __builtin_amdgcn_s_setprio(1); _Pragma("unroll") for (int m = 0; m < 4; ++m) _Pragma("unroll") for (int n = 0; n < 2; ++n) _Pragma("unroll") for (int k = 0; k < 2; ++k) \
;         acc[ai][bj][m][n] = __builtin_amdgcn_mfma_f32_16x16x32_bf16(Bt[n][k], At[m][k], acc[ai][bj][m][n], 0, 0, 0); __builtin_amdgcn_s_setprio(0); } while (0)
; #define PG8_WAIT_V(n) asm volatile("s_waitcnt vmcnt(" #n ")" ::: "memory")
; #define PG8_WAIT_L(n) asm volatile("s_waitcnt lgkmcnt(" #n ")" ::: "memory")
; #define PG8_BAR __builtin_amdgcn_s_barrier()
; #define PG8_SCHED __builtin_amdgcn_sched_barrier(0)
; template <class Epi, class Sched, bool ALIGN_EPI = true, bool SP2 = true>
; __device__ __forceinline__ void gemm_phase(LAS unsigned char* lds, const Gemm g, const Sched& S, const Epi& E) {
;     ...
;         for (int t = 0; t < nt; t += 2) {
;     ...
;             PG8_LDB(B0, 1, 0); PG8_LDB(B1, 1, 1); PG8_SCHED; PG8_LDA(At, 1, 0); PG8_STAGE(PG8_SA(0, 1), a2 + hstep, voffA);
;             PG8_WAIT_V(8); PG8_WAIT_L(0); PG8_BAR; PG8_MMA(0, 0, At, B0); PG8_MMA(0, 1, At, B1); PG8_BAR; PG8_SCHED;
;             PG8_LDA(At, 1, 1); PG8_STAGE(PG8_SB(1, 0), b3, voffB); PG8_STAGE(PG8_SB(1, 1), b3 + hstep, voffB); PG8_STAGE(PG8_SA(1, 0), a3, voffA);
;             PG8_WAIT_V(8); PG8_WAIT_L(0); PG8_BAR; PG8_MMA(1, 0, At, B0); PG8_MMA(1, 1, At, B1); PG8_BAR; PG8_SCHED;
	s_add_i32 s43, 0, 0x18000
	s_add_i32 s46, 0, 0x1c000
	v_add_u32_e32 v150, s43, v155
	v_add_u32_e32 v166, s46, v155
	ds_read_b128 v[138:141], v150
	ds_read_b128 v[142:145], v150 offset:1024
	ds_read_b128 v[146:149], v150 offset:2048
	ds_read_b128 v[150:153], v150 offset:3072
	ds_read_b128 v[170:173], v166
	ds_read_b128 v[174:177], v166 offset:1024
	ds_read_b128 v[178:181], v166 offset:2048
	ds_read_b128 v[182:185], v166 offset:3072
	s_add_u32 s44, s82, 0x80000
	s_addc_u32 s45, s83, 0
	s_mov_b32 m0, s30
	ds_read_b128 v[186:189], v157 offset:32768
	ds_read_b128 v[190:193], v157 offset:33792
	ds_read_b128 v[194:197], v157 offset:34816
	ds_read_b128 v[198:201], v157 offset:35840
	ds_read_b128 v[202:205], v157 offset:36864
	ds_read_b128 v[206:209], v157 offset:37888
	ds_read_b128 v[210:213], v157 offset:38912
	ds_read_b128 v[214:217], v157 offset:39936
	global_load_lds_dwordx4 v128, s[44:45]
	s_mov_b32 m0, s31
	s_nop 0
	global_load_lds_dwordx4 v130, s[44:45]
	s_waitcnt vmcnt(8)
	s_waitcnt lgkmcnt(0)
	s_barrier
	s_setprio 1
	s_waitcnt lgkmcnt(0)
	v_mfma_f32_16x16x32_bf16 v[124:127], v[138:141], v[186:189], v[124:127]
	v_mfma_f32_16x16x32_bf16 v[120:123], v[146:149], v[186:189], v[120:123]
	v_mfma_f32_16x16x32_bf16 v[108:111], v[138:141], v[194:197], v[108:111]
	v_mfma_f32_16x16x32_bf16 v[104:107], v[146:149], v[194:197], v[104:107]
	v_mfma_f32_16x16x32_bf16 v[92:95], v[138:141], v[202:205], v[92:95]
	v_mfma_f32_16x16x32_bf16 v[88:91], v[146:149], v[202:205], v[88:91]
	v_mfma_f32_16x16x32_bf16 v[76:79], v[138:141], v[210:213], v[76:79]
	v_mfma_f32_16x16x32_bf16 v[72:75], v[146:149], v[210:213], v[72:75]
	v_mfma_f32_16x16x32_bf16 v[124:127], v[142:145], v[190:193], v[124:127]
	v_mfma_f32_16x16x32_bf16 v[120:123], v[150:153], v[190:193], v[120:123]
	v_mfma_f32_16x16x32_bf16 v[108:111], v[142:145], v[198:201], v[108:111]
	v_mfma_f32_16x16x32_bf16 v[104:107], v[150:153], v[198:201], v[104:107]
	v_mfma_f32_16x16x32_bf16 v[92:95], v[142:145], v[206:209], v[92:95]
	v_mfma_f32_16x16x32_bf16 v[88:91], v[150:153], v[206:209], v[88:91]
	v_mfma_f32_16x16x32_bf16 v[76:79], v[142:145], v[214:217], v[76:79]
	v_mfma_f32_16x16x32_bf16 v[72:75], v[150:153], v[214:217], v[72:75]
	s_setprio 0
	s_setprio 1
	v_mfma_f32_16x16x32_bf16 v[116:119], v[170:173], v[186:189], v[116:119]
	v_mfma_f32_16x16x32_bf16 v[112:115], v[178:181], v[186:189], v[112:115]
	v_mfma_f32_16x16x32_bf16 v[100:103], v[170:173], v[194:197], v[100:103]
	v_mfma_f32_16x16x32_bf16 v[96:99], v[178:181], v[194:197], v[96:99]
	v_mfma_f32_16x16x32_bf16 v[84:87], v[170:173], v[202:205], v[84:87]
	v_mfma_f32_16x16x32_bf16 v[80:83], v[178:181], v[202:205], v[80:83]
	v_mfma_f32_16x16x32_bf16 v[68:71], v[170:173], v[210:213], v[68:71]
	v_mfma_f32_16x16x32_bf16 v[64:67], v[178:181], v[210:213], v[64:67]
	v_mfma_f32_16x16x32_bf16 v[116:119], v[174:177], v[190:193], v[116:119]
	v_mfma_f32_16x16x32_bf16 v[112:115], v[182:185], v[190:193], v[112:115]
	v_mfma_f32_16x16x32_bf16 v[100:103], v[174:177], v[198:201], v[100:103]
	v_mfma_f32_16x16x32_bf16 v[96:99], v[182:185], v[198:201], v[96:99]
	v_mfma_f32_16x16x32_bf16 v[84:87], v[174:177], v[206:209], v[84:87]
	v_mfma_f32_16x16x32_bf16 v[80:83], v[182:185], v[206:209], v[80:83]
	v_mfma_f32_16x16x32_bf16 v[68:71], v[174:177], v[214:217], v[68:71]
	v_mfma_f32_16x16x32_bf16 v[64:67], v[182:185], v[214:217], v[64:67]
	s_setprio 0
	s_barrier
	s_add_i32 s43, s43, s41
	s_mov_b32 m0, s43
	ds_read_b128 v[186:189], v157 offset:49152
	ds_read_b128 v[190:193], v157 offset:50176
	ds_read_b128 v[194:197], v157 offset:51200
	ds_read_b128 v[198:201], v157 offset:52224
	ds_read_b128 v[202:205], v157 offset:53248
	ds_read_b128 v[206:209], v157 offset:54272
	ds_read_b128 v[210:213], v157 offset:55296
	ds_read_b128 v[214:217], v157 offset:56320
	s_add_u32 s98, s24, 0x80
	s_addc_u32 s99, s25, 0
	global_load_lds_dwordx4 v160, s[98:99]
	s_add_i32 m0, s43, 0x2000
	s_add_u32 s24, s24, 0x80080
	s_addc_u32 s25, s25, 0
	s_add_i32 s43, s46, s41
	global_load_lds_dwordx4 v132, s[98:99]
	s_mov_b32 m0, s43
	s_nop 0
	global_load_lds_dwordx4 v160, s[24:25]
	s_add_i32 m0, s43, 0x2000
	s_nop 0
	global_load_lds_dwordx4 v132, s[24:25]
	s_mov_b32 m0, s60
	s_nop 0
	s_add_u32 s98, s82, 0x80
	s_addc_u32 s99, s83, 0
	global_load_lds_dwordx4 v128, s[98:99]
	s_mov_b32 m0, s61
	s_nop 0
	global_load_lds_dwordx4 v130, s[98:99]
	s_waitcnt vmcnt(8)
	s_waitcnt lgkmcnt(0)
	s_barrier
	s_setprio 1
	s_waitcnt lgkmcnt(0)
	v_mfma_f32_16x16x32_bf16 v[60:63], v[138:141], v[186:189], v[60:63]
	v_mfma_f32_16x16x32_bf16 v[56:59], v[146:149], v[186:189], v[56:59]
	v_mfma_f32_16x16x32_bf16 v[44:47], v[138:141], v[194:197], v[44:47]
	v_mfma_f32_16x16x32_bf16 v[40:43], v[146:149], v[194:197], v[40:43]
	v_mfma_f32_16x16x32_bf16 v[28:31], v[138:141], v[202:205], v[28:31]
	v_mfma_f32_16x16x32_bf16 v[24:27], v[146:149], v[202:205], v[24:27]
	v_mfma_f32_16x16x32_bf16 v[12:15], v[138:141], v[210:213], v[12:15]
	v_mfma_f32_16x16x32_bf16 v[8:11], v[146:149], v[210:213], v[8:11]
	v_mfma_f32_16x16x32_bf16 v[60:63], v[142:145], v[190:193], v[60:63]
	v_mfma_f32_16x16x32_bf16 v[56:59], v[150:153], v[190:193], v[56:59]
	v_mfma_f32_16x16x32_bf16 v[44:47], v[142:145], v[198:201], v[44:47]
	v_mfma_f32_16x16x32_bf16 v[40:43], v[150:153], v[198:201], v[40:43]
	v_mfma_f32_16x16x32_bf16 v[28:31], v[142:145], v[206:209], v[28:31]
	v_mfma_f32_16x16x32_bf16 v[24:27], v[150:153], v[206:209], v[24:27]
	v_mfma_f32_16x16x32_bf16 v[12:15], v[142:145], v[214:217], v[12:15]
	v_mfma_f32_16x16x32_bf16 v[8:11], v[150:153], v[214:217], v[8:11]
	s_setprio 0
	s_setprio 1
	v_mfma_f32_16x16x32_bf16 v[52:55], v[170:173], v[186:189], v[52:55]
	v_mfma_f32_16x16x32_bf16 v[48:51], v[178:181], v[186:189], v[48:51]
	v_mfma_f32_16x16x32_bf16 v[36:39], v[170:173], v[194:197], v[36:39]
	v_mfma_f32_16x16x32_bf16 v[32:35], v[178:181], v[194:197], v[32:35]
	v_mfma_f32_16x16x32_bf16 v[20:23], v[170:173], v[202:205], v[20:23]
	v_mfma_f32_16x16x32_bf16 v[16:19], v[178:181], v[202:205], v[16:19]
	v_mfma_f32_16x16x32_bf16 v[4:7], v[170:173], v[210:213], v[4:7]
	v_mfma_f32_16x16x32_bf16 v[0:3], v[178:181], v[210:213], v[0:3]
	v_mfma_f32_16x16x32_bf16 v[52:55], v[174:177], v[190:193], v[52:55]
	v_mfma_f32_16x16x32_bf16 v[48:51], v[182:185], v[190:193], v[48:51]
	v_mfma_f32_16x16x32_bf16 v[36:39], v[174:177], v[198:201], v[36:39]
	v_mfma_f32_16x16x32_bf16 v[32:35], v[182:185], v[198:201], v[32:35]
	v_mfma_f32_16x16x32_bf16 v[20:23], v[174:177], v[206:209], v[20:23]
	v_mfma_f32_16x16x32_bf16 v[16:19], v[182:185], v[206:209], v[16:19]
	v_mfma_f32_16x16x32_bf16 v[4:7], v[174:177], v[214:217], v[4:7]
	v_mfma_f32_16x16x32_bf16 v[0:3], v[182:185], v[214:217], v[0:3]
	s_setprio 0
	s_barrier
	s_add_i32 s42, s42, 2
	s_add_u32 s62, s62, 0x100
	s_addc_u32 s63, s63, 0
	s_add_u32 s18, s18, 0x100
	s_addc_u32 s19, s19, 0
	s_cmp_gt_u32 s42, 29
	s_cbranch_scc0 .LBB0_354
	s_and_b64 vcc, exec, s[14:15]
	s_cbranch_vccz .LBB0_357
	s_barrier

; #define PG8_STAGE(bufoff, gbase, voff) do { _Pragma("unroll") for (int _i = 0; _i < 2; ++_i) \
;         __builtin_amdgcn_global_load_lds((const unsigned*)((const char*)(gbase) + (voff)[_i]), (LAS unsigned*)(lds + (bufoff) + ldsw + _i * 8192), 16, 0, 0); } while (0)
; #define PG8_LDA(dst, b, h) do { _Pragma("unroll") for (int m = 0; m < 4; ++m) _Pragma("unroll") for (int k = 0; k < 2; ++k) dst[m][k] = *(const LAS bf16x8*)(lds + PG8_SA(b, h) + aoff + m * 2048 + k * 1024); } while (0)
; #define PG8_LDB(dst, b, h) do { _Pragma("unroll") for (int n = 0; n < 2; ++n) _Pragma("unroll") for (int k = 0; k < 2; ++k) dst[n][k] = *(const LAS bf16x8*)(lds + PG8_SB(b, h) + boff + n * 2048 + k * 1024); } while (0)
; #define PG8_MMA(ai, bj, At, Bt) do { __builtin_amdgcn_s_setprio(1); _Pragma("unroll") for (int m = 0; m < 4; ++m) _Pragma("unroll") for (int n = 0; n < 2; ++n) _Pragma("unroll") for (int k = 0; k < 2; ++k) \
;         acc[ai][bj][m][n] = __builtin_amdgcn_mfma_f32_16x16x32_bf16(Bt[n][k], At[m][k], acc[ai][bj][m][n], 0, 0, 0); __builtin_amdgcn_s_setprio(0); } while (0)
; #define PG8_WAIT_V(n) asm volatile("s_waitcnt vmcnt(" #n ")" ::: "memory")
; #define PG8_WAIT_L(n) asm volatile("s_waitcnt lgkmcnt(" #n ")" ::: "memory")
; #define PG8_BAR __builtin_amdgcn_s_barrier()
; #define PG8_SCHED __builtin_amdgcn_sched_barrier(0)
; template <class Epi, class Sched, bool ALIGN_EPI = true, bool SP2 = true>
; __device__ __forceinline__ void gemm_phase(LAS unsigned char* lds, const Gemm g, const Sched& S, const Epi& E) {
;     ...
;             const bool last = (t == nt - 2);
;             const char* a1 = cA + (size_t)(t + 1) * kstep;
;             const char* a2 = last ? nA : cA + (size_t)(t + 2) * kstep; const char* b2 = last ? nB : cB + (size_t)(t + 2) * kstep;
;             const char* a3 = a2 + kstep; const char* b3 = b2 + kstep;
;             if constexpr (SP2) {
;             PG8_LDB(B0, 0, 0); PG8_LDB(B1, 0, 1); PG8_SCHED; PG8_LDA(At, 0, 0); PG8_STAGE(PG8_SA(1, 1), a1 + hstep, voffA);
;             PG8_WAIT_V(8); PG8_WAIT_L(0); PG8_BAR; PG8_MMA(0, 0, At, B0); PG8_MMA(0, 1, At, B1); PG8_BAR; PG8_SCHED;
;             PG8_LDA(At, 0, 1); PG8_STAGE(PG8_SB(0, 0), b2, voffB); PG8_STAGE(PG8_SB(0, 1), b2 + hstep, voffB); PG8_STAGE(PG8_SA(0, 0), a2, voffA);
;             PG8_WAIT_V(8); PG8_WAIT_L(0); PG8_BAR; PG8_MMA(1, 0, At, B0); PG8_MMA(1, 1, At, B1); PG8_BAR; PG8_SCHED;
.LBB0_566:
	s_add_u32 s54, s52, 0x100
	s_addc_u32 s55, s53, 0
	s_add_i32 s46, 0, 0x10000
	s_cmpk_eq_i32 s89, 0x54
	s_cselect_b32 s61, s9, s55
	s_cselect_b32 s60, s8, s54
	v_add_u32_e32 v142, s46, v145
	s_cselect_b32 s25, s31, s3
	s_cselect_b32 s24, s30, s2
	s_add_i32 s47, 0, 0x14000
	ds_read_b128 v[138:141], v142
	ds_read_b128 v[148:151], v142 offset:1024
	ds_read_b128 v[152:155], v142 offset:2048
	ds_read_b128 v[156:159], v142 offset:3072
	v_add_u32_e32 v142, s47, v145
	ds_read_b128 v[170:173], v142
	ds_read_b128 v[174:177], v142 offset:1024
	ds_read_b128 v[178:181], v142 offset:2048
	ds_read_b128 v[182:185], v142 offset:3072
	s_add_i32 m0, s63, 0xc000
	ds_read_b128 v[186:189], v147
	ds_read_b128 v[190:193], v147 offset:1024
	ds_read_b128 v[194:197], v147 offset:2048
	ds_read_b128 v[198:201], v147 offset:3072
	ds_read_b128 v[202:205], v147 offset:4096
	ds_read_b128 v[206:209], v147 offset:5120
	ds_read_b128 v[210:213], v147 offset:6144
	ds_read_b128 v[214:217], v147 offset:7168
	global_load_lds_dwordx4 v134, s[52:53]
	s_add_i32 m0, s63, 0xe000
	s_nop 0
	global_load_lds_dwordx4 v136, s[52:53]
	s_waitcnt vmcnt(8)
	s_waitcnt lgkmcnt(0)
	s_barrier
	s_setprio 1
	s_waitcnt lgkmcnt(0)
	v_mfma_f32_16x16x32_bf16 v[124:127], v[138:141], v[186:189], v[124:127]
	v_mfma_f32_16x16x32_bf16 v[120:123], v[152:155], v[186:189], v[120:123]
	v_mfma_f32_16x16x32_bf16 v[108:111], v[138:141], v[194:197], v[108:111]
	v_mfma_f32_16x16x32_bf16 v[104:107], v[152:155], v[194:197], v[104:107]
	v_mfma_f32_16x16x32_bf16 v[92:95], v[138:141], v[202:205], v[92:95]
	v_mfma_f32_16x16x32_bf16 v[88:91], v[152:155], v[202:205], v[88:91]
	v_mfma_f32_16x16x32_bf16 v[76:79], v[138:141], v[210:213], v[76:79]
	v_mfma_f32_16x16x32_bf16 v[72:75], v[152:155], v[210:213], v[72:75]
	v_mfma_f32_16x16x32_bf16 v[124:127], v[148:151], v[190:193], v[124:127]
	v_mfma_f32_16x16x32_bf16 v[120:123], v[156:159], v[190:193], v[120:123]
	v_mfma_f32_16x16x32_bf16 v[108:111], v[148:151], v[198:201], v[108:111]
	v_mfma_f32_16x16x32_bf16 v[104:107], v[156:159], v[198:201], v[104:107]
	v_mfma_f32_16x16x32_bf16 v[92:95], v[148:151], v[206:209], v[92:95]
	v_mfma_f32_16x16x32_bf16 v[88:91], v[156:159], v[206:209], v[88:91]
	v_mfma_f32_16x16x32_bf16 v[76:79], v[148:151], v[214:217], v[76:79]
	v_mfma_f32_16x16x32_bf16 v[72:75], v[156:159], v[214:217], v[72:75]
	s_setprio 0
	s_setprio 1
	v_mfma_f32_16x16x32_bf16 v[116:119], v[170:173], v[186:189], v[116:119]
	v_mfma_f32_16x16x32_bf16 v[112:115], v[178:181], v[186:189], v[112:115]
	v_mfma_f32_16x16x32_bf16 v[100:103], v[170:173], v[194:197], v[100:103]
	v_mfma_f32_16x16x32_bf16 v[96:99], v[178:181], v[194:197], v[96:99]
	v_mfma_f32_16x16x32_bf16 v[84:87], v[170:173], v[202:205], v[84:87]
	v_mfma_f32_16x16x32_bf16 v[80:83], v[178:181], v[202:205], v[80:83]
	v_mfma_f32_16x16x32_bf16 v[68:71], v[170:173], v[210:213], v[68:71]
	v_mfma_f32_16x16x32_bf16 v[64:67], v[178:181], v[210:213], v[64:67]
	v_mfma_f32_16x16x32_bf16 v[116:119], v[174:177], v[190:193], v[116:119]
	v_mfma_f32_16x16x32_bf16 v[112:115], v[182:185], v[190:193], v[112:115]
	v_mfma_f32_16x16x32_bf16 v[100:103], v[174:177], v[198:201], v[100:103]
	v_mfma_f32_16x16x32_bf16 v[96:99], v[182:185], v[198:201], v[96:99]
	v_mfma_f32_16x16x32_bf16 v[84:87], v[174:177], v[206:209], v[84:87]
	v_mfma_f32_16x16x32_bf16 v[80:83], v[182:185], v[206:209], v[80:83]
	v_mfma_f32_16x16x32_bf16 v[68:71], v[174:177], v[214:217], v[68:71]
	v_mfma_f32_16x16x32_bf16 v[64:67], v[182:185], v[214:217], v[64:67]
	s_setprio 0
	s_barrier
	s_add_i32 s46, s46, s62
	s_mov_b32 m0, s46
	ds_read_b128 v[186:189], v147 offset:16384
	ds_read_b128 v[190:193], v147 offset:17408
	ds_read_b128 v[194:197], v147 offset:18432
	ds_read_b128 v[198:201], v147 offset:19456
	ds_read_b128 v[202:205], v147 offset:20480
	ds_read_b128 v[206:209], v147 offset:21504
	ds_read_b128 v[210:213], v147 offset:22528
	ds_read_b128 v[214:217], v147 offset:23552
	global_load_lds_dwordx4 v160, s[24:25]
	s_add_i32 m0, s46, 0x2000
	s_add_u32 s52, s24, 0x160000
	s_addc_u32 s53, s25, 0
	s_add_i32 s46, s47, s62
	global_load_lds_dwordx4 v132, s[24:25]
	s_mov_b32 m0, s46
	s_nop 0
	global_load_lds_dwordx4 v160, s[52:53]
	s_add_i32 m0, s46, 0x2000
	s_nop 0
	global_load_lds_dwordx4 v132, s[52:53]
	s_mov_b32 m0, s63
	s_nop 0
	global_load_lds_dwordx4 v128, s[60:61]
	s_mov_b32 m0, s66
	s_nop 0
	global_load_lds_dwordx4 v130, s[60:61]
	s_waitcnt vmcnt(8)
	s_waitcnt lgkmcnt(0)
	s_barrier
	s_setprio 1
	s_waitcnt lgkmcnt(0)
	v_mfma_f32_16x16x32_bf16 v[60:63], v[138:141], v[186:189], v[60:63]
	v_mfma_f32_16x16x32_bf16 v[56:59], v[152:155], v[186:189], v[56:59]
	v_mfma_f32_16x16x32_bf16 v[44:47], v[138:141], v[194:197], v[44:47]
	v_mfma_f32_16x16x32_bf16 v[40:43], v[152:155], v[194:197], v[40:43]
	v_mfma_f32_16x16x32_bf16 v[28:31], v[138:141], v[202:205], v[28:31]
	v_mfma_f32_16x16x32_bf16 v[24:27], v[152:155], v[202:205], v[24:27]
	v_mfma_f32_16x16x32_bf16 v[12:15], v[138:141], v[210:213], v[12:15]
	v_mfma_f32_16x16x32_bf16 v[8:11], v[152:155], v[210:213], v[8:11]
	v_mfma_f32_16x16x32_bf16 v[60:63], v[148:151], v[190:193], v[60:63]
	v_mfma_f32_16x16x32_bf16 v[56:59], v[156:159], v[190:193], v[56:59]
	v_mfma_f32_16x16x32_bf16 v[44:47], v[148:151], v[198:201], v[44:47]
	v_mfma_f32_16x16x32_bf16 v[40:43], v[156:159], v[198:201], v[40:43]
	v_mfma_f32_16x16x32_bf16 v[28:31], v[148:151], v[206:209], v[28:31]
	v_mfma_f32_16x16x32_bf16 v[24:27], v[156:159], v[206:209], v[24:27]
	v_mfma_f32_16x16x32_bf16 v[12:15], v[148:151], v[214:217], v[12:15]
	v_mfma_f32_16x16x32_bf16 v[8:11], v[156:159], v[214:217], v[8:11]
	s_setprio 0
	s_setprio 1
	v_mfma_f32_16x16x32_bf16 v[52:55], v[170:173], v[186:189], v[52:55]
	v_mfma_f32_16x16x32_bf16 v[48:51], v[178:181], v[186:189], v[48:51]
	v_mfma_f32_16x16x32_bf16 v[36:39], v[170:173], v[194:197], v[36:39]
	v_mfma_f32_16x16x32_bf16 v[32:35], v[178:181], v[194:197], v[32:35]
	v_mfma_f32_16x16x32_bf16 v[20:23], v[170:173], v[202:205], v[20:23]
	v_mfma_f32_16x16x32_bf16 v[16:19], v[178:181], v[202:205], v[16:19]
	v_mfma_f32_16x16x32_bf16 v[4:7], v[170:173], v[210:213], v[4:7]
	v_mfma_f32_16x16x32_bf16 v[0:3], v[178:181], v[210:213], v[0:3]
	v_mfma_f32_16x16x32_bf16 v[52:55], v[174:177], v[190:193], v[52:55]
	v_mfma_f32_16x16x32_bf16 v[48:51], v[182:185], v[190:193], v[48:51]
	v_mfma_f32_16x16x32_bf16 v[36:39], v[174:177], v[198:201], v[36:39]
	v_mfma_f32_16x16x32_bf16 v[32:35], v[182:185], v[198:201], v[32:35]
	v_mfma_f32_16x16x32_bf16 v[20:23], v[174:177], v[206:209], v[20:23]
	v_mfma_f32_16x16x32_bf16 v[16:19], v[182:185], v[206:209], v[16:19]
	v_mfma_f32_16x16x32_bf16 v[4:7], v[174:177], v[214:217], v[4:7]
	v_mfma_f32_16x16x32_bf16 v[0:3], v[182:185], v[214:217], v[0:3]
	s_setprio 0
	s_barrier
; #define PG8_STAGE(bufoff, gbase, voff) do { _Pragma("unroll") for (int _i = 0; _i < 2; ++_i) \
;         __builtin_amdgcn_global_load_lds((const unsigned*)((const char*)(gbase) + (voff)[_i]), (LAS unsigned*)(lds + (bufoff) + ldsw + _i * 8192), 16, 0, 0); } while (0)
; #define PG8_LDA(dst, b, h) do { _Pragma("unroll") for (int m = 0; m < 4; ++m) _Pragma("unroll") for (int k = 0; k < 2; ++k) dst[m][k] = *(const LAS bf16x8*)(lds + PG8_SA(b, h) + aoff + m * 2048 + k * 1024); } while (0)
; #define PG8_LDB(dst, b, h) do { _Pragma("unroll") for (int n = 0; n < 2; ++n) _Pragma("unroll") for (int k = 0; k < 2; ++k) dst[n][k] = *(const LAS bf16x8*)(lds + PG8_SB(b, h) + boff + n * 2048 + k * 1024); } while (0)
; #define PG8_MMA(ai, bj, At, Bt) do { __builtin_amdgcn_s_setprio(1); _Pragma("unroll") for (int m = 0; m < 4; ++m) _Pragma("unroll") for (int n = 0; n < 2; ++n) _Pragma("unroll") for (int k = 0; k < 2; ++k) \
;         acc[ai][bj][m][n] = __builtin_amdgcn_mfma_f32_16x16x32_bf16(Bt[n][k], At[m][k], acc[ai][bj][m][n], 0, 0, 0); __builtin_amdgcn_s_setprio(0); } while (0)
; #define PG8_WAIT_V(n) asm volatile("s_waitcnt vmcnt(" #n ")" ::: "memory")
; #define PG8_WAIT_L(n) asm volatile("s_waitcnt lgkmcnt(" #n ")" ::: "memory")
; #define PG8_BAR __builtin_amdgcn_s_barrier()
; #define PG8_SCHED __builtin_amdgcn_sched_barrier(0)
; template <class Epi, class Sched, bool ALIGN_EPI = true, bool SP2 = true>
; __device__ __forceinline__ void gemm_phase(LAS unsigned char* lds, const Gemm g, const Sched& S, const Epi& E) {
;     ...
;         for (int t = 0; t < nt; t += 2) {
;     ...
;             PG8_LDB(B0, 1, 0); PG8_LDB(B1, 1, 1); PG8_SCHED; PG8_LDA(At, 1, 0); PG8_STAGE(PG8_SA(0, 1), a2 + hstep, voffA);
;             PG8_WAIT_V(8); PG8_WAIT_L(0); PG8_BAR; PG8_MMA(0, 0, At, B0); PG8_MMA(0, 1, At, B1); PG8_BAR; PG8_SCHED;
;             PG8_LDA(At, 1, 1); PG8_STAGE(PG8_SB(1, 0), b3, voffB); PG8_STAGE(PG8_SB(1, 1), b3 + hstep, voffB); PG8_STAGE(PG8_SA(1, 0), a3, voffA);
;             PG8_WAIT_V(8); PG8_WAIT_L(0); PG8_BAR; PG8_MMA(1, 0, At, B0); PG8_MMA(1, 1, At, B1); PG8_BAR; PG8_SCHED;
	s_add_i32 s46, 0, 0x18000
	s_add_i32 s47, 0, 0x1c000
	v_add_u32_e32 v156, s46, v145
	v_add_u32_e32 v166, s47, v145
	ds_read_b128 v[138:141], v156
	ds_read_b128 v[148:151], v156 offset:1024
	ds_read_b128 v[152:155], v156 offset:2048
	ds_read_b128 v[156:159], v156 offset:3072
	ds_read_b128 v[170:173], v166
	ds_read_b128 v[174:177], v166 offset:1024
	ds_read_b128 v[178:181], v166 offset:2048
	ds_read_b128 v[182:185], v166 offset:3072
	s_add_u32 s52, s60, 0x160000
	s_addc_u32 s53, s61, 0
	s_mov_b32 m0, s67
	ds_read_b128 v[186:189], v147 offset:32768
	ds_read_b128 v[190:193], v147 offset:33792
	ds_read_b128 v[194:197], v147 offset:34816
	ds_read_b128 v[198:201], v147 offset:35840
	ds_read_b128 v[202:205], v147 offset:36864
	ds_read_b128 v[206:209], v147 offset:37888
	ds_read_b128 v[210:213], v147 offset:38912
	ds_read_b128 v[214:217], v147 offset:39936
	global_load_lds_dwordx4 v128, s[52:53]
	s_mov_b32 m0, s72
	s_nop 0
	global_load_lds_dwordx4 v130, s[52:53]
	s_waitcnt vmcnt(8)
	s_waitcnt lgkmcnt(0)
	s_barrier
	s_setprio 1
	s_waitcnt lgkmcnt(0)
	v_mfma_f32_16x16x32_bf16 v[124:127], v[138:141], v[186:189], v[124:127]
	v_mfma_f32_16x16x32_bf16 v[120:123], v[152:155], v[186:189], v[120:123]
	v_mfma_f32_16x16x32_bf16 v[108:111], v[138:141], v[194:197], v[108:111]
	v_mfma_f32_16x16x32_bf16 v[104:107], v[152:155], v[194:197], v[104:107]
	v_mfma_f32_16x16x32_bf16 v[92:95], v[138:141], v[202:205], v[92:95]
	v_mfma_f32_16x16x32_bf16 v[88:91], v[152:155], v[202:205], v[88:91]
	v_mfma_f32_16x16x32_bf16 v[76:79], v[138:141], v[210:213], v[76:79]
	v_mfma_f32_16x16x32_bf16 v[72:75], v[152:155], v[210:213], v[72:75]
	v_mfma_f32_16x16x32_bf16 v[124:127], v[148:151], v[190:193], v[124:127]
	v_mfma_f32_16x16x32_bf16 v[120:123], v[156:159], v[190:193], v[120:123]
	v_mfma_f32_16x16x32_bf16 v[108:111], v[148:151], v[198:201], v[108:111]
	v_mfma_f32_16x16x32_bf16 v[104:107], v[156:159], v[198:201], v[104:107]
	v_mfma_f32_16x16x32_bf16 v[92:95], v[148:151], v[206:209], v[92:95]
	v_mfma_f32_16x16x32_bf16 v[88:91], v[156:159], v[206:209], v[88:91]
	v_mfma_f32_16x16x32_bf16 v[76:79], v[148:151], v[214:217], v[76:79]
	v_mfma_f32_16x16x32_bf16 v[72:75], v[156:159], v[214:217], v[72:75]
	s_setprio 0
	s_setprio 1
	v_mfma_f32_16x16x32_bf16 v[116:119], v[170:173], v[186:189], v[116:119]
	v_mfma_f32_16x16x32_bf16 v[112:115], v[178:181], v[186:189], v[112:115]
	v_mfma_f32_16x16x32_bf16 v[100:103], v[170:173], v[194:197], v[100:103]
	v_mfma_f32_16x16x32_bf16 v[96:99], v[178:181], v[194:197], v[96:99]
	v_mfma_f32_16x16x32_bf16 v[84:87], v[170:173], v[202:205], v[84:87]
	v_mfma_f32_16x16x32_bf16 v[80:83], v[178:181], v[202:205], v[80:83]
	v_mfma_f32_16x16x32_bf16 v[68:71], v[170:173], v[210:213], v[68:71]
	v_mfma_f32_16x16x32_bf16 v[64:67], v[178:181], v[210:213], v[64:67]
	v_mfma_f32_16x16x32_bf16 v[116:119], v[174:177], v[190:193], v[116:119]
	v_mfma_f32_16x16x32_bf16 v[112:115], v[182:185], v[190:193], v[112:115]
	v_mfma_f32_16x16x32_bf16 v[100:103], v[174:177], v[198:201], v[100:103]
	v_mfma_f32_16x16x32_bf16 v[96:99], v[182:185], v[198:201], v[96:99]
	v_mfma_f32_16x16x32_bf16 v[84:87], v[174:177], v[206:209], v[84:87]
	v_mfma_f32_16x16x32_bf16 v[80:83], v[182:185], v[206:209], v[80:83]
	v_mfma_f32_16x16x32_bf16 v[68:71], v[174:177], v[214:217], v[68:71]
	v_mfma_f32_16x16x32_bf16 v[64:67], v[182:185], v[214:217], v[64:67]
	s_setprio 0
	s_barrier
	s_add_i32 s46, s46, s62
	s_mov_b32 m0, s46
	ds_read_b128 v[186:189], v147 offset:49152
	ds_read_b128 v[190:193], v147 offset:50176
	ds_read_b128 v[194:197], v147 offset:51200
	ds_read_b128 v[198:201], v147 offset:52224
	ds_read_b128 v[202:205], v147 offset:53248
	ds_read_b128 v[206:209], v147 offset:54272
	ds_read_b128 v[210:213], v147 offset:55296
	ds_read_b128 v[214:217], v147 offset:56320
	s_add_u32 s98, s24, 0x80
	s_addc_u32 s99, s25, 0
	global_load_lds_dwordx4 v160, s[98:99]
	s_add_i32 m0, s46, 0x2000
	s_add_u32 s24, s24, 0x160080
	s_addc_u32 s25, s25, 0
	s_add_i32 s46, s47, s62
	global_load_lds_dwordx4 v132, s[98:99]
	s_mov_b32 m0, s46
	s_nop 0
	global_load_lds_dwordx4 v160, s[24:25]
	s_add_i32 m0, s46, 0x2000
	s_nop 0
	global_load_lds_dwordx4 v132, s[24:25]
	s_mov_b32 m0, s73
	s_nop 0
	s_add_u32 s98, s52, 0xffea0080
	s_addc_u32 s99, s53, -1
	global_load_lds_dwordx4 v128, s[98:99]
	s_mov_b32 m0, s79
	s_nop 0
	global_load_lds_dwordx4 v130, s[98:99]
	s_waitcnt vmcnt(8)
	s_waitcnt lgkmcnt(0)
	s_barrier
	s_setprio 1
	s_waitcnt lgkmcnt(0)
	v_mfma_f32_16x16x32_bf16 v[60:63], v[138:141], v[186:189], v[60:63]
	v_mfma_f32_16x16x32_bf16 v[56:59], v[152:155], v[186:189], v[56:59]
	v_mfma_f32_16x16x32_bf16 v[44:47], v[138:141], v[194:197], v[44:47]
	v_mfma_f32_16x16x32_bf16 v[40:43], v[152:155], v[194:197], v[40:43]
	v_mfma_f32_16x16x32_bf16 v[28:31], v[138:141], v[202:205], v[28:31]
	v_mfma_f32_16x16x32_bf16 v[24:27], v[152:155], v[202:205], v[24:27]
	v_mfma_f32_16x16x32_bf16 v[12:15], v[138:141], v[210:213], v[12:15]
	v_mfma_f32_16x16x32_bf16 v[8:11], v[152:155], v[210:213], v[8:11]
	v_mfma_f32_16x16x32_bf16 v[60:63], v[148:151], v[190:193], v[60:63]
	v_mfma_f32_16x16x32_bf16 v[56:59], v[156:159], v[190:193], v[56:59]
	v_mfma_f32_16x16x32_bf16 v[44:47], v[148:151], v[198:201], v[44:47]
	v_mfma_f32_16x16x32_bf16 v[40:43], v[156:159], v[198:201], v[40:43]
	v_mfma_f32_16x16x32_bf16 v[28:31], v[148:151], v[206:209], v[28:31]
	v_mfma_f32_16x16x32_bf16 v[24:27], v[156:159], v[206:209], v[24:27]
	v_mfma_f32_16x16x32_bf16 v[12:15], v[148:151], v[214:217], v[12:15]
	v_mfma_f32_16x16x32_bf16 v[8:11], v[156:159], v[214:217], v[8:11]
	s_setprio 0
	s_setprio 1
	v_mfma_f32_16x16x32_bf16 v[52:55], v[170:173], v[186:189], v[52:55]
	v_mfma_f32_16x16x32_bf16 v[48:51], v[178:181], v[186:189], v[48:51]
	v_mfma_f32_16x16x32_bf16 v[36:39], v[170:173], v[194:197], v[36:39]
	v_mfma_f32_16x16x32_bf16 v[32:35], v[178:181], v[194:197], v[32:35]
	v_mfma_f32_16x16x32_bf16 v[20:23], v[170:173], v[202:205], v[20:23]
	v_mfma_f32_16x16x32_bf16 v[16:19], v[178:181], v[202:205], v[16:19]
	v_mfma_f32_16x16x32_bf16 v[4:7], v[170:173], v[210:213], v[4:7]
	v_mfma_f32_16x16x32_bf16 v[0:3], v[178:181], v[210:213], v[0:3]
	v_mfma_f32_16x16x32_bf16 v[52:55], v[174:177], v[190:193], v[52:55]
	v_mfma_f32_16x16x32_bf16 v[48:51], v[182:185], v[190:193], v[48:51]
	v_mfma_f32_16x16x32_bf16 v[36:39], v[174:177], v[198:201], v[36:39]
	v_mfma_f32_16x16x32_bf16 v[32:35], v[182:185], v[198:201], v[32:35]
	v_mfma_f32_16x16x32_bf16 v[20:23], v[174:177], v[206:209], v[20:23]
	v_mfma_f32_16x16x32_bf16 v[16:19], v[182:185], v[206:209], v[16:19]
	v_mfma_f32_16x16x32_bf16 v[4:7], v[174:177], v[214:217], v[4:7]
	v_mfma_f32_16x16x32_bf16 v[0:3], v[182:185], v[214:217], v[0:3]
	s_setprio 0
	s_barrier
	s_add_i32 s89, s89, 2
	s_add_u32 s2, s2, 0x100
	s_addc_u32 s3, s3, 0
	s_cmpk_gt_u32 s89, 0x55
	s_mov_b64 s[52:53], s[54:55]
	s_cbranch_scc0 .LBB0_566
	s_and_b64 vcc, exec, s[18:19]
	s_cbranch_vccz .LBB0_569
	s_barrier

; #define PG8_STAGE(bufoff, gbase, voff) do { _Pragma("unroll") for (int _i = 0; _i < 2; ++_i) \
;         __builtin_amdgcn_global_load_lds((const unsigned*)((const char*)(gbase) + (voff)[_i]), (LAS unsigned*)(lds + (bufoff) + ldsw + _i * 8192), 16, 0, 0); } while (0)
; #define PG8_LDA(dst, b, h) do { _Pragma("unroll") for (int m = 0; m < 4; ++m) _Pragma("unroll") for (int k = 0; k < 2; ++k) dst[m][k] = *(const LAS bf16x8*)(lds + PG8_SA(b, h) + aoff + m * 2048 + k * 1024); } while (0)
; #define PG8_LDB(dst, b, h) do { _Pragma("unroll") for (int n = 0; n < 2; ++n) _Pragma("unroll") for (int k = 0; k < 2; ++k) dst[n][k] = *(const LAS bf16x8*)(lds + PG8_SB(b, h) + boff + n * 2048 + k * 1024); } while (0)
; #define PG8_MMA(ai, bj, At, Bt) do { __builtin_amdgcn_s_setprio(1); _Pragma("unroll") for (int m = 0; m < 4; ++m) _Pragma("unroll") for (int n = 0; n < 2; ++n) _Pragma("unroll") for (int k = 0; k < 2; ++k) \
;         acc[ai][bj][m][n] = __builtin_amdgcn_mfma_f32_16x16x32_bf16(Bt[n][k], At[m][k], acc[ai][bj][m][n], 0, 0, 0); __builtin_amdgcn_s_setprio(0); } while (0)
; #define PG8_WAIT_V(n) asm volatile("s_waitcnt vmcnt(" #n ")" ::: "memory")
; #define PG8_WAIT_L(n) asm volatile("s_waitcnt lgkmcnt(" #n ")" ::: "memory")
; #define PG8_BAR __builtin_amdgcn_s_barrier()
; #define PG8_SCHED __builtin_amdgcn_sched_barrier(0)
; template <class Epi, class Sched, bool ALIGN_EPI = true, bool SP2 = true>
; __device__ __forceinline__ void gemm_phase(LAS unsigned char* lds, const Gemm g, const Sched& S, const Epi& E) {
;     ...
;             const bool last = (t == nt - 2);
;             const char* a1 = cA + (size_t)(t + 1) * kstep;
;             const char* a2 = last ? nA : cA + (size_t)(t + 2) * kstep; const char* b2 = last ? nB : cB + (size_t)(t + 2) * kstep;
;             const char* a3 = a2 + kstep; const char* b3 = b2 + kstep;
;             if constexpr (SP2) {
;             PG8_LDB(B0, 0, 0); PG8_LDB(B1, 0, 1); PG8_SCHED; PG8_LDA(At, 0, 0); PG8_STAGE(PG8_SA(1, 1), a1 + hstep, voffA);
;             PG8_WAIT_V(8); PG8_WAIT_L(0); PG8_BAR; PG8_MMA(0, 0, At, B0); PG8_MMA(0, 1, At, B1); PG8_BAR; PG8_SCHED;
;             PG8_LDA(At, 0, 1); PG8_STAGE(PG8_SB(0, 0), b2, voffB); PG8_STAGE(PG8_SB(0, 1), b2 + hstep, voffB); PG8_STAGE(PG8_SA(0, 0), a2, voffA);
;             PG8_WAIT_V(8); PG8_WAIT_L(0); PG8_BAR; PG8_MMA(1, 0, At, B0); PG8_MMA(1, 1, At, B1); PG8_BAR; PG8_SCHED;
.LBB0_600:
	s_add_u32 s24, s54, 0xfff80080
	s_addc_u32 s25, s55, -1
	s_add_i32 s46, 0, 0x10000
	s_cmp_eq_u32 s83, 28
	s_cselect_b32 s61, s2, s25
	s_cselect_b32 s60, s3, s24
	v_add_u32_e32 v142, s46, v145
	s_cselect_b32 s25, s15, s82
	s_cselect_b32 s24, s17, s79
	s_add_i32 s47, 0, 0x14000
	ds_read_b128 v[138:141], v142
	ds_read_b128 v[148:151], v142 offset:1024
	ds_read_b128 v[152:155], v142 offset:2048
	ds_read_b128 v[156:159], v142 offset:3072
	v_add_u32_e32 v142, s47, v145
	ds_read_b128 v[170:173], v142
	ds_read_b128 v[174:177], v142 offset:1024
	ds_read_b128 v[178:181], v142 offset:2048
	ds_read_b128 v[182:185], v142 offset:3072
	s_add_i32 m0, s43, 0xc000
	ds_read_b128 v[186:189], v147
	ds_read_b128 v[190:193], v147 offset:1024
	ds_read_b128 v[194:197], v147 offset:2048
	ds_read_b128 v[198:201], v147 offset:3072
	ds_read_b128 v[202:205], v147 offset:4096
	ds_read_b128 v[206:209], v147 offset:5120
	ds_read_b128 v[210:213], v147 offset:6144
	ds_read_b128 v[214:217], v147 offset:7168
	global_load_lds_dwordx4 v134, s[54:55]
	s_add_i32 m0, s43, 0xe000
	s_nop 0
	global_load_lds_dwordx4 v136, s[54:55]
	s_waitcnt vmcnt(8)
	s_waitcnt lgkmcnt(0)
	s_barrier
	s_setprio 1
	s_waitcnt lgkmcnt(0)
	v_mfma_f32_16x16x32_bf16 v[124:127], v[138:141], v[186:189], v[124:127]
	v_mfma_f32_16x16x32_bf16 v[116:119], v[152:155], v[186:189], v[116:119]
	v_mfma_f32_16x16x32_bf16 v[108:111], v[138:141], v[194:197], v[108:111]
	v_mfma_f32_16x16x32_bf16 v[100:103], v[152:155], v[194:197], v[100:103]
	v_mfma_f32_16x16x32_bf16 v[92:95], v[138:141], v[202:205], v[92:95]
	v_mfma_f32_16x16x32_bf16 v[84:87], v[152:155], v[202:205], v[84:87]
	v_mfma_f32_16x16x32_bf16 v[76:79], v[138:141], v[210:213], v[76:79]
	v_mfma_f32_16x16x32_bf16 v[68:71], v[152:155], v[210:213], v[68:71]
	v_mfma_f32_16x16x32_bf16 v[124:127], v[148:151], v[190:193], v[124:127]
	v_mfma_f32_16x16x32_bf16 v[116:119], v[156:159], v[190:193], v[116:119]
	v_mfma_f32_16x16x32_bf16 v[108:111], v[148:151], v[198:201], v[108:111]
	v_mfma_f32_16x16x32_bf16 v[100:103], v[156:159], v[198:201], v[100:103]
	v_mfma_f32_16x16x32_bf16 v[92:95], v[148:151], v[206:209], v[92:95]
	v_mfma_f32_16x16x32_bf16 v[84:87], v[156:159], v[206:209], v[84:87]
	v_mfma_f32_16x16x32_bf16 v[76:79], v[148:151], v[214:217], v[76:79]
	v_mfma_f32_16x16x32_bf16 v[68:71], v[156:159], v[214:217], v[68:71]
	s_setprio 0
	s_setprio 1
	v_mfma_f32_16x16x32_bf16 v[120:123], v[170:173], v[186:189], v[120:123]
	v_mfma_f32_16x16x32_bf16 v[112:115], v[178:181], v[186:189], v[112:115]
	v_mfma_f32_16x16x32_bf16 v[104:107], v[170:173], v[194:197], v[104:107]
	v_mfma_f32_16x16x32_bf16 v[96:99], v[178:181], v[194:197], v[96:99]
	v_mfma_f32_16x16x32_bf16 v[88:91], v[170:173], v[202:205], v[88:91]
	v_mfma_f32_16x16x32_bf16 v[80:83], v[178:181], v[202:205], v[80:83]
	v_mfma_f32_16x16x32_bf16 v[72:75], v[170:173], v[210:213], v[72:75]
	v_mfma_f32_16x16x32_bf16 v[64:67], v[178:181], v[210:213], v[64:67]
	v_mfma_f32_16x16x32_bf16 v[120:123], v[174:177], v[190:193], v[120:123]
	v_mfma_f32_16x16x32_bf16 v[112:115], v[182:185], v[190:193], v[112:115]
	v_mfma_f32_16x16x32_bf16 v[104:107], v[174:177], v[198:201], v[104:107]
	v_mfma_f32_16x16x32_bf16 v[96:99], v[182:185], v[198:201], v[96:99]
	v_mfma_f32_16x16x32_bf16 v[88:91], v[174:177], v[206:209], v[88:91]
	v_mfma_f32_16x16x32_bf16 v[80:83], v[182:185], v[206:209], v[80:83]
	v_mfma_f32_16x16x32_bf16 v[72:75], v[174:177], v[214:217], v[72:75]
	v_mfma_f32_16x16x32_bf16 v[64:67], v[182:185], v[214:217], v[64:67]
	s_setprio 0
	s_barrier
	s_add_i32 s46, s46, s62
	s_mov_b32 m0, s46
	ds_read_b128 v[186:189], v147 offset:16384
	ds_read_b128 v[190:193], v147 offset:17408
	ds_read_b128 v[194:197], v147 offset:18432
	ds_read_b128 v[198:201], v147 offset:19456
	ds_read_b128 v[202:205], v147 offset:20480
	ds_read_b128 v[206:209], v147 offset:21504
	ds_read_b128 v[210:213], v147 offset:22528
	ds_read_b128 v[214:217], v147 offset:23552
	global_load_lds_dwordx4 v160, s[24:25]
	s_add_i32 m0, s46, 0x2000
	s_add_u32 s88, s24, 0x80000
	s_addc_u32 s89, s25, 0
	s_add_i32 s46, s47, s62
	global_load_lds_dwordx4 v128, s[24:25]
	s_mov_b32 m0, s46
	s_nop 0
	global_load_lds_dwordx4 v160, s[88:89]
	s_add_i32 m0, s46, 0x2000
	s_nop 0
	global_load_lds_dwordx4 v128, s[88:89]
	s_mov_b32 m0, s43
	s_nop 0
	global_load_lds_dwordx4 v132, s[60:61]
	s_mov_b32 m0, s44
	s_nop 0
	global_load_lds_dwordx4 v130, s[60:61]
	s_waitcnt vmcnt(8)
	s_waitcnt lgkmcnt(0)
	s_barrier
	s_setprio 1
	s_waitcnt lgkmcnt(0)
	v_mfma_f32_16x16x32_bf16 v[60:63], v[138:141], v[186:189], v[60:63]
	v_mfma_f32_16x16x32_bf16 v[52:55], v[152:155], v[186:189], v[52:55]
	v_mfma_f32_16x16x32_bf16 v[44:47], v[138:141], v[194:197], v[44:47]
	v_mfma_f32_16x16x32_bf16 v[36:39], v[152:155], v[194:197], v[36:39]
	v_mfma_f32_16x16x32_bf16 v[28:31], v[138:141], v[202:205], v[28:31]
	v_mfma_f32_16x16x32_bf16 v[20:23], v[152:155], v[202:205], v[20:23]
	v_mfma_f32_16x16x32_bf16 v[12:15], v[138:141], v[210:213], v[12:15]
	v_mfma_f32_16x16x32_bf16 v[4:7], v[152:155], v[210:213], v[4:7]
	v_mfma_f32_16x16x32_bf16 v[60:63], v[148:151], v[190:193], v[60:63]
	v_mfma_f32_16x16x32_bf16 v[52:55], v[156:159], v[190:193], v[52:55]
	v_mfma_f32_16x16x32_bf16 v[44:47], v[148:151], v[198:201], v[44:47]
	v_mfma_f32_16x16x32_bf16 v[36:39], v[156:159], v[198:201], v[36:39]
	v_mfma_f32_16x16x32_bf16 v[28:31], v[148:151], v[206:209], v[28:31]
	v_mfma_f32_16x16x32_bf16 v[20:23], v[156:159], v[206:209], v[20:23]
	v_mfma_f32_16x16x32_bf16 v[12:15], v[148:151], v[214:217], v[12:15]
	v_mfma_f32_16x16x32_bf16 v[4:7], v[156:159], v[214:217], v[4:7]
	s_setprio 0
	s_setprio 1
	v_mfma_f32_16x16x32_bf16 v[56:59], v[170:173], v[186:189], v[56:59]
	v_mfma_f32_16x16x32_bf16 v[48:51], v[178:181], v[186:189], v[48:51]
	v_mfma_f32_16x16x32_bf16 v[40:43], v[170:173], v[194:197], v[40:43]
	v_mfma_f32_16x16x32_bf16 v[32:35], v[178:181], v[194:197], v[32:35]
	v_mfma_f32_16x16x32_bf16 v[24:27], v[170:173], v[202:205], v[24:27]
	v_mfma_f32_16x16x32_bf16 v[16:19], v[178:181], v[202:205], v[16:19]
	v_mfma_f32_16x16x32_bf16 v[8:11], v[170:173], v[210:213], v[8:11]
	v_mfma_f32_16x16x32_bf16 v[0:3], v[178:181], v[210:213], v[0:3]
	v_mfma_f32_16x16x32_bf16 v[56:59], v[174:177], v[190:193], v[56:59]
	v_mfma_f32_16x16x32_bf16 v[48:51], v[182:185], v[190:193], v[48:51]
	v_mfma_f32_16x16x32_bf16 v[40:43], v[174:177], v[198:201], v[40:43]
	v_mfma_f32_16x16x32_bf16 v[32:35], v[182:185], v[198:201], v[32:35]
	v_mfma_f32_16x16x32_bf16 v[24:27], v[174:177], v[206:209], v[24:27]
	v_mfma_f32_16x16x32_bf16 v[16:19], v[182:185], v[206:209], v[16:19]
	v_mfma_f32_16x16x32_bf16 v[8:11], v[174:177], v[214:217], v[8:11]
	v_mfma_f32_16x16x32_bf16 v[0:3], v[182:185], v[214:217], v[0:3]
	s_setprio 0
	s_barrier
; #define PG8_STAGE(bufoff, gbase, voff) do { _Pragma("unroll") for (int _i = 0; _i < 2; ++_i) \
;         __builtin_amdgcn_global_load_lds((const unsigned*)((const char*)(gbase) + (voff)[_i]), (LAS unsigned*)(lds + (bufoff) + ldsw + _i * 8192), 16, 0, 0); } while (0)
; #define PG8_LDA(dst, b, h) do { _Pragma("unroll") for (int m = 0; m < 4; ++m) _Pragma("unroll") for (int k = 0; k < 2; ++k) dst[m][k] = *(const LAS bf16x8*)(lds + PG8_SA(b, h) + aoff + m * 2048 + k * 1024); } while (0)
; #define PG8_LDB(dst, b, h) do { _Pragma("unroll") for (int n = 0; n < 2; ++n) _Pragma("unroll") for (int k = 0; k < 2; ++k) dst[n][k] = *(const LAS bf16x8*)(lds + PG8_SB(b, h) + boff + n * 2048 + k * 1024); } while (0)
; #define PG8_MMA(ai, bj, At, Bt) do { __builtin_amdgcn_s_setprio(1); _Pragma("unroll") for (int m = 0; m < 4; ++m) _Pragma("unroll") for (int n = 0; n < 2; ++n) _Pragma("unroll") for (int k = 0; k < 2; ++k) \
;         acc[ai][bj][m][n] = __builtin_amdgcn_mfma_f32_16x16x32_bf16(Bt[n][k], At[m][k], acc[ai][bj][m][n], 0, 0, 0); __builtin_amdgcn_s_setprio(0); } while (0)
; #define PG8_WAIT_V(n) asm volatile("s_waitcnt vmcnt(" #n ")" ::: "memory")
; #define PG8_WAIT_L(n) asm volatile("s_waitcnt lgkmcnt(" #n ")" ::: "memory")
; #define PG8_BAR __builtin_amdgcn_s_barrier()
; #define PG8_SCHED __builtin_amdgcn_sched_barrier(0)
; template <class Epi, class Sched, bool ALIGN_EPI = true, bool SP2 = true>
; __device__ __forceinline__ void gemm_phase(LAS unsigned char* lds, const Gemm g, const Sched& S, const Epi& E) {
;     ...
;         for (int t = 0; t < nt; t += 2) {
;     ...
;             PG8_LDB(B0, 1, 0); PG8_LDB(B1, 1, 1); PG8_SCHED; PG8_LDA(At, 1, 0); PG8_STAGE(PG8_SA(0, 1), a2 + hstep, voffA);
;             PG8_WAIT_V(8); PG8_WAIT_L(0); PG8_BAR; PG8_MMA(0, 0, At, B0); PG8_MMA(0, 1, At, B1); PG8_BAR; PG8_SCHED;
;             PG8_LDA(At, 1, 1); PG8_STAGE(PG8_SB(1, 0), b3, voffB); PG8_STAGE(PG8_SB(1, 1), b3 + hstep, voffB); PG8_STAGE(PG8_SA(1, 0), a3, voffA);
;             PG8_WAIT_V(8); PG8_WAIT_L(0); PG8_BAR; PG8_MMA(1, 0, At, B0); PG8_MMA(1, 1, At, B1); PG8_BAR; PG8_SCHED;
	s_add_i32 s46, 0, 0x18000
	s_add_i32 s47, 0, 0x1c000
	v_add_u32_e32 v156, s46, v145
	v_add_u32_e32 v166, s47, v145
	ds_read_b128 v[138:141], v156
	ds_read_b128 v[148:151], v156 offset:1024
	ds_read_b128 v[152:155], v156 offset:2048
	ds_read_b128 v[156:159], v156 offset:3072
	ds_read_b128 v[170:173], v166
	ds_read_b128 v[174:177], v166 offset:1024
	ds_read_b128 v[178:181], v166 offset:2048
	ds_read_b128 v[182:185], v166 offset:3072
	s_add_u32 s60, s60, 0x80000
	s_addc_u32 s61, s61, 0
	s_mov_b32 m0, s45
	ds_read_b128 v[186:189], v147 offset:32768
	ds_read_b128 v[190:193], v147 offset:33792
	ds_read_b128 v[194:197], v147 offset:34816
	ds_read_b128 v[198:201], v147 offset:35840
	ds_read_b128 v[202:205], v147 offset:36864
	ds_read_b128 v[206:209], v147 offset:37888
	ds_read_b128 v[210:213], v147 offset:38912
	ds_read_b128 v[214:217], v147 offset:39936
	global_load_lds_dwordx4 v132, s[60:61]
	s_mov_b32 m0, s53
	s_nop 0
	global_load_lds_dwordx4 v130, s[60:61]
	s_waitcnt vmcnt(8)
	s_waitcnt lgkmcnt(0)
	s_barrier
	s_setprio 1
	s_waitcnt lgkmcnt(0)
	v_mfma_f32_16x16x32_bf16 v[124:127], v[138:141], v[186:189], v[124:127]
	v_mfma_f32_16x16x32_bf16 v[116:119], v[152:155], v[186:189], v[116:119]
	v_mfma_f32_16x16x32_bf16 v[108:111], v[138:141], v[194:197], v[108:111]
	v_mfma_f32_16x16x32_bf16 v[100:103], v[152:155], v[194:197], v[100:103]
	v_mfma_f32_16x16x32_bf16 v[92:95], v[138:141], v[202:205], v[92:95]
	v_mfma_f32_16x16x32_bf16 v[84:87], v[152:155], v[202:205], v[84:87]
	v_mfma_f32_16x16x32_bf16 v[76:79], v[138:141], v[210:213], v[76:79]
	v_mfma_f32_16x16x32_bf16 v[68:71], v[152:155], v[210:213], v[68:71]
	v_mfma_f32_16x16x32_bf16 v[124:127], v[148:151], v[190:193], v[124:127]
	v_mfma_f32_16x16x32_bf16 v[116:119], v[156:159], v[190:193], v[116:119]
	v_mfma_f32_16x16x32_bf16 v[108:111], v[148:151], v[198:201], v[108:111]
	v_mfma_f32_16x16x32_bf16 v[100:103], v[156:159], v[198:201], v[100:103]
	v_mfma_f32_16x16x32_bf16 v[92:95], v[148:151], v[206:209], v[92:95]
	v_mfma_f32_16x16x32_bf16 v[84:87], v[156:159], v[206:209], v[84:87]
	v_mfma_f32_16x16x32_bf16 v[76:79], v[148:151], v[214:217], v[76:79]
	v_mfma_f32_16x16x32_bf16 v[68:71], v[156:159], v[214:217], v[68:71]
	s_setprio 0
	s_setprio 1
	v_mfma_f32_16x16x32_bf16 v[120:123], v[170:173], v[186:189], v[120:123]
	v_mfma_f32_16x16x32_bf16 v[112:115], v[178:181], v[186:189], v[112:115]
	v_mfma_f32_16x16x32_bf16 v[104:107], v[170:173], v[194:197], v[104:107]
	v_mfma_f32_16x16x32_bf16 v[96:99], v[178:181], v[194:197], v[96:99]
	v_mfma_f32_16x16x32_bf16 v[88:91], v[170:173], v[202:205], v[88:91]
	v_mfma_f32_16x16x32_bf16 v[80:83], v[178:181], v[202:205], v[80:83]
	v_mfma_f32_16x16x32_bf16 v[72:75], v[170:173], v[210:213], v[72:75]
	v_mfma_f32_16x16x32_bf16 v[64:67], v[178:181], v[210:213], v[64:67]
	v_mfma_f32_16x16x32_bf16 v[120:123], v[174:177], v[190:193], v[120:123]
	v_mfma_f32_16x16x32_bf16 v[112:115], v[182:185], v[190:193], v[112:115]
	v_mfma_f32_16x16x32_bf16 v[104:107], v[174:177], v[198:201], v[104:107]
	v_mfma_f32_16x16x32_bf16 v[96:99], v[182:185], v[198:201], v[96:99]
	v_mfma_f32_16x16x32_bf16 v[88:91], v[174:177], v[206:209], v[88:91]
	v_mfma_f32_16x16x32_bf16 v[80:83], v[182:185], v[206:209], v[80:83]
	v_mfma_f32_16x16x32_bf16 v[72:75], v[174:177], v[214:217], v[72:75]
	v_mfma_f32_16x16x32_bf16 v[64:67], v[182:185], v[214:217], v[64:67]
	s_setprio 0
	s_barrier
	s_add_i32 s46, s46, s62
	s_mov_b32 m0, s46
	ds_read_b128 v[186:189], v147 offset:49152
	ds_read_b128 v[190:193], v147 offset:50176
	ds_read_b128 v[194:197], v147 offset:51200
	ds_read_b128 v[198:201], v147 offset:52224
	ds_read_b128 v[202:205], v147 offset:53248
	ds_read_b128 v[206:209], v147 offset:54272
	ds_read_b128 v[210:213], v147 offset:55296
	ds_read_b128 v[214:217], v147 offset:56320
	s_add_u32 s98, s24, 0x80
	s_addc_u32 s99, s25, 0
	global_load_lds_dwordx4 v160, s[98:99]
	s_add_i32 m0, s46, 0x2000
	s_add_u32 s24, s24, 0x80080
	s_addc_u32 s25, s25, 0
	s_add_i32 s46, s47, s62
	global_load_lds_dwordx4 v128, s[98:99]
	s_mov_b32 m0, s46
	s_nop 0
	global_load_lds_dwordx4 v160, s[24:25]
	s_add_i32 m0, s46, 0x2000
	s_nop 0
	global_load_lds_dwordx4 v128, s[24:25]
	s_mov_b32 m0, s63
	s_nop 0
	s_add_u32 s98, s60, 0xfff80080
	s_addc_u32 s99, s61, -1
	global_load_lds_dwordx4 v132, s[98:99]
	s_mov_b32 m0, s66
	s_nop 0
	global_load_lds_dwordx4 v130, s[98:99]
	s_waitcnt vmcnt(8)
	s_waitcnt lgkmcnt(0)
	s_barrier
	s_setprio 1
	s_waitcnt lgkmcnt(0)
	v_mfma_f32_16x16x32_bf16 v[60:63], v[138:141], v[186:189], v[60:63]
	v_mfma_f32_16x16x32_bf16 v[52:55], v[152:155], v[186:189], v[52:55]
	v_mfma_f32_16x16x32_bf16 v[44:47], v[138:141], v[194:197], v[44:47]
	v_mfma_f32_16x16x32_bf16 v[36:39], v[152:155], v[194:197], v[36:39]
	v_mfma_f32_16x16x32_bf16 v[28:31], v[138:141], v[202:205], v[28:31]
	v_mfma_f32_16x16x32_bf16 v[20:23], v[152:155], v[202:205], v[20:23]
	v_mfma_f32_16x16x32_bf16 v[12:15], v[138:141], v[210:213], v[12:15]
	v_mfma_f32_16x16x32_bf16 v[4:7], v[152:155], v[210:213], v[4:7]
	v_mfma_f32_16x16x32_bf16 v[60:63], v[148:151], v[190:193], v[60:63]
	v_mfma_f32_16x16x32_bf16 v[52:55], v[156:159], v[190:193], v[52:55]
	v_mfma_f32_16x16x32_bf16 v[44:47], v[148:151], v[198:201], v[44:47]
	v_mfma_f32_16x16x32_bf16 v[36:39], v[156:159], v[198:201], v[36:39]
	v_mfma_f32_16x16x32_bf16 v[28:31], v[148:151], v[206:209], v[28:31]
	v_mfma_f32_16x16x32_bf16 v[20:23], v[156:159], v[206:209], v[20:23]
	v_mfma_f32_16x16x32_bf16 v[12:15], v[148:151], v[214:217], v[12:15]
	v_mfma_f32_16x16x32_bf16 v[4:7], v[156:159], v[214:217], v[4:7]
	s_setprio 0
	s_setprio 1
	v_mfma_f32_16x16x32_bf16 v[56:59], v[170:173], v[186:189], v[56:59]
	v_mfma_f32_16x16x32_bf16 v[48:51], v[178:181], v[186:189], v[48:51]
	v_mfma_f32_16x16x32_bf16 v[40:43], v[170:173], v[194:197], v[40:43]
	v_mfma_f32_16x16x32_bf16 v[32:35], v[178:181], v[194:197], v[32:35]
	v_mfma_f32_16x16x32_bf16 v[24:27], v[170:173], v[202:205], v[24:27]
	v_mfma_f32_16x16x32_bf16 v[16:19], v[178:181], v[202:205], v[16:19]
	v_mfma_f32_16x16x32_bf16 v[8:11], v[170:173], v[210:213], v[8:11]
	v_mfma_f32_16x16x32_bf16 v[0:3], v[178:181], v[210:213], v[0:3]
	v_mfma_f32_16x16x32_bf16 v[56:59], v[174:177], v[190:193], v[56:59]
	v_mfma_f32_16x16x32_bf16 v[48:51], v[182:185], v[190:193], v[48:51]
	v_mfma_f32_16x16x32_bf16 v[40:43], v[174:177], v[198:201], v[40:43]
	v_mfma_f32_16x16x32_bf16 v[32:35], v[182:185], v[198:201], v[32:35]
	v_mfma_f32_16x16x32_bf16 v[24:27], v[174:177], v[206:209], v[24:27]
	v_mfma_f32_16x16x32_bf16 v[16:19], v[182:185], v[206:209], v[16:19]
	v_mfma_f32_16x16x32_bf16 v[8:11], v[174:177], v[214:217], v[8:11]
	v_mfma_f32_16x16x32_bf16 v[0:3], v[182:185], v[214:217], v[0:3]
	s_setprio 0
	s_barrier
	s_add_i32 s83, s83, 2
	s_add_u32 s54, s54, 0x100
	s_addc_u32 s55, s55, 0
	s_add_u32 s79, s79, 0x100
	s_addc_u32 s82, s82, 0
	s_cmp_gt_u32 s83, 29
	s_cbranch_scc0 .LBB0_600
	s_and_b64 vcc, exec, s[10:11]
	s_cbranch_vccz .LBB0_603
	s_barrier
